# PEER gather rewritten in column-slice form: 8 slices of 128 B, sorted lists in LDS, XCD-local sync before U and V phases, LDS prefetch
# speedup vs baseline: 1.1127x; 1.0339x over previous
; DEV void sort_lists(int lane, int& myi0, int& myi1, float& myg0, float& myg1) {
; #pragma unroll
;     for (int k = 2; k <= 128; k <<= 1) {
; #pragma unroll
;       for (int j = k >> 1; j >= 1; j >>= 1) {
;         if (j == 64) {
;           const bool sw_ = myi1 < myi0;
;           const int ti = sw_ ? myi1 : myi0, tj = sw_ ? myi0 : myi1; const float tg = sw_ ? myg1 : myg0, th = sw_ ? myg0 : myg1;
;           myi0 = ti; myi1 = tj; myg0 = tg; myg1 = th;
;         } else {
;           const bool lower = (lane & j) == 0;
;           {
;             const bool up = (k == 128) ? true : ((k == 64) ? true : ((lane & k) == 0));
;             const int oi = __shfl_xor(myi0, j); const float og = __shfl_xor(myg0, j);
;             const bool take = (lower == up) ? (oi < myi0) : (oi > myi0);
;             myi0 = take ? oi : myi0; myg0 = take ? og : myg0;
;           }
;           {
;             const bool up = (k == 128) ? true : ((k == 64) ? false : ((lane & k) == 0));
;             const int oi = __shfl_xor(myi1, j); const float og = __shfl_xor(myg1, j);
;             const bool take = (lower == up) ? (oi < myi1) : (oi > myi1);
;             myi1 = take ? oi : myi1; myg1 = take ? og : myg1;
;           }
;         }
;       }
;     }
; }
; DEV void peer_gather(const Params& P, int l, int m0, const int* idxs, const float* gs) {
;     ...
;   const int row = lane >> 4, rmap = ((row & 1) << 1) | (row >> 1);
;   u32x4 nxa = *(const u32x4*)(hn + (size_t)(m0 + wid * 16) * DM + lane * 16), nxb = *(const u32x4*)(hn + (size_t)(m0 + wid * 16) * DM + lane * 16 + 8);
;   int ni0 = idxs[(wid * 16) * 128 + lane], ni1 = idxs[(wid * 16) * 128 + 64 + lane];
;   float ng0 = gs[(wid * 16) * 128 + lane], ng1 = gs[(wid * 16) * 128 + 64 + lane];
;   sort_lists(lane, ni0, ni1, ng0, ng1);
.LBB0_313:
	s_waitcnt vmcnt(0) lgkmcnt(0)
	v_and_b32_e32 v233, 63, v176
	v_lshlrev_b32_e32 v234, 2, v233
	v_and_b32_e32 v116, 7, v233
	v_lshlrev_b32_e32 v235, 4, v116
	v_lshlrev_b32_e32 v236, 5, v116
	v_lshrrev_b32_e32 v117, 3, v233
	v_lshlrev_b32_e32 v237, 2, v117
	v_lshl_add_u32 v239, v116, 3, v117
	v_lshlrev_b32_e32 v239, 2, v239
	v_lshlrev_b32_e32 v238, 4, v116
	v_and_b32_e32 v117, 1, v117
	v_lshl_add_u32 v238, v117, 2, v238
	v_bfe_u32 v117, v233, 4, 1
	v_lshl_add_u32 v238, v117, 1, v238
	v_lshrrev_b32_e32 v117, 5, v233
	v_add_u32_e32 v238, v117, v238
	v_lshlrev_b32_e32 v238, 2, v238
	v_add_u32_e32 v249, 0, v237
	v_add_u32_e32 v250, 32, v237
	v_add_u32_e32 v251, 64, v237
	v_add_u32_e32 v252, 96, v237
	v_add_u32_e32 v253, 128, v237
	v_add_u32_e32 v254, 160, v237
	v_add_u32_e32 v255, 192, v237
	v_add_u32_e32 v153, 224, v237
	v_readfirstlane_b32 s33, v176
	s_lshr_b32 s33, s33, 6
	s_lshl_b32 s101, s33, 13
	s_lshl_b32 s33, s33, 4
	v_readlane_b32 s3, v231, 30
	s_add_u32 s3, s3, s33
	s_mov_b32 s2, 0
.Lpg0_p0:
	v_readlane_b32 s82, v231, 26
	v_readlane_b32 s83, v231, 27
	s_nop 4
	s_lshl_b32 s98, s2, 2
	s_add_u32 s98, s98, s33
	s_add_u32 s98, s98, 0
	s_lshl_b32 s98, s98, 9
	v_add_u32_e32 v116, s98, v234
	global_load_dword v241, v116, s[82:83]
	global_load_dword v242, v116, s[82:83] offset:256
	s_lshl_b32 s98, s2, 2
	s_add_u32 s98, s98, s33
	s_add_u32 s98, s98, 1
	s_lshl_b32 s98, s98, 9
	v_add_u32_e32 v117, s98, v234
	global_load_dword v243, v117, s[82:83]
	global_load_dword v244, v117, s[82:83] offset:256
	s_lshl_b32 s98, s2, 2
	s_add_u32 s98, s98, s33
	s_add_u32 s98, s98, 2
	s_lshl_b32 s98, s98, 9
	v_add_u32_e32 v118, s98, v234
	global_load_dword v245, v118, s[82:83]
	global_load_dword v246, v118, s[82:83] offset:256
	s_lshl_b32 s98, s2, 2
	s_add_u32 s98, s98, s33
	s_add_u32 s98, s98, 3
	s_lshl_b32 s98, s98, 9
	v_add_u32_e32 v119, s98, v234
	global_load_dword v247, v119, s[82:83]
	global_load_dword v248, v119, s[82:83] offset:256
	s_waitcnt vmcnt(0)
	v_or_b32_e32 v116, 64, v233
	v_lshl_or_b32 v241, v241, 7, v233
	v_lshl_or_b32 v242, v242, 7, v116
	v_lshl_or_b32 v243, v243, 7, v233
	v_lshl_or_b32 v244, v244, 7, v116
	v_lshl_or_b32 v245, v245, 7, v233
	v_lshl_or_b32 v246, v246, 7, v116
	v_lshl_or_b32 v247, v247, 7, v233
	v_lshl_or_b32 v248, v248, 7, v116
	v_xor_b32_e32 v116, 4, v234
	ds_bpermute_b32 v0, v116, v241
	ds_bpermute_b32 v1, v116, v243
	ds_bpermute_b32 v2, v116, v245
	ds_bpermute_b32 v3, v116, v247
	ds_bpermute_b32 v4, v116, v242
	ds_bpermute_b32 v5, v116, v244
	ds_bpermute_b32 v6, v116, v246
	ds_bpermute_b32 v7, v116, v248
	s_waitcnt lgkmcnt(0)
	s_mov_b32 s88, 0x99999999
	s_mov_b32 s89, 0x99999999
	v_min_u32_e32 v104, v241, v0
	v_max_u32_e32 v105, v241, v0
	v_cndmask_b32_e64 v241, v105, v104, s[88:89]
	v_min_u32_e32 v106, v243, v1
	v_max_u32_e32 v107, v243, v1
	v_cndmask_b32_e64 v243, v107, v106, s[88:89]
	v_min_u32_e32 v104, v245, v2
	v_max_u32_e32 v105, v245, v2
	v_cndmask_b32_e64 v245, v105, v104, s[88:89]
	v_min_u32_e32 v106, v247, v3
	v_max_u32_e32 v107, v247, v3
	v_cndmask_b32_e64 v247, v107, v106, s[88:89]
	v_min_u32_e32 v104, v242, v4
	v_max_u32_e32 v105, v242, v4
	v_cndmask_b32_e64 v242, v105, v104, s[88:89]
	v_min_u32_e32 v106, v244, v5
	v_max_u32_e32 v107, v244, v5
	v_cndmask_b32_e64 v244, v107, v106, s[88:89]
	v_min_u32_e32 v104, v246, v6
	v_max_u32_e32 v105, v246, v6
	v_cndmask_b32_e64 v246, v105, v104, s[88:89]
	v_min_u32_e32 v106, v248, v7
	v_max_u32_e32 v107, v248, v7
	v_cndmask_b32_e64 v248, v107, v106, s[88:89]
	v_xor_b32_e32 v116, 8, v234
	ds_bpermute_b32 v0, v116, v241
	ds_bpermute_b32 v1, v116, v243
	ds_bpermute_b32 v2, v116, v245
	ds_bpermute_b32 v3, v116, v247
	ds_bpermute_b32 v4, v116, v242
	ds_bpermute_b32 v5, v116, v244
	ds_bpermute_b32 v6, v116, v246
	ds_bpermute_b32 v7, v116, v248
	s_waitcnt lgkmcnt(0)
	s_mov_b32 s88, 0xc3c3c3c3
	s_mov_b32 s89, 0xc3c3c3c3
	v_min_u32_e32 v104, v241, v0
	v_max_u32_e32 v105, v241, v0
	v_cndmask_b32_e64 v241, v105, v104, s[88:89]
	v_min_u32_e32 v106, v243, v1
	v_max_u32_e32 v107, v243, v1
	v_cndmask_b32_e64 v243, v107, v106, s[88:89]
	v_min_u32_e32 v104, v245, v2
	v_max_u32_e32 v105, v245, v2
	v_cndmask_b32_e64 v245, v105, v104, s[88:89]
	v_min_u32_e32 v106, v247, v3
	v_max_u32_e32 v107, v247, v3
	v_cndmask_b32_e64 v247, v107, v106, s[88:89]
	v_min_u32_e32 v104, v242, v4
	v_max_u32_e32 v105, v242, v4
	v_cndmask_b32_e64 v242, v105, v104, s[88:89]
	v_min_u32_e32 v106, v244, v5
	v_max_u32_e32 v107, v244, v5
	v_cndmask_b32_e64 v244, v107, v106, s[88:89]
	v_min_u32_e32 v104, v246, v6
	v_max_u32_e32 v105, v246, v6
	v_cndmask_b32_e64 v246, v105, v104, s[88:89]
	v_min_u32_e32 v106, v248, v7
	v_max_u32_e32 v107, v248, v7
	v_cndmask_b32_e64 v248, v107, v106, s[88:89]
	v_xor_b32_e32 v116, 4, v234
	ds_bpermute_b32 v0, v116, v241
	ds_bpermute_b32 v1, v116, v243
	ds_bpermute_b32 v2, v116, v245
	ds_bpermute_b32 v3, v116, v247
	ds_bpermute_b32 v4, v116, v242
	ds_bpermute_b32 v5, v116, v244
	ds_bpermute_b32 v6, v116, v246
	ds_bpermute_b32 v7, v116, v248
	s_waitcnt lgkmcnt(0)
	s_mov_b32 s88, 0xa5a5a5a5
	s_mov_b32 s89, 0xa5a5a5a5
	v_min_u32_e32 v104, v241, v0
	v_max_u32_e32 v105, v241, v0
	v_cndmask_b32_e64 v241, v105, v104, s[88:89]
	v_min_u32_e32 v106, v243, v1
	v_max_u32_e32 v107, v243, v1
	v_cndmask_b32_e64 v243, v107, v106, s[88:89]
	v_min_u32_e32 v104, v245, v2
	v_max_u32_e32 v105, v245, v2
	v_cndmask_b32_e64 v245, v105, v104, s[88:89]
	v_min_u32_e32 v106, v247, v3
	v_max_u32_e32 v107, v247, v3
	v_cndmask_b32_e64 v247, v107, v106, s[88:89]
	v_min_u32_e32 v104, v242, v4
	v_max_u32_e32 v105, v242, v4
	v_cndmask_b32_e64 v242, v105, v104, s[88:89]
	v_min_u32_e32 v106, v244, v5
	v_max_u32_e32 v107, v244, v5
	v_cndmask_b32_e64 v244, v107, v106, s[88:89]
	v_min_u32_e32 v104, v246, v6
	v_max_u32_e32 v105, v246, v6
	v_cndmask_b32_e64 v246, v105, v104, s[88:89]
	v_min_u32_e32 v106, v248, v7
	v_max_u32_e32 v107, v248, v7
	v_cndmask_b32_e64 v248, v107, v106, s[88:89]
	v_xor_b32_e32 v116, 16, v234
	ds_bpermute_b32 v0, v116, v241
	ds_bpermute_b32 v1, v116, v243
	ds_bpermute_b32 v2, v116, v245
	ds_bpermute_b32 v3, v116, v247
	ds_bpermute_b32 v4, v116, v242
	ds_bpermute_b32 v5, v116, v244
	ds_bpermute_b32 v6, v116, v246
	ds_bpermute_b32 v7, v116, v248
	s_waitcnt lgkmcnt(0)
; DEV void sort_lists(int lane, int& myi0, int& myi1, float& myg0, float& myg1) {
; #pragma unroll
;     for (int k = 2; k <= 128; k <<= 1) {
; #pragma unroll
;       for (int j = k >> 1; j >= 1; j >>= 1) {
;         if (j == 64) {
;           const bool sw_ = myi1 < myi0;
;           const int ti = sw_ ? myi1 : myi0, tj = sw_ ? myi0 : myi1; const float tg = sw_ ? myg1 : myg0, th = sw_ ? myg0 : myg1;
;           myi0 = ti; myi1 = tj; myg0 = tg; myg1 = th;
;         } else {
;           const bool lower = (lane & j) == 0;
;           {
;             const bool up = (k == 128) ? true : ((k == 64) ? true : ((lane & k) == 0));
;             const int oi = __shfl_xor(myi0, j); const float og = __shfl_xor(myg0, j);
;             const bool take = (lower == up) ? (oi < myi0) : (oi > myi0);
;             myi0 = take ? oi : myi0; myg0 = take ? og : myg0;
;           }
;           {
;             const bool up = (k == 128) ? true : ((k == 64) ? false : ((lane & k) == 0));
;             const int oi = __shfl_xor(myi1, j); const float og = __shfl_xor(myg1, j);
;             const bool take = (lower == up) ? (oi < myi1) : (oi > myi1);
;             myi1 = take ? oi : myi1; myg1 = take ? og : myg1;
;           }
;         }
;       }
;     }
; }
	s_mov_b32 s88, 0xf00ff00f
	s_mov_b32 s89, 0xf00ff00f
	v_min_u32_e32 v104, v241, v0
	v_max_u32_e32 v105, v241, v0
	v_cndmask_b32_e64 v241, v105, v104, s[88:89]
	v_min_u32_e32 v106, v243, v1
	v_max_u32_e32 v107, v243, v1
	v_cndmask_b32_e64 v243, v107, v106, s[88:89]
	v_min_u32_e32 v104, v245, v2
	v_max_u32_e32 v105, v245, v2
	v_cndmask_b32_e64 v245, v105, v104, s[88:89]
	v_min_u32_e32 v106, v247, v3
	v_max_u32_e32 v107, v247, v3
	v_cndmask_b32_e64 v247, v107, v106, s[88:89]
	v_min_u32_e32 v104, v242, v4
	v_max_u32_e32 v105, v242, v4
	v_cndmask_b32_e64 v242, v105, v104, s[88:89]
	v_min_u32_e32 v106, v244, v5
	v_max_u32_e32 v107, v244, v5
	v_cndmask_b32_e64 v244, v107, v106, s[88:89]
	v_min_u32_e32 v104, v246, v6
	v_max_u32_e32 v105, v246, v6
	v_cndmask_b32_e64 v246, v105, v104, s[88:89]
	v_min_u32_e32 v106, v248, v7
	v_max_u32_e32 v107, v248, v7
	v_cndmask_b32_e64 v248, v107, v106, s[88:89]
	v_xor_b32_e32 v116, 8, v234
	ds_bpermute_b32 v0, v116, v241
	ds_bpermute_b32 v1, v116, v243
	ds_bpermute_b32 v2, v116, v245
	ds_bpermute_b32 v3, v116, v247
	ds_bpermute_b32 v4, v116, v242
	ds_bpermute_b32 v5, v116, v244
	ds_bpermute_b32 v6, v116, v246
	ds_bpermute_b32 v7, v116, v248
	s_waitcnt lgkmcnt(0)
	s_mov_b32 s88, 0xcc33cc33
	s_mov_b32 s89, 0xcc33cc33
	v_min_u32_e32 v104, v241, v0
	v_max_u32_e32 v105, v241, v0
	v_cndmask_b32_e64 v241, v105, v104, s[88:89]
	v_min_u32_e32 v106, v243, v1
	v_max_u32_e32 v107, v243, v1
	v_cndmask_b32_e64 v243, v107, v106, s[88:89]
	v_min_u32_e32 v104, v245, v2
	v_max_u32_e32 v105, v245, v2
	v_cndmask_b32_e64 v245, v105, v104, s[88:89]
	v_min_u32_e32 v106, v247, v3
	v_max_u32_e32 v107, v247, v3
	v_cndmask_b32_e64 v247, v107, v106, s[88:89]
	v_min_u32_e32 v104, v242, v4
	v_max_u32_e32 v105, v242, v4
	v_cndmask_b32_e64 v242, v105, v104, s[88:89]
	v_min_u32_e32 v106, v244, v5
	v_max_u32_e32 v107, v244, v5
	v_cndmask_b32_e64 v244, v107, v106, s[88:89]
	v_min_u32_e32 v104, v246, v6
	v_max_u32_e32 v105, v246, v6
	v_cndmask_b32_e64 v246, v105, v104, s[88:89]
	v_min_u32_e32 v106, v248, v7
	v_max_u32_e32 v107, v248, v7
	v_cndmask_b32_e64 v248, v107, v106, s[88:89]
	v_xor_b32_e32 v116, 4, v234
	ds_bpermute_b32 v0, v116, v241
	ds_bpermute_b32 v1, v116, v243
	ds_bpermute_b32 v2, v116, v245
	ds_bpermute_b32 v3, v116, v247
	ds_bpermute_b32 v4, v116, v242
	ds_bpermute_b32 v5, v116, v244
	ds_bpermute_b32 v6, v116, v246
	ds_bpermute_b32 v7, v116, v248
	s_waitcnt lgkmcnt(0)
	s_mov_b32 s88, 0xaa55aa55
	s_mov_b32 s89, 0xaa55aa55
	v_min_u32_e32 v104, v241, v0
	v_max_u32_e32 v105, v241, v0
	v_cndmask_b32_e64 v241, v105, v104, s[88:89]
	v_min_u32_e32 v106, v243, v1
	v_max_u32_e32 v107, v243, v1
	v_cndmask_b32_e64 v243, v107, v106, s[88:89]
	v_min_u32_e32 v104, v245, v2
	v_max_u32_e32 v105, v245, v2
	v_cndmask_b32_e64 v245, v105, v104, s[88:89]
	v_min_u32_e32 v106, v247, v3
	v_max_u32_e32 v107, v247, v3
	v_cndmask_b32_e64 v247, v107, v106, s[88:89]
	v_min_u32_e32 v104, v242, v4
	v_max_u32_e32 v105, v242, v4
	v_cndmask_b32_e64 v242, v105, v104, s[88:89]
	v_min_u32_e32 v106, v244, v5
	v_max_u32_e32 v107, v244, v5
	v_cndmask_b32_e64 v244, v107, v106, s[88:89]
	v_min_u32_e32 v104, v246, v6
	v_max_u32_e32 v105, v246, v6
	v_cndmask_b32_e64 v246, v105, v104, s[88:89]
	v_min_u32_e32 v106, v248, v7
	v_max_u32_e32 v107, v248, v7
	v_cndmask_b32_e64 v248, v107, v106, s[88:89]
	v_xor_b32_e32 v116, 32, v234
	ds_bpermute_b32 v0, v116, v241
	ds_bpermute_b32 v1, v116, v243
	ds_bpermute_b32 v2, v116, v245
	ds_bpermute_b32 v3, v116, v247
	ds_bpermute_b32 v4, v116, v242
	ds_bpermute_b32 v5, v116, v244
	ds_bpermute_b32 v6, v116, v246
	ds_bpermute_b32 v7, v116, v248
	s_waitcnt lgkmcnt(0)
	s_mov_b32 s88, 0xff0000ff
	s_mov_b32 s89, 0xff0000ff
	v_min_u32_e32 v104, v241, v0
	v_max_u32_e32 v105, v241, v0
	v_cndmask_b32_e64 v241, v105, v104, s[88:89]
	v_min_u32_e32 v106, v243, v1
	v_max_u32_e32 v107, v243, v1
	v_cndmask_b32_e64 v243, v107, v106, s[88:89]
	v_min_u32_e32 v104, v245, v2
	v_max_u32_e32 v105, v245, v2
	v_cndmask_b32_e64 v245, v105, v104, s[88:89]
	v_min_u32_e32 v106, v247, v3
	v_max_u32_e32 v107, v247, v3
	v_cndmask_b32_e64 v247, v107, v106, s[88:89]
	v_min_u32_e32 v104, v242, v4
	v_max_u32_e32 v105, v242, v4
	v_cndmask_b32_e64 v242, v105, v104, s[88:89]
	v_min_u32_e32 v106, v244, v5
	v_max_u32_e32 v107, v244, v5
	v_cndmask_b32_e64 v244, v107, v106, s[88:89]
	v_min_u32_e32 v104, v246, v6
	v_max_u32_e32 v105, v246, v6
	v_cndmask_b32_e64 v246, v105, v104, s[88:89]
	v_min_u32_e32 v106, v248, v7
	v_max_u32_e32 v107, v248, v7
	v_cndmask_b32_e64 v248, v107, v106, s[88:89]
	v_xor_b32_e32 v116, 16, v234
	ds_bpermute_b32 v0, v116, v241
	ds_bpermute_b32 v1, v116, v243
	ds_bpermute_b32 v2, v116, v245
	ds_bpermute_b32 v3, v116, v247
	ds_bpermute_b32 v4, v116, v242
	ds_bpermute_b32 v5, v116, v244
	ds_bpermute_b32 v6, v116, v246
	ds_bpermute_b32 v7, v116, v248
	s_waitcnt lgkmcnt(0)
	s_mov_b32 s88, 0xf0f00f0f
	s_mov_b32 s89, 0xf0f00f0f
	v_min_u32_e32 v104, v241, v0
	v_max_u32_e32 v105, v241, v0
	v_cndmask_b32_e64 v241, v105, v104, s[88:89]
	v_min_u32_e32 v106, v243, v1
	v_max_u32_e32 v107, v243, v1
	v_cndmask_b32_e64 v243, v107, v106, s[88:89]
	v_min_u32_e32 v104, v245, v2
	v_max_u32_e32 v105, v245, v2
	v_cndmask_b32_e64 v245, v105, v104, s[88:89]
	v_min_u32_e32 v106, v247, v3
	v_max_u32_e32 v107, v247, v3
	v_cndmask_b32_e64 v247, v107, v106, s[88:89]
	v_min_u32_e32 v104, v242, v4
	v_max_u32_e32 v105, v242, v4
	v_cndmask_b32_e64 v242, v105, v104, s[88:89]
	v_min_u32_e32 v106, v244, v5
	v_max_u32_e32 v107, v244, v5
	v_cndmask_b32_e64 v244, v107, v106, s[88:89]
	v_min_u32_e32 v104, v246, v6
	v_max_u32_e32 v105, v246, v6
	v_cndmask_b32_e64 v246, v105, v104, s[88:89]
	v_min_u32_e32 v106, v248, v7
	v_max_u32_e32 v107, v248, v7
	v_cndmask_b32_e64 v248, v107, v106, s[88:89]
	v_xor_b32_e32 v116, 8, v234
	ds_bpermute_b32 v0, v116, v241
	ds_bpermute_b32 v1, v116, v243
	ds_bpermute_b32 v2, v116, v245
	ds_bpermute_b32 v3, v116, v247
	ds_bpermute_b32 v4, v116, v242
	ds_bpermute_b32 v5, v116, v244
	ds_bpermute_b32 v6, v116, v246
	ds_bpermute_b32 v7, v116, v248
	s_waitcnt lgkmcnt(0)
; DEV void sort_lists(int lane, int& myi0, int& myi1, float& myg0, float& myg1) {
; #pragma unroll
;     for (int k = 2; k <= 128; k <<= 1) {
; #pragma unroll
;       for (int j = k >> 1; j >= 1; j >>= 1) {
;         if (j == 64) {
;           const bool sw_ = myi1 < myi0;
;           const int ti = sw_ ? myi1 : myi0, tj = sw_ ? myi0 : myi1; const float tg = sw_ ? myg1 : myg0, th = sw_ ? myg0 : myg1;
;           myi0 = ti; myi1 = tj; myg0 = tg; myg1 = th;
;         } else {
;           const bool lower = (lane & j) == 0;
;           {
;             const bool up = (k == 128) ? true : ((k == 64) ? true : ((lane & k) == 0));
;             const int oi = __shfl_xor(myi0, j); const float og = __shfl_xor(myg0, j);
;             const bool take = (lower == up) ? (oi < myi0) : (oi > myi0);
;             myi0 = take ? oi : myi0; myg0 = take ? og : myg0;
;           }
;           {
;             const bool up = (k == 128) ? true : ((k == 64) ? false : ((lane & k) == 0));
;             const int oi = __shfl_xor(myi1, j); const float og = __shfl_xor(myg1, j);
;             const bool take = (lower == up) ? (oi < myi1) : (oi > myi1);
;             myi1 = take ? oi : myi1; myg1 = take ? og : myg1;
;           }
;         }
;       }
;     }
; }
	s_mov_b32 s88, 0xcccc3333
	s_mov_b32 s89, 0xcccc3333
	v_min_u32_e32 v104, v241, v0
	v_max_u32_e32 v105, v241, v0
	v_cndmask_b32_e64 v241, v105, v104, s[88:89]
	v_min_u32_e32 v106, v243, v1
	v_max_u32_e32 v107, v243, v1
	v_cndmask_b32_e64 v243, v107, v106, s[88:89]
	v_min_u32_e32 v104, v245, v2
	v_max_u32_e32 v105, v245, v2
	v_cndmask_b32_e64 v245, v105, v104, s[88:89]
	v_min_u32_e32 v106, v247, v3
	v_max_u32_e32 v107, v247, v3
	v_cndmask_b32_e64 v247, v107, v106, s[88:89]
	v_min_u32_e32 v104, v242, v4
	v_max_u32_e32 v105, v242, v4
	v_cndmask_b32_e64 v242, v105, v104, s[88:89]
	v_min_u32_e32 v106, v244, v5
	v_max_u32_e32 v107, v244, v5
	v_cndmask_b32_e64 v244, v107, v106, s[88:89]
	v_min_u32_e32 v104, v246, v6
	v_max_u32_e32 v105, v246, v6
	v_cndmask_b32_e64 v246, v105, v104, s[88:89]
	v_min_u32_e32 v106, v248, v7
	v_max_u32_e32 v107, v248, v7
	v_cndmask_b32_e64 v248, v107, v106, s[88:89]
	v_xor_b32_e32 v116, 4, v234
	ds_bpermute_b32 v0, v116, v241
	ds_bpermute_b32 v1, v116, v243
	ds_bpermute_b32 v2, v116, v245
	ds_bpermute_b32 v3, v116, v247
	ds_bpermute_b32 v4, v116, v242
	ds_bpermute_b32 v5, v116, v244
	ds_bpermute_b32 v6, v116, v246
	ds_bpermute_b32 v7, v116, v248
	s_waitcnt lgkmcnt(0)
	s_mov_b32 s88, 0xaaaa5555
	s_mov_b32 s89, 0xaaaa5555
	v_min_u32_e32 v104, v241, v0
	v_max_u32_e32 v105, v241, v0
	v_cndmask_b32_e64 v241, v105, v104, s[88:89]
	v_min_u32_e32 v106, v243, v1
	v_max_u32_e32 v107, v243, v1
	v_cndmask_b32_e64 v243, v107, v106, s[88:89]
	v_min_u32_e32 v104, v245, v2
	v_max_u32_e32 v105, v245, v2
	v_cndmask_b32_e64 v245, v105, v104, s[88:89]
	v_min_u32_e32 v106, v247, v3
	v_max_u32_e32 v107, v247, v3
	v_cndmask_b32_e64 v247, v107, v106, s[88:89]
	v_min_u32_e32 v104, v242, v4
	v_max_u32_e32 v105, v242, v4
	v_cndmask_b32_e64 v242, v105, v104, s[88:89]
	v_min_u32_e32 v106, v244, v5
	v_max_u32_e32 v107, v244, v5
	v_cndmask_b32_e64 v244, v107, v106, s[88:89]
	v_min_u32_e32 v104, v246, v6
	v_max_u32_e32 v105, v246, v6
	v_cndmask_b32_e64 v246, v105, v104, s[88:89]
	v_min_u32_e32 v106, v248, v7
	v_max_u32_e32 v107, v248, v7
	v_cndmask_b32_e64 v248, v107, v106, s[88:89]
	v_xor_b32_e32 v116, 64, v234
	ds_bpermute_b32 v0, v116, v241
	ds_bpermute_b32 v1, v116, v243
	ds_bpermute_b32 v2, v116, v245
	ds_bpermute_b32 v3, v116, v247
	ds_bpermute_b32 v4, v116, v242
	ds_bpermute_b32 v5, v116, v244
	ds_bpermute_b32 v6, v116, v246
	ds_bpermute_b32 v7, v116, v248
	s_waitcnt lgkmcnt(0)
	s_mov_b32 s88, 0xffff
	s_mov_b32 s89, 0xffff0000
	v_min_u32_e32 v104, v241, v0
	v_max_u32_e32 v105, v241, v0
	v_cndmask_b32_e64 v241, v105, v104, s[88:89]
	v_min_u32_e32 v106, v243, v1
	v_max_u32_e32 v107, v243, v1
	v_cndmask_b32_e64 v243, v107, v106, s[88:89]
	v_min_u32_e32 v104, v245, v2
	v_max_u32_e32 v105, v245, v2
	v_cndmask_b32_e64 v245, v105, v104, s[88:89]
	v_min_u32_e32 v106, v247, v3
	v_max_u32_e32 v107, v247, v3
	v_cndmask_b32_e64 v247, v107, v106, s[88:89]
	v_min_u32_e32 v104, v242, v4
	v_max_u32_e32 v105, v242, v4
	v_cndmask_b32_e64 v242, v105, v104, s[88:89]
	v_min_u32_e32 v106, v244, v5
	v_max_u32_e32 v107, v244, v5
	v_cndmask_b32_e64 v244, v107, v106, s[88:89]
	v_min_u32_e32 v104, v246, v6
	v_max_u32_e32 v105, v246, v6
	v_cndmask_b32_e64 v246, v105, v104, s[88:89]
	v_min_u32_e32 v106, v248, v7
	v_max_u32_e32 v107, v248, v7
	v_cndmask_b32_e64 v248, v107, v106, s[88:89]
	v_xor_b32_e32 v116, 32, v234
	ds_bpermute_b32 v0, v116, v241
	ds_bpermute_b32 v1, v116, v243
	ds_bpermute_b32 v2, v116, v245
	ds_bpermute_b32 v3, v116, v247
	ds_bpermute_b32 v4, v116, v242
	ds_bpermute_b32 v5, v116, v244
	ds_bpermute_b32 v6, v116, v246
	ds_bpermute_b32 v7, v116, v248
	s_waitcnt lgkmcnt(0)
	s_mov_b32 s88, 0xff00ff
	s_mov_b32 s89, 0xff00ff00
	v_min_u32_e32 v104, v241, v0
	v_max_u32_e32 v105, v241, v0
	v_cndmask_b32_e64 v241, v105, v104, s[88:89]
	v_min_u32_e32 v106, v243, v1
	v_max_u32_e32 v107, v243, v1
	v_cndmask_b32_e64 v243, v107, v106, s[88:89]
	v_min_u32_e32 v104, v245, v2
	v_max_u32_e32 v105, v245, v2
	v_cndmask_b32_e64 v245, v105, v104, s[88:89]
	v_min_u32_e32 v106, v247, v3
	v_max_u32_e32 v107, v247, v3
	v_cndmask_b32_e64 v247, v107, v106, s[88:89]
	v_min_u32_e32 v104, v242, v4
	v_max_u32_e32 v105, v242, v4
	v_cndmask_b32_e64 v242, v105, v104, s[88:89]
	v_min_u32_e32 v106, v244, v5
	v_max_u32_e32 v107, v244, v5
	v_cndmask_b32_e64 v244, v107, v106, s[88:89]
	v_min_u32_e32 v104, v246, v6
	v_max_u32_e32 v105, v246, v6
	v_cndmask_b32_e64 v246, v105, v104, s[88:89]
	v_min_u32_e32 v106, v248, v7
	v_max_u32_e32 v107, v248, v7
	v_cndmask_b32_e64 v248, v107, v106, s[88:89]
	v_xor_b32_e32 v116, 16, v234
	ds_bpermute_b32 v0, v116, v241
	ds_bpermute_b32 v1, v116, v243
	ds_bpermute_b32 v2, v116, v245
	ds_bpermute_b32 v3, v116, v247
	ds_bpermute_b32 v4, v116, v242
	ds_bpermute_b32 v5, v116, v244
	ds_bpermute_b32 v6, v116, v246
	ds_bpermute_b32 v7, v116, v248
	s_waitcnt lgkmcnt(0)
	s_mov_b32 s88, 0xf0f0f0f
	s_mov_b32 s89, 0xf0f0f0f0
	v_min_u32_e32 v104, v241, v0
	v_max_u32_e32 v105, v241, v0
	v_cndmask_b32_e64 v241, v105, v104, s[88:89]
	v_min_u32_e32 v106, v243, v1
	v_max_u32_e32 v107, v243, v1
	v_cndmask_b32_e64 v243, v107, v106, s[88:89]
	v_min_u32_e32 v104, v245, v2
	v_max_u32_e32 v105, v245, v2
	v_cndmask_b32_e64 v245, v105, v104, s[88:89]
	v_min_u32_e32 v106, v247, v3
	v_max_u32_e32 v107, v247, v3
	v_cndmask_b32_e64 v247, v107, v106, s[88:89]
	v_min_u32_e32 v104, v242, v4
	v_max_u32_e32 v105, v242, v4
	v_cndmask_b32_e64 v242, v105, v104, s[88:89]
	v_min_u32_e32 v106, v244, v5
	v_max_u32_e32 v107, v244, v5
	v_cndmask_b32_e64 v244, v107, v106, s[88:89]
	v_min_u32_e32 v104, v246, v6
	v_max_u32_e32 v105, v246, v6
	v_cndmask_b32_e64 v246, v105, v104, s[88:89]
	v_min_u32_e32 v106, v248, v7
	v_max_u32_e32 v107, v248, v7
	v_cndmask_b32_e64 v248, v107, v106, s[88:89]
	v_xor_b32_e32 v116, 8, v234
	ds_bpermute_b32 v0, v116, v241
	ds_bpermute_b32 v1, v116, v243
	ds_bpermute_b32 v2, v116, v245
	ds_bpermute_b32 v3, v116, v247
	ds_bpermute_b32 v4, v116, v242
	ds_bpermute_b32 v5, v116, v244
	ds_bpermute_b32 v6, v116, v246
	ds_bpermute_b32 v7, v116, v248
	s_waitcnt lgkmcnt(0)
; DEV void sort_lists(int lane, int& myi0, int& myi1, float& myg0, float& myg1) {
; #pragma unroll
;     for (int k = 2; k <= 128; k <<= 1) {
; #pragma unroll
;       for (int j = k >> 1; j >= 1; j >>= 1) {
;         if (j == 64) {
;           const bool sw_ = myi1 < myi0;
;           const int ti = sw_ ? myi1 : myi0, tj = sw_ ? myi0 : myi1; const float tg = sw_ ? myg1 : myg0, th = sw_ ? myg0 : myg1;
;           myi0 = ti; myi1 = tj; myg0 = tg; myg1 = th;
;         } else {
;           const bool lower = (lane & j) == 0;
;           {
;             const bool up = (k == 128) ? true : ((k == 64) ? true : ((lane & k) == 0));
;             const int oi = __shfl_xor(myi0, j); const float og = __shfl_xor(myg0, j);
;             const bool take = (lower == up) ? (oi < myi0) : (oi > myi0);
;             myi0 = take ? oi : myi0; myg0 = take ? og : myg0;
;           }
;           {
;             const bool up = (k == 128) ? true : ((k == 64) ? false : ((lane & k) == 0));
;             const int oi = __shfl_xor(myi1, j); const float og = __shfl_xor(myg1, j);
;             const bool take = (lower == up) ? (oi < myi1) : (oi > myi1);
;             myi1 = take ? oi : myi1; myg1 = take ? og : myg1;
;           }
;         }
;       }
;     }
; }
	s_mov_b32 s88, 0x33333333
	s_mov_b32 s89, 0xcccccccc
	v_min_u32_e32 v104, v241, v0
	v_max_u32_e32 v105, v241, v0
	v_cndmask_b32_e64 v241, v105, v104, s[88:89]
	v_min_u32_e32 v106, v243, v1
	v_max_u32_e32 v107, v243, v1
	v_cndmask_b32_e64 v243, v107, v106, s[88:89]
	v_min_u32_e32 v104, v245, v2
	v_max_u32_e32 v105, v245, v2
	v_cndmask_b32_e64 v245, v105, v104, s[88:89]
	v_min_u32_e32 v106, v247, v3
	v_max_u32_e32 v107, v247, v3
	v_cndmask_b32_e64 v247, v107, v106, s[88:89]
	v_min_u32_e32 v104, v242, v4
	v_max_u32_e32 v105, v242, v4
	v_cndmask_b32_e64 v242, v105, v104, s[88:89]
	v_min_u32_e32 v106, v244, v5
	v_max_u32_e32 v107, v244, v5
	v_cndmask_b32_e64 v244, v107, v106, s[88:89]
	v_min_u32_e32 v104, v246, v6
	v_max_u32_e32 v105, v246, v6
	v_cndmask_b32_e64 v246, v105, v104, s[88:89]
	v_min_u32_e32 v106, v248, v7
	v_max_u32_e32 v107, v248, v7
	v_cndmask_b32_e64 v248, v107, v106, s[88:89]
	v_xor_b32_e32 v116, 4, v234
	ds_bpermute_b32 v0, v116, v241
	ds_bpermute_b32 v1, v116, v243
	ds_bpermute_b32 v2, v116, v245
	ds_bpermute_b32 v3, v116, v247
	ds_bpermute_b32 v4, v116, v242
	ds_bpermute_b32 v5, v116, v244
	ds_bpermute_b32 v6, v116, v246
	ds_bpermute_b32 v7, v116, v248
	s_waitcnt lgkmcnt(0)
	s_mov_b32 s88, 0x55555555
	s_mov_b32 s89, 0xaaaaaaaa
	v_min_u32_e32 v104, v241, v0
	v_max_u32_e32 v105, v241, v0
	v_cndmask_b32_e64 v241, v105, v104, s[88:89]
	v_min_u32_e32 v106, v243, v1
	v_max_u32_e32 v107, v243, v1
	v_cndmask_b32_e64 v243, v107, v106, s[88:89]
	v_min_u32_e32 v104, v245, v2
	v_max_u32_e32 v105, v245, v2
	v_cndmask_b32_e64 v245, v105, v104, s[88:89]
	v_min_u32_e32 v106, v247, v3
	v_max_u32_e32 v107, v247, v3
	v_cndmask_b32_e64 v247, v107, v106, s[88:89]
	v_min_u32_e32 v104, v242, v4
	v_max_u32_e32 v105, v242, v4
	v_cndmask_b32_e64 v242, v105, v104, s[88:89]
	v_min_u32_e32 v106, v244, v5
	v_max_u32_e32 v107, v244, v5
	v_cndmask_b32_e64 v244, v107, v106, s[88:89]
	v_min_u32_e32 v104, v246, v6
	v_max_u32_e32 v105, v246, v6
	v_cndmask_b32_e64 v246, v105, v104, s[88:89]
	v_min_u32_e32 v106, v248, v7
	v_max_u32_e32 v107, v248, v7
	v_cndmask_b32_e64 v248, v107, v106, s[88:89]
	v_xor_b32_e32 v116, 128, v234
	ds_bpermute_b32 v0, v116, v241
	ds_bpermute_b32 v1, v116, v243
	ds_bpermute_b32 v2, v116, v245
	ds_bpermute_b32 v3, v116, v247
	ds_bpermute_b32 v4, v116, v242
	ds_bpermute_b32 v5, v116, v244
	ds_bpermute_b32 v6, v116, v246
	ds_bpermute_b32 v7, v116, v248
	s_waitcnt lgkmcnt(0)
	s_mov_b32 s88, 0xffffffff
	s_mov_b32 s89, 0x0
	v_min_u32_e32 v104, v241, v0
	v_max_u32_e32 v105, v241, v0
	v_cndmask_b32_e64 v241, v105, v104, s[88:89]
	v_min_u32_e32 v106, v243, v1
	v_max_u32_e32 v107, v243, v1
	v_cndmask_b32_e64 v243, v107, v106, s[88:89]
	v_min_u32_e32 v104, v245, v2
	v_max_u32_e32 v105, v245, v2
	v_cndmask_b32_e64 v245, v105, v104, s[88:89]
	v_min_u32_e32 v106, v247, v3
	v_max_u32_e32 v107, v247, v3
	v_cndmask_b32_e64 v247, v107, v106, s[88:89]
	s_mov_b32 s88, 0x0
	s_mov_b32 s89, 0xffffffff
	v_min_u32_e32 v104, v242, v4
	v_max_u32_e32 v105, v242, v4
	v_cndmask_b32_e64 v242, v105, v104, s[88:89]
	v_min_u32_e32 v106, v244, v5
	v_max_u32_e32 v107, v244, v5
	v_cndmask_b32_e64 v244, v107, v106, s[88:89]
	v_min_u32_e32 v104, v246, v6
	v_max_u32_e32 v105, v246, v6
	v_cndmask_b32_e64 v246, v105, v104, s[88:89]
	v_min_u32_e32 v106, v248, v7
	v_max_u32_e32 v107, v248, v7
	v_cndmask_b32_e64 v248, v107, v106, s[88:89]
	v_xor_b32_e32 v116, 64, v234
	ds_bpermute_b32 v0, v116, v241
	ds_bpermute_b32 v1, v116, v243
	ds_bpermute_b32 v2, v116, v245
	ds_bpermute_b32 v3, v116, v247
	ds_bpermute_b32 v4, v116, v242
	ds_bpermute_b32 v5, v116, v244
	ds_bpermute_b32 v6, v116, v246
	ds_bpermute_b32 v7, v116, v248
	s_waitcnt lgkmcnt(0)
	s_mov_b32 s88, 0xffff
	s_mov_b32 s89, 0xffff
	v_min_u32_e32 v104, v241, v0
	v_max_u32_e32 v105, v241, v0
	v_cndmask_b32_e64 v241, v105, v104, s[88:89]
	v_min_u32_e32 v106, v243, v1
	v_max_u32_e32 v107, v243, v1
	v_cndmask_b32_e64 v243, v107, v106, s[88:89]
	v_min_u32_e32 v104, v245, v2
	v_max_u32_e32 v105, v245, v2
	v_cndmask_b32_e64 v245, v105, v104, s[88:89]
	v_min_u32_e32 v106, v247, v3
	v_max_u32_e32 v107, v247, v3
	v_cndmask_b32_e64 v247, v107, v106, s[88:89]
	s_mov_b32 s88, 0xffff0000
	s_mov_b32 s89, 0xffff0000
	v_min_u32_e32 v104, v242, v4
	v_max_u32_e32 v105, v242, v4
	v_cndmask_b32_e64 v242, v105, v104, s[88:89]
	v_min_u32_e32 v106, v244, v5
	v_max_u32_e32 v107, v244, v5
	v_cndmask_b32_e64 v244, v107, v106, s[88:89]
	v_min_u32_e32 v104, v246, v6
	v_max_u32_e32 v105, v246, v6
	v_cndmask_b32_e64 v246, v105, v104, s[88:89]
	v_min_u32_e32 v106, v248, v7
	v_max_u32_e32 v107, v248, v7
	v_cndmask_b32_e64 v248, v107, v106, s[88:89]
	v_xor_b32_e32 v116, 32, v234
	ds_bpermute_b32 v0, v116, v241
	ds_bpermute_b32 v1, v116, v243
	ds_bpermute_b32 v2, v116, v245
	ds_bpermute_b32 v3, v116, v247
	ds_bpermute_b32 v4, v116, v242
	ds_bpermute_b32 v5, v116, v244
	ds_bpermute_b32 v6, v116, v246
	ds_bpermute_b32 v7, v116, v248
	s_waitcnt lgkmcnt(0)
	s_mov_b32 s88, 0xff00ff
	s_mov_b32 s89, 0xff00ff
	v_min_u32_e32 v104, v241, v0
	v_max_u32_e32 v105, v241, v0
	v_cndmask_b32_e64 v241, v105, v104, s[88:89]
	v_min_u32_e32 v106, v243, v1
	v_max_u32_e32 v107, v243, v1
	v_cndmask_b32_e64 v243, v107, v106, s[88:89]
	v_min_u32_e32 v104, v245, v2
	v_max_u32_e32 v105, v245, v2
	v_cndmask_b32_e64 v245, v105, v104, s[88:89]
	v_min_u32_e32 v106, v247, v3
	v_max_u32_e32 v107, v247, v3
	v_cndmask_b32_e64 v247, v107, v106, s[88:89]
	s_mov_b32 s88, 0xff00ff00
	s_mov_b32 s89, 0xff00ff00
	v_min_u32_e32 v104, v242, v4
	v_max_u32_e32 v105, v242, v4
	v_cndmask_b32_e64 v242, v105, v104, s[88:89]
	v_min_u32_e32 v106, v244, v5
	v_max_u32_e32 v107, v244, v5
	v_cndmask_b32_e64 v244, v107, v106, s[88:89]
	v_min_u32_e32 v104, v246, v6
	v_max_u32_e32 v105, v246, v6
	v_cndmask_b32_e64 v246, v105, v104, s[88:89]
	v_min_u32_e32 v106, v248, v7
	v_max_u32_e32 v107, v248, v7
	v_cndmask_b32_e64 v248, v107, v106, s[88:89]
	v_xor_b32_e32 v116, 16, v234
	ds_bpermute_b32 v0, v116, v241
	ds_bpermute_b32 v1, v116, v243
	ds_bpermute_b32 v2, v116, v245
	ds_bpermute_b32 v3, v116, v247
	ds_bpermute_b32 v4, v116, v242
	ds_bpermute_b32 v5, v116, v244
	ds_bpermute_b32 v6, v116, v246
	ds_bpermute_b32 v7, v116, v248
	s_waitcnt lgkmcnt(0)
; DEV void sort_lists(int lane, int& myi0, int& myi1, float& myg0, float& myg1) {
; #pragma unroll
;     for (int k = 2; k <= 128; k <<= 1) {
; #pragma unroll
;       for (int j = k >> 1; j >= 1; j >>= 1) {
;         if (j == 64) {
;           const bool sw_ = myi1 < myi0;
;           const int ti = sw_ ? myi1 : myi0, tj = sw_ ? myi0 : myi1; const float tg = sw_ ? myg1 : myg0, th = sw_ ? myg0 : myg1;
;           myi0 = ti; myi1 = tj; myg0 = tg; myg1 = th;
;         } else {
;           const bool lower = (lane & j) == 0;
;           {
;             const bool up = (k == 128) ? true : ((k == 64) ? true : ((lane & k) == 0));
;             const int oi = __shfl_xor(myi0, j); const float og = __shfl_xor(myg0, j);
;             const bool take = (lower == up) ? (oi < myi0) : (oi > myi0);
;             myi0 = take ? oi : myi0; myg0 = take ? og : myg0;
;           }
;           {
;             const bool up = (k == 128) ? true : ((k == 64) ? false : ((lane & k) == 0));
;             const int oi = __shfl_xor(myi1, j); const float og = __shfl_xor(myg1, j);
;             const bool take = (lower == up) ? (oi < myi1) : (oi > myi1);
;             myi1 = take ? oi : myi1; myg1 = take ? og : myg1;
;           }
;         }
;       }
;     }
; }
	s_mov_b32 s88, 0xf0f0f0f
	s_mov_b32 s89, 0xf0f0f0f
	v_min_u32_e32 v104, v241, v0
	v_max_u32_e32 v105, v241, v0
	v_cndmask_b32_e64 v241, v105, v104, s[88:89]
	v_min_u32_e32 v106, v243, v1
	v_max_u32_e32 v107, v243, v1
	v_cndmask_b32_e64 v243, v107, v106, s[88:89]
	v_min_u32_e32 v104, v245, v2
	v_max_u32_e32 v105, v245, v2
	v_cndmask_b32_e64 v245, v105, v104, s[88:89]
	v_min_u32_e32 v106, v247, v3
	v_max_u32_e32 v107, v247, v3
	v_cndmask_b32_e64 v247, v107, v106, s[88:89]
	s_mov_b32 s88, 0xf0f0f0f0
	s_mov_b32 s89, 0xf0f0f0f0
	v_min_u32_e32 v104, v242, v4
	v_max_u32_e32 v105, v242, v4
	v_cndmask_b32_e64 v242, v105, v104, s[88:89]
	v_min_u32_e32 v106, v244, v5
	v_max_u32_e32 v107, v244, v5
	v_cndmask_b32_e64 v244, v107, v106, s[88:89]
	v_min_u32_e32 v104, v246, v6
	v_max_u32_e32 v105, v246, v6
	v_cndmask_b32_e64 v246, v105, v104, s[88:89]
	v_min_u32_e32 v106, v248, v7
	v_max_u32_e32 v107, v248, v7
	v_cndmask_b32_e64 v248, v107, v106, s[88:89]
	v_xor_b32_e32 v116, 8, v234
	ds_bpermute_b32 v0, v116, v241
	ds_bpermute_b32 v1, v116, v243
	ds_bpermute_b32 v2, v116, v245
	ds_bpermute_b32 v3, v116, v247
	ds_bpermute_b32 v4, v116, v242
	ds_bpermute_b32 v5, v116, v244
	ds_bpermute_b32 v6, v116, v246
	ds_bpermute_b32 v7, v116, v248
	s_waitcnt lgkmcnt(0)
	s_mov_b32 s88, 0x33333333
	s_mov_b32 s89, 0x33333333
	v_min_u32_e32 v104, v241, v0
	v_max_u32_e32 v105, v241, v0
	v_cndmask_b32_e64 v241, v105, v104, s[88:89]
	v_min_u32_e32 v106, v243, v1
	v_max_u32_e32 v107, v243, v1
	v_cndmask_b32_e64 v243, v107, v106, s[88:89]
	v_min_u32_e32 v104, v245, v2
	v_max_u32_e32 v105, v245, v2
	v_cndmask_b32_e64 v245, v105, v104, s[88:89]
	v_min_u32_e32 v106, v247, v3
	v_max_u32_e32 v107, v247, v3
	v_cndmask_b32_e64 v247, v107, v106, s[88:89]
	s_mov_b32 s88, 0xcccccccc
	s_mov_b32 s89, 0xcccccccc
	v_min_u32_e32 v104, v242, v4
	v_max_u32_e32 v105, v242, v4
	v_cndmask_b32_e64 v242, v105, v104, s[88:89]
	v_min_u32_e32 v106, v244, v5
	v_max_u32_e32 v107, v244, v5
	v_cndmask_b32_e64 v244, v107, v106, s[88:89]
	v_min_u32_e32 v104, v246, v6
	v_max_u32_e32 v105, v246, v6
	v_cndmask_b32_e64 v246, v105, v104, s[88:89]
	v_min_u32_e32 v106, v248, v7
	v_max_u32_e32 v107, v248, v7
	v_cndmask_b32_e64 v248, v107, v106, s[88:89]
	v_xor_b32_e32 v116, 4, v234
	ds_bpermute_b32 v0, v116, v241
	ds_bpermute_b32 v1, v116, v243
	ds_bpermute_b32 v2, v116, v245
	ds_bpermute_b32 v3, v116, v247
	ds_bpermute_b32 v4, v116, v242
	ds_bpermute_b32 v5, v116, v244
	ds_bpermute_b32 v6, v116, v246
	ds_bpermute_b32 v7, v116, v248
	s_waitcnt lgkmcnt(0)
	s_mov_b32 s88, 0x55555555
	s_mov_b32 s89, 0x55555555
	v_min_u32_e32 v104, v241, v0
	v_max_u32_e32 v105, v241, v0
	v_cndmask_b32_e64 v241, v105, v104, s[88:89]
	v_min_u32_e32 v106, v243, v1
	v_max_u32_e32 v107, v243, v1
	v_cndmask_b32_e64 v243, v107, v106, s[88:89]
	v_min_u32_e32 v104, v245, v2
	v_max_u32_e32 v105, v245, v2
	v_cndmask_b32_e64 v245, v105, v104, s[88:89]
	v_min_u32_e32 v106, v247, v3
	v_max_u32_e32 v107, v247, v3
	v_cndmask_b32_e64 v247, v107, v106, s[88:89]
	s_mov_b32 s88, 0xaaaaaaaa
	s_mov_b32 s89, 0xaaaaaaaa
	v_min_u32_e32 v104, v242, v4
	v_max_u32_e32 v105, v242, v4
	v_cndmask_b32_e64 v242, v105, v104, s[88:89]
	v_min_u32_e32 v106, v244, v5
	v_max_u32_e32 v107, v244, v5
	v_cndmask_b32_e64 v244, v107, v106, s[88:89]
	v_min_u32_e32 v104, v246, v6
	v_max_u32_e32 v105, v246, v6
	v_cndmask_b32_e64 v246, v105, v104, s[88:89]
	v_min_u32_e32 v106, v248, v7
	v_max_u32_e32 v107, v248, v7
	v_cndmask_b32_e64 v248, v107, v106, s[88:89]
	v_min_u32_e32 v104, v241, v242
	v_max_u32_e32 v242, v241, v242
	v_mov_b32_e32 v241, v104
	v_min_u32_e32 v106, v243, v244
	v_max_u32_e32 v244, v243, v244
	v_mov_b32_e32 v243, v106
	v_min_u32_e32 v104, v245, v246
	v_max_u32_e32 v246, v245, v246
	v_mov_b32_e32 v245, v104
	v_min_u32_e32 v106, v247, v248
	v_max_u32_e32 v248, v247, v248
	v_mov_b32_e32 v247, v106
	v_xor_b32_e32 v116, 128, v234
	ds_bpermute_b32 v0, v116, v241
	ds_bpermute_b32 v1, v116, v243
	ds_bpermute_b32 v2, v116, v245
	ds_bpermute_b32 v3, v116, v247
	ds_bpermute_b32 v4, v116, v242
	ds_bpermute_b32 v5, v116, v244
	ds_bpermute_b32 v6, v116, v246
	ds_bpermute_b32 v7, v116, v248
	s_waitcnt lgkmcnt(0)
	s_mov_b32 s88, 0xffffffff
	s_mov_b32 s89, 0x0
	v_min_u32_e32 v104, v241, v0
	v_max_u32_e32 v105, v241, v0
	v_cndmask_b32_e64 v241, v105, v104, s[88:89]
	v_min_u32_e32 v106, v243, v1
	v_max_u32_e32 v107, v243, v1
	v_cndmask_b32_e64 v243, v107, v106, s[88:89]
	v_min_u32_e32 v104, v245, v2
	v_max_u32_e32 v105, v245, v2
	v_cndmask_b32_e64 v245, v105, v104, s[88:89]
	v_min_u32_e32 v106, v247, v3
	v_max_u32_e32 v107, v247, v3
	v_cndmask_b32_e64 v247, v107, v106, s[88:89]
	v_min_u32_e32 v104, v242, v4
	v_max_u32_e32 v105, v242, v4
	v_cndmask_b32_e64 v242, v105, v104, s[88:89]
	v_min_u32_e32 v106, v244, v5
	v_max_u32_e32 v107, v244, v5
	v_cndmask_b32_e64 v244, v107, v106, s[88:89]
	v_min_u32_e32 v104, v246, v6
	v_max_u32_e32 v105, v246, v6
	v_cndmask_b32_e64 v246, v105, v104, s[88:89]
	v_min_u32_e32 v106, v248, v7
	v_max_u32_e32 v107, v248, v7
	v_cndmask_b32_e64 v248, v107, v106, s[88:89]
	v_xor_b32_e32 v116, 64, v234
	ds_bpermute_b32 v0, v116, v241
	ds_bpermute_b32 v1, v116, v243
	ds_bpermute_b32 v2, v116, v245
	ds_bpermute_b32 v3, v116, v247
	ds_bpermute_b32 v4, v116, v242
	ds_bpermute_b32 v5, v116, v244
	ds_bpermute_b32 v6, v116, v246
	ds_bpermute_b32 v7, v116, v248
	s_waitcnt lgkmcnt(0)
; DEV void sort_lists(int lane, int& myi0, int& myi1, float& myg0, float& myg1) {
; #pragma unroll
;     for (int k = 2; k <= 128; k <<= 1) {
; #pragma unroll
;       for (int j = k >> 1; j >= 1; j >>= 1) {
;         if (j == 64) {
;           const bool sw_ = myi1 < myi0;
;           const int ti = sw_ ? myi1 : myi0, tj = sw_ ? myi0 : myi1; const float tg = sw_ ? myg1 : myg0, th = sw_ ? myg0 : myg1;
;           myi0 = ti; myi1 = tj; myg0 = tg; myg1 = th;
;         } else {
;           const bool lower = (lane & j) == 0;
;           {
;             const bool up = (k == 128) ? true : ((k == 64) ? true : ((lane & k) == 0));
;             const int oi = __shfl_xor(myi0, j); const float og = __shfl_xor(myg0, j);
;             const bool take = (lower == up) ? (oi < myi0) : (oi > myi0);
;             myi0 = take ? oi : myi0; myg0 = take ? og : myg0;
;           }
;           {
;             const bool up = (k == 128) ? true : ((k == 64) ? false : ((lane & k) == 0));
;             const int oi = __shfl_xor(myi1, j); const float og = __shfl_xor(myg1, j);
;             const bool take = (lower == up) ? (oi < myi1) : (oi > myi1);
;             myi1 = take ? oi : myi1; myg1 = take ? og : myg1;
;           }
;         }
;       }
;     }
; }
	s_mov_b32 s88, 0xffff
	s_mov_b32 s89, 0xffff
	v_min_u32_e32 v104, v241, v0
	v_max_u32_e32 v105, v241, v0
	v_cndmask_b32_e64 v241, v105, v104, s[88:89]
	v_min_u32_e32 v106, v243, v1
	v_max_u32_e32 v107, v243, v1
	v_cndmask_b32_e64 v243, v107, v106, s[88:89]
	v_min_u32_e32 v104, v245, v2
	v_max_u32_e32 v105, v245, v2
	v_cndmask_b32_e64 v245, v105, v104, s[88:89]
	v_min_u32_e32 v106, v247, v3
	v_max_u32_e32 v107, v247, v3
	v_cndmask_b32_e64 v247, v107, v106, s[88:89]
	v_min_u32_e32 v104, v242, v4
	v_max_u32_e32 v105, v242, v4
	v_cndmask_b32_e64 v242, v105, v104, s[88:89]
	v_min_u32_e32 v106, v244, v5
	v_max_u32_e32 v107, v244, v5
	v_cndmask_b32_e64 v244, v107, v106, s[88:89]
	v_min_u32_e32 v104, v246, v6
	v_max_u32_e32 v105, v246, v6
	v_cndmask_b32_e64 v246, v105, v104, s[88:89]
	v_min_u32_e32 v106, v248, v7
	v_max_u32_e32 v107, v248, v7
	v_cndmask_b32_e64 v248, v107, v106, s[88:89]
	v_xor_b32_e32 v116, 32, v234
	ds_bpermute_b32 v0, v116, v241
	ds_bpermute_b32 v1, v116, v243
	ds_bpermute_b32 v2, v116, v245
	ds_bpermute_b32 v3, v116, v247
	ds_bpermute_b32 v4, v116, v242
	ds_bpermute_b32 v5, v116, v244
	ds_bpermute_b32 v6, v116, v246
	ds_bpermute_b32 v7, v116, v248
	s_waitcnt lgkmcnt(0)
	s_mov_b32 s88, 0xff00ff
	s_mov_b32 s89, 0xff00ff
	v_min_u32_e32 v104, v241, v0
	v_max_u32_e32 v105, v241, v0
	v_cndmask_b32_e64 v241, v105, v104, s[88:89]
	v_min_u32_e32 v106, v243, v1
	v_max_u32_e32 v107, v243, v1
	v_cndmask_b32_e64 v243, v107, v106, s[88:89]
	v_min_u32_e32 v104, v245, v2
	v_max_u32_e32 v105, v245, v2
	v_cndmask_b32_e64 v245, v105, v104, s[88:89]
	v_min_u32_e32 v106, v247, v3
	v_max_u32_e32 v107, v247, v3
	v_cndmask_b32_e64 v247, v107, v106, s[88:89]
	v_min_u32_e32 v104, v242, v4
	v_max_u32_e32 v105, v242, v4
	v_cndmask_b32_e64 v242, v105, v104, s[88:89]
	v_min_u32_e32 v106, v244, v5
	v_max_u32_e32 v107, v244, v5
	v_cndmask_b32_e64 v244, v107, v106, s[88:89]
	v_min_u32_e32 v104, v246, v6
	v_max_u32_e32 v105, v246, v6
	v_cndmask_b32_e64 v246, v105, v104, s[88:89]
	v_min_u32_e32 v106, v248, v7
	v_max_u32_e32 v107, v248, v7
	v_cndmask_b32_e64 v248, v107, v106, s[88:89]
	v_xor_b32_e32 v116, 16, v234
	ds_bpermute_b32 v0, v116, v241
	ds_bpermute_b32 v1, v116, v243
	ds_bpermute_b32 v2, v116, v245
	ds_bpermute_b32 v3, v116, v247
	ds_bpermute_b32 v4, v116, v242
	ds_bpermute_b32 v5, v116, v244
	ds_bpermute_b32 v6, v116, v246
	ds_bpermute_b32 v7, v116, v248
	s_waitcnt lgkmcnt(0)
	s_mov_b32 s88, 0xf0f0f0f
	s_mov_b32 s89, 0xf0f0f0f
	v_min_u32_e32 v104, v241, v0
	v_max_u32_e32 v105, v241, v0
	v_cndmask_b32_e64 v241, v105, v104, s[88:89]
	v_min_u32_e32 v106, v243, v1
	v_max_u32_e32 v107, v243, v1
	v_cndmask_b32_e64 v243, v107, v106, s[88:89]
	v_min_u32_e32 v104, v245, v2
	v_max_u32_e32 v105, v245, v2
	v_cndmask_b32_e64 v245, v105, v104, s[88:89]
	v_min_u32_e32 v106, v247, v3
	v_max_u32_e32 v107, v247, v3
	v_cndmask_b32_e64 v247, v107, v106, s[88:89]
	v_min_u32_e32 v104, v242, v4
	v_max_u32_e32 v105, v242, v4
	v_cndmask_b32_e64 v242, v105, v104, s[88:89]
	v_min_u32_e32 v106, v244, v5
	v_max_u32_e32 v107, v244, v5
	v_cndmask_b32_e64 v244, v107, v106, s[88:89]
	v_min_u32_e32 v104, v246, v6
	v_max_u32_e32 v105, v246, v6
	v_cndmask_b32_e64 v246, v105, v104, s[88:89]
	v_min_u32_e32 v106, v248, v7
	v_max_u32_e32 v107, v248, v7
	v_cndmask_b32_e64 v248, v107, v106, s[88:89]
	v_xor_b32_e32 v116, 8, v234
	ds_bpermute_b32 v0, v116, v241
	ds_bpermute_b32 v1, v116, v243
	ds_bpermute_b32 v2, v116, v245
	ds_bpermute_b32 v3, v116, v247
	ds_bpermute_b32 v4, v116, v242
	ds_bpermute_b32 v5, v116, v244
	ds_bpermute_b32 v6, v116, v246
	ds_bpermute_b32 v7, v116, v248
	s_waitcnt lgkmcnt(0)
	s_mov_b32 s88, 0x33333333
	s_mov_b32 s89, 0x33333333
	v_min_u32_e32 v104, v241, v0
	v_max_u32_e32 v105, v241, v0
	v_cndmask_b32_e64 v241, v105, v104, s[88:89]
	v_min_u32_e32 v106, v243, v1
	v_max_u32_e32 v107, v243, v1
	v_cndmask_b32_e64 v243, v107, v106, s[88:89]
	v_min_u32_e32 v104, v245, v2
	v_max_u32_e32 v105, v245, v2
	v_cndmask_b32_e64 v245, v105, v104, s[88:89]
	v_min_u32_e32 v106, v247, v3
	v_max_u32_e32 v107, v247, v3
	v_cndmask_b32_e64 v247, v107, v106, s[88:89]
	v_min_u32_e32 v104, v242, v4
	v_max_u32_e32 v105, v242, v4
	v_cndmask_b32_e64 v242, v105, v104, s[88:89]
	v_min_u32_e32 v106, v244, v5
	v_max_u32_e32 v107, v244, v5
	v_cndmask_b32_e64 v244, v107, v106, s[88:89]
	v_min_u32_e32 v104, v246, v6
	v_max_u32_e32 v105, v246, v6
	v_cndmask_b32_e64 v246, v105, v104, s[88:89]
	v_min_u32_e32 v106, v248, v7
	v_max_u32_e32 v107, v248, v7
	v_cndmask_b32_e64 v248, v107, v106, s[88:89]
	v_xor_b32_e32 v116, 4, v234
	ds_bpermute_b32 v0, v116, v241
	ds_bpermute_b32 v1, v116, v243
	ds_bpermute_b32 v2, v116, v245
	ds_bpermute_b32 v3, v116, v247
	ds_bpermute_b32 v4, v116, v242
	ds_bpermute_b32 v5, v116, v244
	ds_bpermute_b32 v6, v116, v246
	ds_bpermute_b32 v7, v116, v248
	s_waitcnt lgkmcnt(0)
; DEV void sort_lists(int lane, int& myi0, int& myi1, float& myg0, float& myg1) {
; #pragma unroll
;     for (int k = 2; k <= 128; k <<= 1) {
; #pragma unroll
;       for (int j = k >> 1; j >= 1; j >>= 1) {
;         if (j == 64) {
;           const bool sw_ = myi1 < myi0;
;           const int ti = sw_ ? myi1 : myi0, tj = sw_ ? myi0 : myi1; const float tg = sw_ ? myg1 : myg0, th = sw_ ? myg0 : myg1;
;           myi0 = ti; myi1 = tj; myg0 = tg; myg1 = th;
;         } else {
;           const bool lower = (lane & j) == 0;
;           {
;             const bool up = (k == 128) ? true : ((k == 64) ? true : ((lane & k) == 0));
;             const int oi = __shfl_xor(myi0, j); const float og = __shfl_xor(myg0, j);
;             const bool take = (lower == up) ? (oi < myi0) : (oi > myi0);
;             myi0 = take ? oi : myi0; myg0 = take ? og : myg0;
;           }
;           {
;             const bool up = (k == 128) ? true : ((k == 64) ? false : ((lane & k) == 0));
;             const int oi = __shfl_xor(myi1, j); const float og = __shfl_xor(myg1, j);
;             const bool take = (lower == up) ? (oi < myi1) : (oi > myi1);
;             myi1 = take ? oi : myi1; myg1 = take ? og : myg1;
;           }
;         }
;       }
;     }
; }
	s_mov_b32 s88, 0x55555555
	s_mov_b32 s89, 0x55555555
	v_min_u32_e32 v104, v241, v0
	v_max_u32_e32 v105, v241, v0
	v_cndmask_b32_e64 v241, v105, v104, s[88:89]
	v_min_u32_e32 v106, v243, v1
	v_max_u32_e32 v107, v243, v1
	v_cndmask_b32_e64 v243, v107, v106, s[88:89]
	v_min_u32_e32 v104, v245, v2
	v_max_u32_e32 v105, v245, v2
	v_cndmask_b32_e64 v245, v105, v104, s[88:89]
	v_min_u32_e32 v106, v247, v3
	v_max_u32_e32 v107, v247, v3
	v_cndmask_b32_e64 v247, v107, v106, s[88:89]
	v_min_u32_e32 v104, v242, v4
	v_max_u32_e32 v105, v242, v4
	v_cndmask_b32_e64 v242, v105, v104, s[88:89]
	v_min_u32_e32 v106, v244, v5
	v_max_u32_e32 v107, v244, v5
	v_cndmask_b32_e64 v244, v107, v106, s[88:89]
	v_min_u32_e32 v104, v246, v6
	v_max_u32_e32 v105, v246, v6
	v_cndmask_b32_e64 v246, v105, v104, s[88:89]
	v_min_u32_e32 v106, v248, v7
	v_max_u32_e32 v107, v248, v7
	v_cndmask_b32_e64 v248, v107, v106, s[88:89]
	v_mov_b32_e32 v117, 0
	s_lshl_b32 s98, s2, 11
	s_add_u32 s98, s98, s101
	v_add_u32_e32 v116, s98, v234
	v_and_b32_e32 v144, 0x7f, v241
	v_and_b32_e32 v241, 0xffffff80, v241
	v_lshl_or_b32 v241, v241, 3, v144
	ds_write_b32 v116, v241 offset:0
	v_and_b32_e32 v145, 0x7f, v242
	v_and_b32_e32 v242, 0xffffff80, v242
	v_lshl_or_b32 v242, v242, 3, v145
	ds_write_b32 v116, v242 offset:256
	v_and_b32_e32 v146, 0x7f, v243
	v_and_b32_e32 v243, 0xffffff80, v243
	v_lshl_or_b32 v243, v243, 3, v146
	ds_write_b32 v116, v243 offset:512
	v_and_b32_e32 v147, 0x7f, v244
	v_and_b32_e32 v244, 0xffffff80, v244
	v_lshl_or_b32 v244, v244, 3, v147
	ds_write_b32 v116, v244 offset:768
	v_and_b32_e32 v148, 0x7f, v245
	v_and_b32_e32 v245, 0xffffff80, v245
	v_lshl_or_b32 v245, v245, 3, v148
	ds_write_b32 v116, v245 offset:1024
	v_and_b32_e32 v149, 0x7f, v246
	v_and_b32_e32 v246, 0xffffff80, v246
	v_lshl_or_b32 v246, v246, 3, v149
	ds_write_b32 v116, v246 offset:1280
	v_and_b32_e32 v150, 0x7f, v247
	v_and_b32_e32 v247, 0xffffff80, v247
	v_lshl_or_b32 v247, v247, 3, v150
	ds_write_b32 v116, v247 offset:1536
	v_and_b32_e32 v151, 0x7f, v248
	v_and_b32_e32 v248, 0xffffff80, v248
	v_lshl_or_b32 v248, v248, 3, v151
	ds_write_b32 v116, v248 offset:1792
	v_add_u32_e32 v118, 0x10000, v116
	ds_write_b32 v118, v117 offset:0
	ds_write_b32 v118, v117 offset:256
	ds_write_b32 v118, v117 offset:512
	ds_write_b32 v118, v117 offset:768
	ds_write_b32 v118, v117 offset:1024
	ds_write_b32 v118, v117 offset:1280
	ds_write_b32 v118, v117 offset:1536
	ds_write_b32 v118, v117 offset:1792
	s_add_u32 s2, s2, 1
	s_cmp_lt_u32 s2, 4
	s_cbranch_scc1 .Lpg0_p0
	s_waitcnt lgkmcnt(0)
	v_readfirstlane_b32 s80, v124
	v_readfirstlane_b32 s81, v125
	s_nop 4
	s_waitcnt vmcnt(0) lgkmcnt(0)
	s_barrier
	v_readfirstlane_b32 s98, v176
	s_cmp_lt_u32 s98, 64
	s_cbranch_scc0 .Lpg0_sk1
	v_readfirstlane_b32 s82, v122
	v_readfirstlane_b32 s83, v123
	s_nop 4
	s_add_u32 s82, s82, 0x123800
	s_addc_u32 s83, s83, 0
	s_getreg_b32 s99, hwreg(HW_REG_XCC_ID, 0, 4)
	s_lshl_b32 s99, s99, 6
	v_mov_b32_e32 v144, s99
	v_mov_b32_e32 v145, 1
	v_mov_b32_e32 v146, 0x27fc0
	s_mov_b64 exec, 1
	ds_read_b32 v147, v146
	global_atomic_add v144, v145, s[82:83]
	s_waitcnt lgkmcnt(0)
	v_readfirstlane_b32 s92, v147
	s_mul_i32 s92, s92, 1
	s_mov_b32 s93, 0
.Lpg0_sp1:
	global_load_dword v148, v144, s[82:83] sc1
	s_waitcnt vmcnt(0)
	v_readfirstlane_b32 s99, v148
	s_cmp_ge_u32 s99, s92
	s_cbranch_scc1 .Lpg0_dn1
	s_sleep 2
	s_add_u32 s93, s93, 1
	s_cmp_lt_u32 s93, 4096
	s_cbranch_scc1 .Lpg0_sp1
.Lpg0_dn1:
	s_mov_b64 exec, -1
.Lpg0_sk1:
	s_barrier
	s_mov_b32 s90, 0xfffffc00
	s_mov_b32 s100, 0
	s_mov_b32 s98, 0
	s_mov_b32 s99, 0
	v_readfirstlane_b32 s82, v128
	v_readfirstlane_b32 s83, v129
	s_nop 4
	s_add_u32 vcc_lo, s3, s98
	s_lshl_b32 vcc_lo, vcc_lo, 11
	s_lshl_b32 vcc_hi, s99, 8
	s_add_u32 vcc_lo, vcc_lo, vcc_hi
	v_add_u32_e32 v119, vcc_lo, v236
	global_load_dwordx4 v[80:83], v119, s[82:83]
	global_load_dwordx4 v[84:87], v119, s[82:83] offset:16
	s_lshl_b32 vcc_lo, s98, 9
	s_add_u32 vcc_lo, vcc_lo, s101
	v_add_u32_e32 v116, vcc_lo, v234
	ds_read_b32 v134, v116
	ds_read_b32 v135, v116 offset:256
	s_lshl_b32 vcc_lo, s99, 7
	v_add_u32_e32 v240, vcc_lo, v235
	s_waitcnt lgkmcnt(0)
	ds_bpermute_b32 v142, v249, v134
	ds_bpermute_b32 v143, v250, v134
	s_waitcnt lgkmcnt(0)
	v_and_or_b32 v142, v142, s90, v240
	v_and_or_b32 v143, v143, s90, v240
	global_load_dwordx4 v[0:3], v142, s[80:81]
	global_load_dwordx4 v[4:7], v143, s[80:81]
	ds_bpermute_b32 v142, v251, v134
	ds_bpermute_b32 v143, v252, v134
	s_waitcnt lgkmcnt(0)
	v_and_or_b32 v142, v142, s90, v240
	v_and_or_b32 v143, v143, s90, v240
	global_load_dwordx4 v[8:11], v142, s[80:81]
	global_load_dwordx4 v[12:15], v143, s[80:81]
	ds_bpermute_b32 v142, v253, v134
	ds_bpermute_b32 v143, v254, v134
	s_waitcnt lgkmcnt(0)
	v_and_or_b32 v142, v142, s90, v240
	v_and_or_b32 v143, v143, s90, v240
	global_load_dwordx4 v[16:19], v142, s[80:81]
	global_load_dwordx4 v[20:23], v143, s[80:81]
	ds_bpermute_b32 v142, v255, v134
	ds_bpermute_b32 v143, v153, v134
	s_waitcnt lgkmcnt(0)
	v_and_or_b32 v142, v142, s90, v240
	v_and_or_b32 v143, v143, s90, v240
	global_load_dwordx4 v[24:27], v142, s[80:81]
	global_load_dwordx4 v[28:31], v143, s[80:81]
	ds_bpermute_b32 v142, v249, v135
	ds_bpermute_b32 v143, v250, v135
	s_waitcnt lgkmcnt(0)
	v_and_or_b32 v142, v142, s90, v240
	v_and_or_b32 v143, v143, s90, v240
	global_load_dwordx4 v[32:35], v142, s[80:81]
	global_load_dwordx4 v[36:39], v143, s[80:81]
	ds_bpermute_b32 v142, v251, v135
	ds_bpermute_b32 v143, v252, v135
	s_waitcnt lgkmcnt(0)
	v_and_or_b32 v142, v142, s90, v240
	v_and_or_b32 v143, v143, s90, v240
	global_load_dwordx4 v[40:43], v142, s[80:81]
	global_load_dwordx4 v[44:47], v143, s[80:81]
	ds_bpermute_b32 v142, v253, v135
	ds_bpermute_b32 v143, v254, v135
	s_waitcnt lgkmcnt(0)
	v_and_or_b32 v142, v142, s90, v240
	v_and_or_b32 v143, v143, s90, v240
	global_load_dwordx4 v[48:51], v142, s[80:81]
	global_load_dwordx4 v[52:55], v143, s[80:81]
	ds_bpermute_b32 v142, v255, v135
	ds_bpermute_b32 v143, v153, v135
	s_waitcnt lgkmcnt(0)
	v_and_or_b32 v142, v142, s90, v240
	v_and_or_b32 v143, v143, s90, v240
	global_load_dwordx4 v[56:59], v142, s[80:81]
	global_load_dwordx4 v[60:63], v143, s[80:81]
	s_mov_b32 s92, 1
	s_lshl_b32 vcc_lo, s92, 9
	s_add_u32 vcc_lo, vcc_lo, s101
	v_add_u32_e32 v116, vcc_lo, v234
	ds_read_b32 v134, v116
	ds_read_b32 v135, v116 offset:256
; #define PG_ISSUE(BUF, TAB, e0_) do { const int isrc_ = ((e0_) < 64) ? myi0 : myi1; \
;       _Pragma("unroll") for (int e = 0; e < 8; ++e) { const int idx_ = __builtin_amdgcn_readlane(isrc_, ((e0_) + e) & 63); \
;         BUF[e] = *(const u32x4*)((TAB) + (size_t)idx_ * 1024 + lane * 16); } } while (0)
; DEV void peer_gather(const Params& P, int l, int m0, const int* idxs, const float* gs) {
;     ...
;     PG_ISSUE(b0, U, 0);
; #pragma nounroll
;     for (int e0 = 0; e0 < 128; e0 += 16) {
;       PG_ISSUE(b1, U, e0 + 8);
;       PG_U8(b0, 0, e0);
;       if (e0 + 16 < 128) PG_ISSUE(b0, U, e0 + 16); else PG_ISSUE(b0, V, 0);
;       PG_U8(b1, 0, e0 + 8);
.Lpg0_uloop:
	s_and_b32 s98, s100, 15
	s_lshr_b32 s99, s100, 4
	s_add_u32 s92, s100, 1
	s_min_u32 s92, s92, 127
	s_lshr_b32 s93, s92, 4
	s_and_b32 s92, s92, 15
	s_waitcnt vmcnt(16)
	v_lshlrev_b32_e32 v64, 16, v80
	v_and_b32_e32 v65, 0xffff0000, v80
	v_lshlrev_b32_e32 v66, 16, v81
	v_and_b32_e32 v67, 0xffff0000, v81
	v_lshlrev_b32_e32 v68, 16, v82
	v_and_b32_e32 v69, 0xffff0000, v82
	v_lshlrev_b32_e32 v70, 16, v83
	v_and_b32_e32 v71, 0xffff0000, v83
	v_lshlrev_b32_e32 v72, 16, v84
	v_and_b32_e32 v73, 0xffff0000, v84
	v_lshlrev_b32_e32 v74, 16, v85
	v_and_b32_e32 v75, 0xffff0000, v85
	v_lshlrev_b32_e32 v76, 16, v86
	v_and_b32_e32 v77, 0xffff0000, v86
	v_lshlrev_b32_e32 v78, 16, v87
	v_and_b32_e32 v79, 0xffff0000, v87
	v_readfirstlane_b32 s82, v128
	v_readfirstlane_b32 s83, v129
	s_nop 4
	s_add_u32 vcc_lo, s3, s92
	s_lshl_b32 vcc_lo, vcc_lo, 11
	s_lshl_b32 vcc_hi, s93, 8
	s_add_u32 vcc_lo, vcc_lo, vcc_hi
	v_add_u32_e32 v119, vcc_lo, v236
	global_load_dwordx4 v[80:83], v119, s[82:83]
	global_load_dwordx4 v[84:87], v119, s[82:83] offset:16
	s_lshl_b32 vcc_lo, s93, 7
	v_add_u32_e32 v240, vcc_lo, v235
	s_waitcnt lgkmcnt(0)
	ds_bpermute_b32 v142, v249, v134
	ds_bpermute_b32 v143, v250, v134
	s_waitcnt vmcnt(16)
	v_cvt_pk_f32_fp8_e32 v[104:105], v0
	v_cvt_pk_f32_fp8_e32 v[108:109], v4
	v_cvt_pk_f32_fp8_sdwa v[106:107], v0 src0_sel:WORD_1
	v_cvt_pk_f32_fp8_sdwa v[110:111], v4 src0_sel:WORD_1
	v_pk_mul_f32 v[112:113], v[64:65], v[104:105]
	v_pk_mul_f32 v[114:115], v[64:65], v[108:109]
	v_pk_fma_f32 v[112:113], v[66:67], v[106:107], v[112:113]
	v_pk_fma_f32 v[114:115], v[66:67], v[110:111], v[114:115]
	v_cvt_pk_f32_fp8_e32 v[104:105], v1
	v_cvt_pk_f32_fp8_e32 v[108:109], v5
	v_cvt_pk_f32_fp8_sdwa v[106:107], v1 src0_sel:WORD_1
	v_cvt_pk_f32_fp8_sdwa v[110:111], v5 src0_sel:WORD_1
	v_pk_fma_f32 v[112:113], v[68:69], v[104:105], v[112:113]
	v_pk_fma_f32 v[114:115], v[68:69], v[108:109], v[114:115]
	v_pk_fma_f32 v[112:113], v[70:71], v[106:107], v[112:113]
	v_pk_fma_f32 v[114:115], v[70:71], v[110:111], v[114:115]
	v_cvt_pk_f32_fp8_e32 v[104:105], v2
	v_cvt_pk_f32_fp8_e32 v[108:109], v6
	v_cvt_pk_f32_fp8_sdwa v[106:107], v2 src0_sel:WORD_1
	v_cvt_pk_f32_fp8_sdwa v[110:111], v6 src0_sel:WORD_1
	v_pk_fma_f32 v[112:113], v[72:73], v[104:105], v[112:113]
	v_pk_fma_f32 v[114:115], v[72:73], v[108:109], v[114:115]
	v_pk_fma_f32 v[112:113], v[74:75], v[106:107], v[112:113]
	v_pk_fma_f32 v[114:115], v[74:75], v[110:111], v[114:115]
	v_cvt_pk_f32_fp8_e32 v[104:105], v3
	v_cvt_pk_f32_fp8_e32 v[108:109], v7
	v_cvt_pk_f32_fp8_sdwa v[106:107], v3 src0_sel:WORD_1
	v_cvt_pk_f32_fp8_sdwa v[110:111], v7 src0_sel:WORD_1
	v_pk_fma_f32 v[112:113], v[76:77], v[104:105], v[112:113]
	v_pk_fma_f32 v[114:115], v[76:77], v[108:109], v[114:115]
	s_waitcnt lgkmcnt(0)
	v_and_or_b32 v142, v142, s90, v240
	v_and_or_b32 v143, v143, s90, v240
	global_load_dwordx4 v[0:3], v142, s[80:81]
	global_load_dwordx4 v[4:7], v143, s[80:81]
	v_pk_fma_f32 v[112:113], v[78:79], v[106:107], v[112:113]
	v_pk_fma_f32 v[114:115], v[78:79], v[110:111], v[114:115]
	v_add_f32_e32 v88, v112, v113
	v_add_f32_e32 v89, v114, v115
	ds_bpermute_b32 v142, v251, v134
	ds_bpermute_b32 v143, v252, v134
	s_waitcnt vmcnt(16)
	v_cvt_pk_f32_fp8_e32 v[104:105], v8
	v_cvt_pk_f32_fp8_e32 v[108:109], v12
	v_cvt_pk_f32_fp8_sdwa v[106:107], v8 src0_sel:WORD_1
	v_cvt_pk_f32_fp8_sdwa v[110:111], v12 src0_sel:WORD_1
	v_pk_mul_f32 v[112:113], v[64:65], v[104:105]
	v_pk_mul_f32 v[114:115], v[64:65], v[108:109]
	v_pk_fma_f32 v[112:113], v[66:67], v[106:107], v[112:113]
	v_pk_fma_f32 v[114:115], v[66:67], v[110:111], v[114:115]
	v_cvt_pk_f32_fp8_e32 v[104:105], v9
	v_cvt_pk_f32_fp8_e32 v[108:109], v13
	v_cvt_pk_f32_fp8_sdwa v[106:107], v9 src0_sel:WORD_1
	v_cvt_pk_f32_fp8_sdwa v[110:111], v13 src0_sel:WORD_1
	v_pk_fma_f32 v[112:113], v[68:69], v[104:105], v[112:113]
	v_pk_fma_f32 v[114:115], v[68:69], v[108:109], v[114:115]
	v_pk_fma_f32 v[112:113], v[70:71], v[106:107], v[112:113]
	v_pk_fma_f32 v[114:115], v[70:71], v[110:111], v[114:115]
	v_cvt_pk_f32_fp8_e32 v[104:105], v10
	v_cvt_pk_f32_fp8_e32 v[108:109], v14
	v_cvt_pk_f32_fp8_sdwa v[106:107], v10 src0_sel:WORD_1
	v_cvt_pk_f32_fp8_sdwa v[110:111], v14 src0_sel:WORD_1
	v_pk_fma_f32 v[112:113], v[72:73], v[104:105], v[112:113]
	v_pk_fma_f32 v[114:115], v[72:73], v[108:109], v[114:115]
	v_pk_fma_f32 v[112:113], v[74:75], v[106:107], v[112:113]
	v_pk_fma_f32 v[114:115], v[74:75], v[110:111], v[114:115]
	v_cvt_pk_f32_fp8_e32 v[104:105], v11
	v_cvt_pk_f32_fp8_e32 v[108:109], v15
	v_cvt_pk_f32_fp8_sdwa v[106:107], v11 src0_sel:WORD_1
	v_cvt_pk_f32_fp8_sdwa v[110:111], v15 src0_sel:WORD_1
	v_pk_fma_f32 v[112:113], v[76:77], v[104:105], v[112:113]
	v_pk_fma_f32 v[114:115], v[76:77], v[108:109], v[114:115]
	s_waitcnt lgkmcnt(0)
	v_and_or_b32 v142, v142, s90, v240
	v_and_or_b32 v143, v143, s90, v240
	global_load_dwordx4 v[8:11], v142, s[80:81]
	global_load_dwordx4 v[12:15], v143, s[80:81]
	v_pk_fma_f32 v[112:113], v[78:79], v[106:107], v[112:113]
	v_pk_fma_f32 v[114:115], v[78:79], v[110:111], v[114:115]
	v_add_f32_e32 v90, v112, v113
	v_add_f32_e32 v91, v114, v115
	ds_bpermute_b32 v142, v253, v134
	ds_bpermute_b32 v143, v254, v134
	s_waitcnt vmcnt(16)
	v_cvt_pk_f32_fp8_e32 v[104:105], v16
	v_cvt_pk_f32_fp8_e32 v[108:109], v20
	v_cvt_pk_f32_fp8_sdwa v[106:107], v16 src0_sel:WORD_1
	v_cvt_pk_f32_fp8_sdwa v[110:111], v20 src0_sel:WORD_1
	v_pk_mul_f32 v[112:113], v[64:65], v[104:105]
	v_pk_mul_f32 v[114:115], v[64:65], v[108:109]
	v_pk_fma_f32 v[112:113], v[66:67], v[106:107], v[112:113]
	v_pk_fma_f32 v[114:115], v[66:67], v[110:111], v[114:115]
	v_cvt_pk_f32_fp8_e32 v[104:105], v17
	v_cvt_pk_f32_fp8_e32 v[108:109], v21
	v_cvt_pk_f32_fp8_sdwa v[106:107], v17 src0_sel:WORD_1
	v_cvt_pk_f32_fp8_sdwa v[110:111], v21 src0_sel:WORD_1
	v_pk_fma_f32 v[112:113], v[68:69], v[104:105], v[112:113]
	v_pk_fma_f32 v[114:115], v[68:69], v[108:109], v[114:115]
	v_pk_fma_f32 v[112:113], v[70:71], v[106:107], v[112:113]
	v_pk_fma_f32 v[114:115], v[70:71], v[110:111], v[114:115]
	v_cvt_pk_f32_fp8_e32 v[104:105], v18
	v_cvt_pk_f32_fp8_e32 v[108:109], v22
	v_cvt_pk_f32_fp8_sdwa v[106:107], v18 src0_sel:WORD_1
	v_cvt_pk_f32_fp8_sdwa v[110:111], v22 src0_sel:WORD_1
	v_pk_fma_f32 v[112:113], v[72:73], v[104:105], v[112:113]
	v_pk_fma_f32 v[114:115], v[72:73], v[108:109], v[114:115]
	v_pk_fma_f32 v[112:113], v[74:75], v[106:107], v[112:113]
	v_pk_fma_f32 v[114:115], v[74:75], v[110:111], v[114:115]
	v_cvt_pk_f32_fp8_e32 v[104:105], v19
	v_cvt_pk_f32_fp8_e32 v[108:109], v23
	v_cvt_pk_f32_fp8_sdwa v[106:107], v19 src0_sel:WORD_1
	v_cvt_pk_f32_fp8_sdwa v[110:111], v23 src0_sel:WORD_1
	v_pk_fma_f32 v[112:113], v[76:77], v[104:105], v[112:113]
	v_pk_fma_f32 v[114:115], v[76:77], v[108:109], v[114:115]
	s_waitcnt lgkmcnt(0)
	v_and_or_b32 v142, v142, s90, v240
	v_and_or_b32 v143, v143, s90, v240
	global_load_dwordx4 v[16:19], v142, s[80:81]
	global_load_dwordx4 v[20:23], v143, s[80:81]
	v_pk_fma_f32 v[112:113], v[78:79], v[106:107], v[112:113]
	v_pk_fma_f32 v[114:115], v[78:79], v[110:111], v[114:115]
	v_add_f32_e32 v92, v112, v113
	v_add_f32_e32 v93, v114, v115
	ds_bpermute_b32 v142, v255, v134
	ds_bpermute_b32 v143, v153, v134
	s_waitcnt vmcnt(16)
	v_cvt_pk_f32_fp8_e32 v[104:105], v24
	v_cvt_pk_f32_fp8_e32 v[108:109], v28
	v_cvt_pk_f32_fp8_sdwa v[106:107], v24 src0_sel:WORD_1
	v_cvt_pk_f32_fp8_sdwa v[110:111], v28 src0_sel:WORD_1
	v_pk_mul_f32 v[112:113], v[64:65], v[104:105]
	v_pk_mul_f32 v[114:115], v[64:65], v[108:109]
	v_pk_fma_f32 v[112:113], v[66:67], v[106:107], v[112:113]
	v_pk_fma_f32 v[114:115], v[66:67], v[110:111], v[114:115]
	v_cvt_pk_f32_fp8_e32 v[104:105], v25
	v_cvt_pk_f32_fp8_e32 v[108:109], v29
	v_cvt_pk_f32_fp8_sdwa v[106:107], v25 src0_sel:WORD_1
	v_cvt_pk_f32_fp8_sdwa v[110:111], v29 src0_sel:WORD_1
	v_pk_fma_f32 v[112:113], v[68:69], v[104:105], v[112:113]
	v_pk_fma_f32 v[114:115], v[68:69], v[108:109], v[114:115]
	v_pk_fma_f32 v[112:113], v[70:71], v[106:107], v[112:113]
	v_pk_fma_f32 v[114:115], v[70:71], v[110:111], v[114:115]
	v_cvt_pk_f32_fp8_e32 v[104:105], v26
	v_cvt_pk_f32_fp8_e32 v[108:109], v30
	v_cvt_pk_f32_fp8_sdwa v[106:107], v26 src0_sel:WORD_1
	v_cvt_pk_f32_fp8_sdwa v[110:111], v30 src0_sel:WORD_1
	v_pk_fma_f32 v[112:113], v[72:73], v[104:105], v[112:113]
	v_pk_fma_f32 v[114:115], v[72:73], v[108:109], v[114:115]
	v_pk_fma_f32 v[112:113], v[74:75], v[106:107], v[112:113]
	v_pk_fma_f32 v[114:115], v[74:75], v[110:111], v[114:115]
	v_cvt_pk_f32_fp8_e32 v[104:105], v27
	v_cvt_pk_f32_fp8_e32 v[108:109], v31
	v_cvt_pk_f32_fp8_sdwa v[106:107], v27 src0_sel:WORD_1
	v_cvt_pk_f32_fp8_sdwa v[110:111], v31 src0_sel:WORD_1
	v_pk_fma_f32 v[112:113], v[76:77], v[104:105], v[112:113]
	v_pk_fma_f32 v[114:115], v[76:77], v[108:109], v[114:115]
	s_waitcnt lgkmcnt(0)
	v_and_or_b32 v142, v142, s90, v240
	v_and_or_b32 v143, v143, s90, v240
	global_load_dwordx4 v[24:27], v142, s[80:81]
	global_load_dwordx4 v[28:31], v143, s[80:81]
	v_pk_fma_f32 v[112:113], v[78:79], v[106:107], v[112:113]
	v_pk_fma_f32 v[114:115], v[78:79], v[110:111], v[114:115]
	v_add_f32_e32 v94, v112, v113
	v_add_f32_e32 v95, v114, v115
	ds_bpermute_b32 v142, v249, v135
	ds_bpermute_b32 v143, v250, v135
	s_waitcnt vmcnt(16)
	v_cvt_pk_f32_fp8_e32 v[104:105], v32
	v_cvt_pk_f32_fp8_e32 v[108:109], v36
	v_cvt_pk_f32_fp8_sdwa v[106:107], v32 src0_sel:WORD_1
	v_cvt_pk_f32_fp8_sdwa v[110:111], v36 src0_sel:WORD_1
	v_pk_mul_f32 v[112:113], v[64:65], v[104:105]
	v_pk_mul_f32 v[114:115], v[64:65], v[108:109]
	v_pk_fma_f32 v[112:113], v[66:67], v[106:107], v[112:113]
	v_pk_fma_f32 v[114:115], v[66:67], v[110:111], v[114:115]
	v_cvt_pk_f32_fp8_e32 v[104:105], v33
	v_cvt_pk_f32_fp8_e32 v[108:109], v37
	v_cvt_pk_f32_fp8_sdwa v[106:107], v33 src0_sel:WORD_1
	v_cvt_pk_f32_fp8_sdwa v[110:111], v37 src0_sel:WORD_1
	v_pk_fma_f32 v[112:113], v[68:69], v[104:105], v[112:113]
	v_pk_fma_f32 v[114:115], v[68:69], v[108:109], v[114:115]
	v_pk_fma_f32 v[112:113], v[70:71], v[106:107], v[112:113]
	v_pk_fma_f32 v[114:115], v[70:71], v[110:111], v[114:115]
	v_cvt_pk_f32_fp8_e32 v[104:105], v34
	v_cvt_pk_f32_fp8_e32 v[108:109], v38
	v_cvt_pk_f32_fp8_sdwa v[106:107], v34 src0_sel:WORD_1
	v_cvt_pk_f32_fp8_sdwa v[110:111], v38 src0_sel:WORD_1
	v_pk_fma_f32 v[112:113], v[72:73], v[104:105], v[112:113]
	v_pk_fma_f32 v[114:115], v[72:73], v[108:109], v[114:115]
	v_pk_fma_f32 v[112:113], v[74:75], v[106:107], v[112:113]
	v_pk_fma_f32 v[114:115], v[74:75], v[110:111], v[114:115]
	v_cvt_pk_f32_fp8_e32 v[104:105], v35
	v_cvt_pk_f32_fp8_e32 v[108:109], v39
	v_cvt_pk_f32_fp8_sdwa v[106:107], v35 src0_sel:WORD_1
	v_cvt_pk_f32_fp8_sdwa v[110:111], v39 src0_sel:WORD_1
	v_pk_fma_f32 v[112:113], v[76:77], v[104:105], v[112:113]
	v_pk_fma_f32 v[114:115], v[76:77], v[108:109], v[114:115]
	s_waitcnt lgkmcnt(0)
	v_and_or_b32 v142, v142, s90, v240
	v_and_or_b32 v143, v143, s90, v240
	global_load_dwordx4 v[32:35], v142, s[80:81]
	global_load_dwordx4 v[36:39], v143, s[80:81]
	v_pk_fma_f32 v[112:113], v[78:79], v[106:107], v[112:113]
	v_pk_fma_f32 v[114:115], v[78:79], v[110:111], v[114:115]
	v_add_f32_e32 v96, v112, v113
	v_add_f32_e32 v97, v114, v115
	ds_bpermute_b32 v142, v251, v135
	ds_bpermute_b32 v143, v252, v135
	s_waitcnt vmcnt(16)
	v_cvt_pk_f32_fp8_e32 v[104:105], v40
	v_cvt_pk_f32_fp8_e32 v[108:109], v44
	v_cvt_pk_f32_fp8_sdwa v[106:107], v40 src0_sel:WORD_1
	v_cvt_pk_f32_fp8_sdwa v[110:111], v44 src0_sel:WORD_1
	v_pk_mul_f32 v[112:113], v[64:65], v[104:105]
	v_pk_mul_f32 v[114:115], v[64:65], v[108:109]
	v_pk_fma_f32 v[112:113], v[66:67], v[106:107], v[112:113]
	v_pk_fma_f32 v[114:115], v[66:67], v[110:111], v[114:115]
	v_cvt_pk_f32_fp8_e32 v[104:105], v41
	v_cvt_pk_f32_fp8_e32 v[108:109], v45
	v_cvt_pk_f32_fp8_sdwa v[106:107], v41 src0_sel:WORD_1
	v_cvt_pk_f32_fp8_sdwa v[110:111], v45 src0_sel:WORD_1
	v_pk_fma_f32 v[112:113], v[68:69], v[104:105], v[112:113]
	v_pk_fma_f32 v[114:115], v[68:69], v[108:109], v[114:115]
	v_pk_fma_f32 v[112:113], v[70:71], v[106:107], v[112:113]
	v_pk_fma_f32 v[114:115], v[70:71], v[110:111], v[114:115]
	v_cvt_pk_f32_fp8_e32 v[104:105], v42
	v_cvt_pk_f32_fp8_e32 v[108:109], v46
	v_cvt_pk_f32_fp8_sdwa v[106:107], v42 src0_sel:WORD_1
	v_cvt_pk_f32_fp8_sdwa v[110:111], v46 src0_sel:WORD_1
	v_pk_fma_f32 v[112:113], v[72:73], v[104:105], v[112:113]
	v_pk_fma_f32 v[114:115], v[72:73], v[108:109], v[114:115]
	v_pk_fma_f32 v[112:113], v[74:75], v[106:107], v[112:113]
	v_pk_fma_f32 v[114:115], v[74:75], v[110:111], v[114:115]
	v_cvt_pk_f32_fp8_e32 v[104:105], v43
	v_cvt_pk_f32_fp8_e32 v[108:109], v47
	v_cvt_pk_f32_fp8_sdwa v[106:107], v43 src0_sel:WORD_1
	v_cvt_pk_f32_fp8_sdwa v[110:111], v47 src0_sel:WORD_1
	v_pk_fma_f32 v[112:113], v[76:77], v[104:105], v[112:113]
	v_pk_fma_f32 v[114:115], v[76:77], v[108:109], v[114:115]
	s_waitcnt lgkmcnt(0)
	v_and_or_b32 v142, v142, s90, v240
	v_and_or_b32 v143, v143, s90, v240
	global_load_dwordx4 v[40:43], v142, s[80:81]
	global_load_dwordx4 v[44:47], v143, s[80:81]
	v_pk_fma_f32 v[112:113], v[78:79], v[106:107], v[112:113]
	v_pk_fma_f32 v[114:115], v[78:79], v[110:111], v[114:115]
	v_add_f32_e32 v98, v112, v113
	v_add_f32_e32 v99, v114, v115
	ds_bpermute_b32 v142, v253, v135
	ds_bpermute_b32 v143, v254, v135
	s_waitcnt vmcnt(16)
	v_cvt_pk_f32_fp8_e32 v[104:105], v48
	v_cvt_pk_f32_fp8_e32 v[108:109], v52
	v_cvt_pk_f32_fp8_sdwa v[106:107], v48 src0_sel:WORD_1
	v_cvt_pk_f32_fp8_sdwa v[110:111], v52 src0_sel:WORD_1
	v_pk_mul_f32 v[112:113], v[64:65], v[104:105]
	v_pk_mul_f32 v[114:115], v[64:65], v[108:109]
	v_pk_fma_f32 v[112:113], v[66:67], v[106:107], v[112:113]
	v_pk_fma_f32 v[114:115], v[66:67], v[110:111], v[114:115]
	v_cvt_pk_f32_fp8_e32 v[104:105], v49
	v_cvt_pk_f32_fp8_e32 v[108:109], v53
	v_cvt_pk_f32_fp8_sdwa v[106:107], v49 src0_sel:WORD_1
	v_cvt_pk_f32_fp8_sdwa v[110:111], v53 src0_sel:WORD_1
	v_pk_fma_f32 v[112:113], v[68:69], v[104:105], v[112:113]
	v_pk_fma_f32 v[114:115], v[68:69], v[108:109], v[114:115]
	v_pk_fma_f32 v[112:113], v[70:71], v[106:107], v[112:113]
	v_pk_fma_f32 v[114:115], v[70:71], v[110:111], v[114:115]
	v_cvt_pk_f32_fp8_e32 v[104:105], v50
	v_cvt_pk_f32_fp8_e32 v[108:109], v54
	v_cvt_pk_f32_fp8_sdwa v[106:107], v50 src0_sel:WORD_1
	v_cvt_pk_f32_fp8_sdwa v[110:111], v54 src0_sel:WORD_1
	v_pk_fma_f32 v[112:113], v[72:73], v[104:105], v[112:113]
	v_pk_fma_f32 v[114:115], v[72:73], v[108:109], v[114:115]
	v_pk_fma_f32 v[112:113], v[74:75], v[106:107], v[112:113]
	v_pk_fma_f32 v[114:115], v[74:75], v[110:111], v[114:115]
	v_cvt_pk_f32_fp8_e32 v[104:105], v51
	v_cvt_pk_f32_fp8_e32 v[108:109], v55
	v_cvt_pk_f32_fp8_sdwa v[106:107], v51 src0_sel:WORD_1
	v_cvt_pk_f32_fp8_sdwa v[110:111], v55 src0_sel:WORD_1
	v_pk_fma_f32 v[112:113], v[76:77], v[104:105], v[112:113]
	v_pk_fma_f32 v[114:115], v[76:77], v[108:109], v[114:115]
	s_waitcnt lgkmcnt(0)
	v_and_or_b32 v142, v142, s90, v240
	v_and_or_b32 v143, v143, s90, v240
	global_load_dwordx4 v[48:51], v142, s[80:81]
	global_load_dwordx4 v[52:55], v143, s[80:81]
	v_pk_fma_f32 v[112:113], v[78:79], v[106:107], v[112:113]
	v_pk_fma_f32 v[114:115], v[78:79], v[110:111], v[114:115]
	v_add_f32_e32 v100, v112, v113
	v_add_f32_e32 v101, v114, v115
	ds_bpermute_b32 v142, v255, v135
	ds_bpermute_b32 v143, v153, v135
	s_waitcnt vmcnt(16)
	v_cvt_pk_f32_fp8_e32 v[104:105], v56
	v_cvt_pk_f32_fp8_e32 v[108:109], v60
	v_cvt_pk_f32_fp8_sdwa v[106:107], v56 src0_sel:WORD_1
	v_cvt_pk_f32_fp8_sdwa v[110:111], v60 src0_sel:WORD_1
	v_pk_mul_f32 v[112:113], v[64:65], v[104:105]
	v_pk_mul_f32 v[114:115], v[64:65], v[108:109]
	v_pk_fma_f32 v[112:113], v[66:67], v[106:107], v[112:113]
	v_pk_fma_f32 v[114:115], v[66:67], v[110:111], v[114:115]
	v_cvt_pk_f32_fp8_e32 v[104:105], v57
	v_cvt_pk_f32_fp8_e32 v[108:109], v61
	v_cvt_pk_f32_fp8_sdwa v[106:107], v57 src0_sel:WORD_1
	v_cvt_pk_f32_fp8_sdwa v[110:111], v61 src0_sel:WORD_1
	v_pk_fma_f32 v[112:113], v[68:69], v[104:105], v[112:113]
	v_pk_fma_f32 v[114:115], v[68:69], v[108:109], v[114:115]
	v_pk_fma_f32 v[112:113], v[70:71], v[106:107], v[112:113]
	v_pk_fma_f32 v[114:115], v[70:71], v[110:111], v[114:115]
	v_cvt_pk_f32_fp8_e32 v[104:105], v58
	v_cvt_pk_f32_fp8_e32 v[108:109], v62
	v_cvt_pk_f32_fp8_sdwa v[106:107], v58 src0_sel:WORD_1
	v_cvt_pk_f32_fp8_sdwa v[110:111], v62 src0_sel:WORD_1
	v_pk_fma_f32 v[112:113], v[72:73], v[104:105], v[112:113]
	v_pk_fma_f32 v[114:115], v[72:73], v[108:109], v[114:115]
	v_pk_fma_f32 v[112:113], v[74:75], v[106:107], v[112:113]
	v_pk_fma_f32 v[114:115], v[74:75], v[110:111], v[114:115]
	v_cvt_pk_f32_fp8_e32 v[104:105], v59
	v_cvt_pk_f32_fp8_e32 v[108:109], v63
	v_cvt_pk_f32_fp8_sdwa v[106:107], v59 src0_sel:WORD_1
	v_cvt_pk_f32_fp8_sdwa v[110:111], v63 src0_sel:WORD_1
	v_pk_fma_f32 v[112:113], v[76:77], v[104:105], v[112:113]
	v_pk_fma_f32 v[114:115], v[76:77], v[108:109], v[114:115]
	s_waitcnt lgkmcnt(0)
; #define PG_ISSUE(BUF, TAB, e0_) do { const int isrc_ = ((e0_) < 64) ? myi0 : myi1; \
;       _Pragma("unroll") for (int e = 0; e < 8; ++e) { const int idx_ = __builtin_amdgcn_readlane(isrc_, ((e0_) + e) & 63); \
;         BUF[e] = *(const u32x4*)((TAB) + (size_t)idx_ * 1024 + lane * 16); } } while (0)
; DEV void peer_gather(const Params& P, int l, int m0, const int* idxs, const float* gs) {
;     ...
;     for (int e0 = 0; e0 < 128; e0 += 16) {
;       PG_ISSUE(b1, U, e0 + 8);
;       PG_U8(b0, 0, e0);
;       if (e0 + 16 < 128) PG_ISSUE(b0, U, e0 + 16); else PG_ISSUE(b0, V, 0);
;       PG_U8(b1, 0, e0 + 8);
;     }
	v_and_or_b32 v142, v142, s90, v240
	v_and_or_b32 v143, v143, s90, v240
	global_load_dwordx4 v[56:59], v142, s[80:81]
	global_load_dwordx4 v[60:63], v143, s[80:81]
	v_pk_fma_f32 v[112:113], v[78:79], v[106:107], v[112:113]
	v_pk_fma_f32 v[114:115], v[78:79], v[110:111], v[114:115]
	v_add_f32_e32 v102, v112, v113
	v_add_f32_e32 v103, v114, v115
	s_add_u32 s92, s100, 2
	s_min_u32 s92, s92, 127
	s_and_b32 s92, s92, 15
	s_lshl_b32 vcc_lo, s92, 9
	s_add_u32 vcc_lo, vcc_lo, s101
	v_add_u32_e32 v116, vcc_lo, v234
	ds_read_b32 v134, v116
	ds_read_b32 v135, v116 offset:256
	s_lshl_b32 vcc_lo, s98, 9
	s_add_u32 vcc_lo, vcc_lo, s101
	s_add_u32 vcc_lo, vcc_lo, 0x10000
	v_add_u32_e32 v117, vcc_lo, v234
	ds_read_b32 v136, v117
	ds_read_b32 v137, v117 offset:256
	s_mov_b32 s88, 0xf0f0f0f0
	s_mov_b32 s89, 0xf0f0f0f0
	v_cndmask_b32_e64 v144, v88, v92, s[88:89]
	v_cndmask_b32_e64 v92, v92, v88, s[88:89]
	v_cndmask_b32_e64 v145, v89, v93, s[88:89]
	v_cndmask_b32_e64 v93, v93, v89, s[88:89]
	v_cndmask_b32_e64 v146, v90, v94, s[88:89]
	v_cndmask_b32_e64 v94, v94, v90, s[88:89]
	v_cndmask_b32_e64 v147, v91, v95, s[88:89]
	v_cndmask_b32_e64 v95, v95, v91, s[88:89]
	v_add_f32_dpp v88, v92, v144 row_shl:4 row_mask:0xf bank_mask:0x5
	v_add_f32_dpp v89, v93, v145 row_shl:4 row_mask:0xf bank_mask:0x5
	v_add_f32_dpp v90, v94, v146 row_shl:4 row_mask:0xf bank_mask:0x5
	v_add_f32_dpp v91, v95, v147 row_shl:4 row_mask:0xf bank_mask:0x5
	v_add_f32_dpp v88, v92, v144 row_shr:4 row_mask:0xf bank_mask:0xa
	v_add_f32_dpp v89, v93, v145 row_shr:4 row_mask:0xf bank_mask:0xa
	v_add_f32_dpp v90, v94, v146 row_shr:4 row_mask:0xf bank_mask:0xa
	v_add_f32_dpp v91, v95, v147 row_shr:4 row_mask:0xf bank_mask:0xa
	v_cndmask_b32_e64 v144, v96, v100, s[88:89]
	v_cndmask_b32_e64 v100, v100, v96, s[88:89]
	v_cndmask_b32_e64 v145, v97, v101, s[88:89]
	v_cndmask_b32_e64 v101, v101, v97, s[88:89]
	v_cndmask_b32_e64 v146, v98, v102, s[88:89]
	v_cndmask_b32_e64 v102, v102, v98, s[88:89]
	v_cndmask_b32_e64 v147, v99, v103, s[88:89]
	v_cndmask_b32_e64 v103, v103, v99, s[88:89]
	v_add_f32_dpp v96, v100, v144 row_shl:4 row_mask:0xf bank_mask:0x5
	v_add_f32_dpp v97, v101, v145 row_shl:4 row_mask:0xf bank_mask:0x5
	v_add_f32_dpp v98, v102, v146 row_shl:4 row_mask:0xf bank_mask:0x5
	v_add_f32_dpp v99, v103, v147 row_shl:4 row_mask:0xf bank_mask:0x5
	v_add_f32_dpp v96, v100, v144 row_shr:4 row_mask:0xf bank_mask:0xa
	v_add_f32_dpp v97, v101, v145 row_shr:4 row_mask:0xf bank_mask:0xa
	v_add_f32_dpp v98, v102, v146 row_shr:4 row_mask:0xf bank_mask:0xa
	v_add_f32_dpp v99, v103, v147 row_shr:4 row_mask:0xf bank_mask:0xa
	s_mov_b32 s88, 0xcccccccc
	s_mov_b32 s89, 0xcccccccc
	v_cndmask_b32_e64 v144, v88, v90, s[88:89]
	v_cndmask_b32_e64 v90, v90, v88, s[88:89]
	v_cndmask_b32_e64 v145, v89, v91, s[88:89]
	v_cndmask_b32_e64 v91, v91, v89, s[88:89]
	v_cndmask_b32_e64 v146, v96, v98, s[88:89]
	v_cndmask_b32_e64 v98, v98, v96, s[88:89]
	v_cndmask_b32_e64 v147, v97, v99, s[88:89]
	v_cndmask_b32_e64 v99, v99, v97, s[88:89]
	v_add_f32_dpp v88, v90, v144 quad_perm:[2,3,0,1] row_mask:0xf bank_mask:0xf
	v_add_f32_dpp v89, v91, v145 quad_perm:[2,3,0,1] row_mask:0xf bank_mask:0xf
	v_add_f32_dpp v96, v98, v146 quad_perm:[2,3,0,1] row_mask:0xf bank_mask:0xf
	v_add_f32_dpp v97, v99, v147 quad_perm:[2,3,0,1] row_mask:0xf bank_mask:0xf
	s_mov_b32 s88, 0xaaaaaaaa
	s_mov_b32 s89, 0xaaaaaaaa
	v_cndmask_b32_e64 v144, v88, v89, s[88:89]
	v_cndmask_b32_e64 v89, v89, v88, s[88:89]
	v_cndmask_b32_e64 v145, v96, v97, s[88:89]
	v_cndmask_b32_e64 v97, v97, v96, s[88:89]
	s_nop 1
	v_add_f32_dpp v88, v89, v144 quad_perm:[1,0,3,2] row_mask:0xf bank_mask:0xf
	v_add_f32_dpp v96, v97, v145 quad_perm:[1,0,3,2] row_mask:0xf bank_mask:0xf
	s_nop 0
	ds_bpermute_b32 v144, v239, v88
	ds_bpermute_b32 v145, v239, v96
	s_waitcnt lgkmcnt(0)
	v_add_f32_e32 v136, v136, v144
	v_add_f32_e32 v137, v137, v145
	ds_write_b32 v117, v136
	ds_write_b32 v117, v137 offset:256
	s_add_u32 s100, s100, 1
	s_cmp_lt_u32 s100, 128
	s_cbranch_scc1 .Lpg0_uloop
	s_waitcnt vmcnt(0) lgkmcnt(0)
	s_mov_b32 s2, 0
.Lpg0_act:
	v_readlane_b32 s82, v231, 28
	v_readlane_b32 s83, v231, 29
	s_nop 4
	s_lshl_b32 s98, s2, 11
	s_add_u32 s98, s98, s101
	v_add_u32_e32 v116, s98, v234
	v_add_u32_e32 v117, 0x10000, v116
	ds_read_b32 v0, v116 offset:0
	ds_read_b32 v8, v117 offset:0
	ds_read_b32 v1, v116 offset:256
	ds_read_b32 v9, v117 offset:256
	ds_read_b32 v2, v116 offset:512
	ds_read_b32 v10, v117 offset:512
	ds_read_b32 v3, v116 offset:768
	ds_read_b32 v11, v117 offset:768
	ds_read_b32 v4, v116 offset:1024
	ds_read_b32 v12, v117 offset:1024
	ds_read_b32 v5, v116 offset:1280
	ds_read_b32 v13, v117 offset:1280
	ds_read_b32 v6, v116 offset:1536
	ds_read_b32 v14, v117 offset:1536
	ds_read_b32 v7, v116 offset:1792
	ds_read_b32 v15, v117 offset:1792
	s_waitcnt lgkmcnt(0)
	s_lshl_b32 s99, s2, 2
	s_add_u32 s99, s99, s33
	s_add_u32 s99, s99, 0
	s_lshl_b32 s99, s99, 9
	v_and_b32_e32 v0, 0x7f, v0
	v_lshl_add_u32 v0, v0, 2, s99
	global_load_dword v16, v0, s[82:83]
	v_and_b32_e32 v1, 0x7f, v1
	v_lshl_add_u32 v1, v1, 2, s99
	global_load_dword v17, v1, s[82:83]
	s_lshl_b32 s99, s2, 2
	s_add_u32 s99, s99, s33
	s_add_u32 s99, s99, 1
	s_lshl_b32 s99, s99, 9
	v_and_b32_e32 v2, 0x7f, v2
	v_lshl_add_u32 v2, v2, 2, s99
	global_load_dword v18, v2, s[82:83]
	v_and_b32_e32 v3, 0x7f, v3
	v_lshl_add_u32 v3, v3, 2, s99
	global_load_dword v19, v3, s[82:83]
	s_lshl_b32 s99, s2, 2
	s_add_u32 s99, s99, s33
	s_add_u32 s99, s99, 2
	s_lshl_b32 s99, s99, 9
	v_and_b32_e32 v4, 0x7f, v4
	v_lshl_add_u32 v4, v4, 2, s99
	global_load_dword v20, v4, s[82:83]
	v_and_b32_e32 v5, 0x7f, v5
	v_lshl_add_u32 v5, v5, 2, s99
	global_load_dword v21, v5, s[82:83]
	s_lshl_b32 s99, s2, 2
	s_add_u32 s99, s99, s33
	s_add_u32 s99, s99, 3
	s_lshl_b32 s99, s99, 9
	v_and_b32_e32 v6, 0x7f, v6
	v_lshl_add_u32 v6, v6, 2, s99
	global_load_dword v22, v6, s[82:83]
	v_and_b32_e32 v7, 0x7f, v7
	v_lshl_add_u32 v7, v7, 2, s99
	global_load_dword v23, v7, s[82:83]
	v_mul_f32_e32 v8, 0x3c800000, v8
	v_mul_f32_e32 v9, 0x3c800000, v9
	v_mul_f32_e32 v10, 0x3c800000, v10
	v_mul_f32_e32 v11, 0x3c800000, v11
	v_mul_f32_e32 v12, 0x3c800000, v12
	v_mul_f32_e32 v13, 0x3c800000, v13
	v_mul_f32_e32 v14, 0x3c800000, v14
	v_mul_f32_e32 v15, 0x3c800000, v15
	v_mul_f32_e32 v24, 0x3d372713, v8
	v_mul_f32_e32 v25, 0x3d372713, v9
	v_mul_f32_e32 v26, 0x3d372713, v10
	v_mul_f32_e32 v27, 0x3d372713, v11
	v_mul_f32_e32 v28, 0x3d372713, v12
	v_mul_f32_e32 v29, 0x3d372713, v13
	v_mul_f32_e32 v30, 0x3d372713, v14
	v_mul_f32_e32 v31, 0x3d372713, v15
	v_mul_f32_e32 v24, v8, v24
	v_mul_f32_e32 v25, v9, v25
	v_mul_f32_e32 v26, v10, v26
	v_mul_f32_e32 v27, v11, v27
	v_mul_f32_e32 v28, v12, v28
	v_mul_f32_e32 v29, v13, v29
	v_mul_f32_e32 v30, v14, v30
	v_mul_f32_e32 v31, v15, v31
	v_fma_f32 v24, v8, v24, v8
	v_fma_f32 v25, v9, v25, v9
	v_fma_f32 v26, v10, v26, v10
	v_fma_f32 v27, v11, v27, v11
	v_fma_f32 v28, v12, v28, v12
	v_fma_f32 v29, v13, v29, v13
	v_fma_f32 v30, v14, v30, v14
	v_fma_f32 v31, v15, v31, v15
	v_mul_f32_e32 v24, 0xbfcc422a, v24
	v_mul_f32_e32 v25, 0xbfcc422a, v25
	v_mul_f32_e32 v26, 0xbfcc422a, v26
	v_mul_f32_e32 v27, 0xbfcc422a, v27
	v_mul_f32_e32 v28, 0xbfcc422a, v28
	v_mul_f32_e32 v29, 0xbfcc422a, v29
	v_mul_f32_e32 v30, 0xbfcc422a, v30
	v_mul_f32_e32 v31, 0xbfcc422a, v31
	v_mul_f32_e32 v24, 0x3fb8aa3b, v24
	v_mul_f32_e32 v25, 0x3fb8aa3b, v25
	v_mul_f32_e32 v26, 0x3fb8aa3b, v26
	v_mul_f32_e32 v27, 0x3fb8aa3b, v27
	v_mul_f32_e32 v28, 0x3fb8aa3b, v28
	v_mul_f32_e32 v29, 0x3fb8aa3b, v29
	v_mul_f32_e32 v30, 0x3fb8aa3b, v30
	v_mul_f32_e32 v31, 0x3fb8aa3b, v31
	v_exp_f32_e32 v24, v24
	v_exp_f32_e32 v25, v25
	v_exp_f32_e32 v26, v26
	v_exp_f32_e32 v27, v27
	v_exp_f32_e32 v28, v28
	v_exp_f32_e32 v29, v29
	v_exp_f32_e32 v30, v30
	v_exp_f32_e32 v31, v31
	s_nop 0
	v_add_f32_e32 v24, 1.0, v24
	v_add_f32_e32 v25, 1.0, v25
	v_add_f32_e32 v26, 1.0, v26
	v_add_f32_e32 v27, 1.0, v27
	v_add_f32_e32 v28, 1.0, v28
	v_add_f32_e32 v29, 1.0, v29
	v_add_f32_e32 v30, 1.0, v30
	v_add_f32_e32 v31, 1.0, v31
	v_rcp_f32_e32 v24, v24
	v_rcp_f32_e32 v25, v25
	v_rcp_f32_e32 v26, v26
	v_rcp_f32_e32 v27, v27
	v_rcp_f32_e32 v28, v28
	v_rcp_f32_e32 v29, v29
	v_rcp_f32_e32 v30, v30
	v_rcp_f32_e32 v31, v31
	s_nop 0
	v_mul_f32_e32 v24, v8, v24
	v_mul_f32_e32 v25, v9, v25
	v_mul_f32_e32 v26, v10, v26
	v_mul_f32_e32 v27, v11, v27
	v_mul_f32_e32 v28, v12, v28
	v_mul_f32_e32 v29, v13, v29
	v_mul_f32_e32 v30, v14, v30
	v_mul_f32_e32 v31, v15, v31
	s_waitcnt vmcnt(0)
	v_mul_f32_e32 v24, v24, v16
	ds_write_b32 v117, v24 offset:0
	v_mul_f32_e32 v25, v25, v17
	ds_write_b32 v117, v25 offset:256
	v_mul_f32_e32 v26, v26, v18
	ds_write_b32 v117, v26 offset:512
	v_mul_f32_e32 v27, v27, v19
	ds_write_b32 v117, v27 offset:768
	v_mul_f32_e32 v28, v28, v20
	ds_write_b32 v117, v28 offset:1024
	v_mul_f32_e32 v29, v29, v21
	ds_write_b32 v117, v29 offset:1280
	v_mul_f32_e32 v30, v30, v22
	ds_write_b32 v117, v30 offset:1536
	v_mul_f32_e32 v31, v31, v23
	ds_write_b32 v117, v31 offset:1792
	s_add_u32 s2, s2, 1
	s_cmp_lt_u32 s2, 4
	s_cbranch_scc1 .Lpg0_act
	s_waitcnt lgkmcnt(0)
	v_readfirstlane_b32 s80, v126
	v_readfirstlane_b32 s81, v127
	s_nop 4
	s_waitcnt vmcnt(0) lgkmcnt(0)
	s_barrier
	v_readfirstlane_b32 s98, v176
	s_cmp_lt_u32 s98, 64
	s_cbranch_scc0 .Lpg0_sk2
	v_readfirstlane_b32 s82, v122
	v_readfirstlane_b32 s83, v123
	s_nop 4
	s_add_u32 s82, s82, 0x123800
	s_addc_u32 s83, s83, 0
	s_getreg_b32 s99, hwreg(HW_REG_XCC_ID, 0, 4)
	s_lshl_b32 s99, s99, 6
	v_mov_b32_e32 v144, s99
	v_mov_b32_e32 v145, 1
	v_mov_b32_e32 v146, 0x27fc0
	s_mov_b64 exec, 1
	ds_read_b32 v147, v146
	global_atomic_add v144, v145, s[82:83]
	s_waitcnt lgkmcnt(0)
	v_readfirstlane_b32 s92, v147
	s_mul_i32 s92, s92, 2
	s_mov_b32 s93, 0

; #define PG_ISSUE(BUF, TAB, e0_) do { const int isrc_ = ((e0_) < 64) ? myi0 : myi1; \
;       _Pragma("unroll") for (int e = 0; e < 8; ++e) { const int idx_ = __builtin_amdgcn_readlane(isrc_, ((e0_) + e) & 63); \
;         BUF[e] = *(const u32x4*)((TAB) + (size_t)idx_ * 1024 + lane * 16); } } while (0)
; DEV void peer_gather(const Params& P, int l, int m0, const int* idxs, const float* gs) {
;     ...
;     for (int e0 = 0; e0 < 128; e0 += 16) {
;       PG_ISSUE(b1, V, e0 + 8);
;       if (e0 == 64 && i + 1 < 16) sort_lists(lane, ni0, ni1, ng0, ng1);
;       PG_V16(b0, e0);
;       if (e0 + 16 < 128) PG_ISSUE(b0, V, e0 + 16);
;       PG_V16(b1, e0 + 8);
;     }
.Lpg0_sk2:
	s_barrier
	s_mov_b32 s90, 0xfffffc00
	s_mov_b32 s100, 0
	s_mov_b32 s98, 0
	s_mov_b32 s99, 0
	s_lshl_b32 vcc_lo, s98, 9
	s_add_u32 vcc_lo, vcc_lo, s101
	v_add_u32_e32 v116, vcc_lo, v234
	ds_read_b32 v134, v116
	ds_read_b32 v135, v116 offset:256
	s_lshl_b32 vcc_lo, s99, 7
	v_add_u32_e32 v240, vcc_lo, v235
	s_waitcnt lgkmcnt(0)
	ds_bpermute_b32 v142, v249, v134
	ds_bpermute_b32 v143, v250, v134
	s_waitcnt lgkmcnt(0)
	v_and_or_b32 v142, v142, s90, v240
	v_and_or_b32 v143, v143, s90, v240
	global_load_dwordx4 v[0:3], v142, s[80:81]
	global_load_dwordx4 v[4:7], v143, s[80:81]
	ds_bpermute_b32 v142, v251, v134
	ds_bpermute_b32 v143, v252, v134
	s_waitcnt lgkmcnt(0)
	v_and_or_b32 v142, v142, s90, v240
	v_and_or_b32 v143, v143, s90, v240
	global_load_dwordx4 v[8:11], v142, s[80:81]
	global_load_dwordx4 v[12:15], v143, s[80:81]
	ds_bpermute_b32 v142, v253, v134
	ds_bpermute_b32 v143, v254, v134
	s_waitcnt lgkmcnt(0)
	v_and_or_b32 v142, v142, s90, v240
	v_and_or_b32 v143, v143, s90, v240
	global_load_dwordx4 v[16:19], v142, s[80:81]
	global_load_dwordx4 v[20:23], v143, s[80:81]
	ds_bpermute_b32 v142, v255, v134
	ds_bpermute_b32 v143, v153, v134
	s_waitcnt lgkmcnt(0)
	v_and_or_b32 v142, v142, s90, v240
	v_and_or_b32 v143, v143, s90, v240
	global_load_dwordx4 v[24:27], v142, s[80:81]
	global_load_dwordx4 v[28:31], v143, s[80:81]
	ds_bpermute_b32 v142, v249, v135
	ds_bpermute_b32 v143, v250, v135
	s_waitcnt lgkmcnt(0)
	v_and_or_b32 v142, v142, s90, v240
	v_and_or_b32 v143, v143, s90, v240
	global_load_dwordx4 v[32:35], v142, s[80:81]
	global_load_dwordx4 v[36:39], v143, s[80:81]
	ds_bpermute_b32 v142, v251, v135
	ds_bpermute_b32 v143, v252, v135
	s_waitcnt lgkmcnt(0)
	v_and_or_b32 v142, v142, s90, v240
	v_and_or_b32 v143, v143, s90, v240
	global_load_dwordx4 v[40:43], v142, s[80:81]
	global_load_dwordx4 v[44:47], v143, s[80:81]
	ds_bpermute_b32 v142, v253, v135
	ds_bpermute_b32 v143, v254, v135
	s_waitcnt lgkmcnt(0)
	v_and_or_b32 v142, v142, s90, v240
	v_and_or_b32 v143, v143, s90, v240
	global_load_dwordx4 v[48:51], v142, s[80:81]
	global_load_dwordx4 v[52:55], v143, s[80:81]
	ds_bpermute_b32 v142, v255, v135
	ds_bpermute_b32 v143, v153, v135
	s_waitcnt lgkmcnt(0)
	v_and_or_b32 v142, v142, s90, v240
	v_and_or_b32 v143, v143, s90, v240
	global_load_dwordx4 v[56:59], v142, s[80:81]
	global_load_dwordx4 v[60:63], v143, s[80:81]
	s_mov_b32 s92, 1
	s_lshl_b32 vcc_lo, s92, 9
	s_add_u32 vcc_lo, vcc_lo, s101
	v_add_u32_e32 v116, vcc_lo, v234
	ds_read_b32 v134, v116
	ds_read_b32 v135, v116 offset:256
	s_lshl_b32 vcc_lo, s98, 9
	s_add_u32 vcc_lo, vcc_lo, s101
	s_add_u32 vcc_lo, vcc_lo, 0x10000
	v_add_u32_e32 v117, vcc_lo, v234
	ds_read_b32 v136, v117
	ds_read_b32 v137, v117 offset:256
	s_waitcnt vmcnt(0)
.Lpg0_vloop:
	s_and_b32 s98, s100, 15
	s_lshr_b32 s99, s100, 4
	s_add_u32 s92, s100, 1
	s_min_u32 s92, s92, 127
	s_lshr_b32 s93, s92, 4
	s_and_b32 s92, s92, 15
	v_readfirstlane_b32 s82, v132
	v_readfirstlane_b32 s83, v133
	s_nop 4
	s_add_u32 vcc_lo, s3, s98
	s_lshl_b32 vcc_lo, vcc_lo, 12
	s_lshl_b32 vcc_hi, s99, 9
	s_add_u32 vcc_lo, vcc_lo, vcc_hi
	v_add_u32_e32 v119, vcc_lo, v238
	global_load_dword v80, v119, s[82:83]
	global_load_dword v81, v119, s[82:83] offset:32
	s_lshl_b32 vcc_lo, s93, 7
	v_add_u32_e32 v240, vcc_lo, v235
	s_waitcnt lgkmcnt(0)
	ds_bpermute_b32 v138, v249, v136
	ds_bpermute_b32 v140, v250, v136
	v_mov_b32_e32 v64, 0
	v_mov_b32_e32 v65, 0
	v_mov_b32_e32 v66, 0
	v_mov_b32_e32 v67, 0
	v_mov_b32_e32 v68, 0
	v_mov_b32_e32 v69, 0
	v_mov_b32_e32 v70, 0
	v_mov_b32_e32 v71, 0
	v_mov_b32_e32 v72, 0
	v_mov_b32_e32 v73, 0
	v_mov_b32_e32 v74, 0
	v_mov_b32_e32 v75, 0
	v_mov_b32_e32 v76, 0
	v_mov_b32_e32 v77, 0
	v_mov_b32_e32 v78, 0
	v_mov_b32_e32 v79, 0
	ds_bpermute_b32 v142, v249, v134
	ds_bpermute_b32 v143, v250, v134
	ds_bpermute_b32 v144, v251, v136
	ds_bpermute_b32 v146, v252, v136
	s_waitcnt vmcnt(18) lgkmcnt(4)
	v_cvt_pk_f32_fp8_e32 v[104:105], v0
	v_cvt_pk_f32_fp8_e32 v[108:109], v4
	v_cvt_pk_f32_fp8_sdwa v[106:107], v0 src0_sel:WORD_1
	v_cvt_pk_f32_fp8_sdwa v[110:111], v4 src0_sel:WORD_1
	v_pk_fma_f32 v[64:65], v[104:105], v[138:139], v[64:65] op_sel_hi:[1,0,1]
	v_pk_fma_f32 v[66:67], v[106:107], v[138:139], v[66:67] op_sel_hi:[1,0,1]
	v_pk_fma_f32 v[64:65], v[108:109], v[140:141], v[64:65] op_sel_hi:[1,0,1]
	v_pk_fma_f32 v[66:67], v[110:111], v[140:141], v[66:67] op_sel_hi:[1,0,1]
	v_cvt_pk_f32_fp8_e32 v[104:105], v1
	v_cvt_pk_f32_fp8_e32 v[108:109], v5
	v_cvt_pk_f32_fp8_sdwa v[106:107], v1 src0_sel:WORD_1
	v_cvt_pk_f32_fp8_sdwa v[110:111], v5 src0_sel:WORD_1
	v_pk_fma_f32 v[68:69], v[104:105], v[138:139], v[68:69] op_sel_hi:[1,0,1]
	v_pk_fma_f32 v[70:71], v[106:107], v[138:139], v[70:71] op_sel_hi:[1,0,1]
	v_pk_fma_f32 v[68:69], v[108:109], v[140:141], v[68:69] op_sel_hi:[1,0,1]
	v_pk_fma_f32 v[70:71], v[110:111], v[140:141], v[70:71] op_sel_hi:[1,0,1]
	v_cvt_pk_f32_fp8_e32 v[104:105], v2
	v_cvt_pk_f32_fp8_e32 v[108:109], v6
	v_cvt_pk_f32_fp8_sdwa v[106:107], v2 src0_sel:WORD_1
	v_cvt_pk_f32_fp8_sdwa v[110:111], v6 src0_sel:WORD_1
	v_pk_fma_f32 v[72:73], v[104:105], v[138:139], v[72:73] op_sel_hi:[1,0,1]
	v_pk_fma_f32 v[74:75], v[106:107], v[138:139], v[74:75] op_sel_hi:[1,0,1]
	v_pk_fma_f32 v[72:73], v[108:109], v[140:141], v[72:73] op_sel_hi:[1,0,1]
	v_pk_fma_f32 v[74:75], v[110:111], v[140:141], v[74:75] op_sel_hi:[1,0,1]
	v_cvt_pk_f32_fp8_e32 v[104:105], v3
	v_cvt_pk_f32_fp8_e32 v[108:109], v7
	v_cvt_pk_f32_fp8_sdwa v[106:107], v3 src0_sel:WORD_1
	v_cvt_pk_f32_fp8_sdwa v[110:111], v7 src0_sel:WORD_1
	v_pk_fma_f32 v[76:77], v[104:105], v[138:139], v[76:77] op_sel_hi:[1,0,1]
	v_pk_fma_f32 v[78:79], v[106:107], v[138:139], v[78:79] op_sel_hi:[1,0,1]
	s_waitcnt lgkmcnt(0)
	v_and_or_b32 v142, v142, s90, v240
	v_and_or_b32 v143, v143, s90, v240
	global_load_dwordx4 v[0:3], v142, s[80:81]
	global_load_dwordx4 v[4:7], v143, s[80:81]
	v_pk_fma_f32 v[76:77], v[108:109], v[140:141], v[76:77] op_sel_hi:[1,0,1]
	v_pk_fma_f32 v[78:79], v[110:111], v[140:141], v[78:79] op_sel_hi:[1,0,1]
	ds_bpermute_b32 v142, v251, v134
	ds_bpermute_b32 v143, v252, v134
	ds_bpermute_b32 v138, v253, v136
	ds_bpermute_b32 v140, v254, v136
	s_waitcnt vmcnt(18) lgkmcnt(4)
	v_cvt_pk_f32_fp8_e32 v[104:105], v8
	v_cvt_pk_f32_fp8_e32 v[108:109], v12
	v_cvt_pk_f32_fp8_sdwa v[106:107], v8 src0_sel:WORD_1
	v_cvt_pk_f32_fp8_sdwa v[110:111], v12 src0_sel:WORD_1
	v_pk_fma_f32 v[64:65], v[104:105], v[144:145], v[64:65] op_sel_hi:[1,0,1]
	v_pk_fma_f32 v[66:67], v[106:107], v[144:145], v[66:67] op_sel_hi:[1,0,1]
	v_pk_fma_f32 v[64:65], v[108:109], v[146:147], v[64:65] op_sel_hi:[1,0,1]
	v_pk_fma_f32 v[66:67], v[110:111], v[146:147], v[66:67] op_sel_hi:[1,0,1]
	v_cvt_pk_f32_fp8_e32 v[104:105], v9
	v_cvt_pk_f32_fp8_e32 v[108:109], v13
	v_cvt_pk_f32_fp8_sdwa v[106:107], v9 src0_sel:WORD_1
	v_cvt_pk_f32_fp8_sdwa v[110:111], v13 src0_sel:WORD_1
	v_pk_fma_f32 v[68:69], v[104:105], v[144:145], v[68:69] op_sel_hi:[1,0,1]
	v_pk_fma_f32 v[70:71], v[106:107], v[144:145], v[70:71] op_sel_hi:[1,0,1]
	v_pk_fma_f32 v[68:69], v[108:109], v[146:147], v[68:69] op_sel_hi:[1,0,1]
	v_pk_fma_f32 v[70:71], v[110:111], v[146:147], v[70:71] op_sel_hi:[1,0,1]
	v_cvt_pk_f32_fp8_e32 v[104:105], v10
	v_cvt_pk_f32_fp8_e32 v[108:109], v14
	v_cvt_pk_f32_fp8_sdwa v[106:107], v10 src0_sel:WORD_1
	v_cvt_pk_f32_fp8_sdwa v[110:111], v14 src0_sel:WORD_1
	v_pk_fma_f32 v[72:73], v[104:105], v[144:145], v[72:73] op_sel_hi:[1,0,1]
	v_pk_fma_f32 v[74:75], v[106:107], v[144:145], v[74:75] op_sel_hi:[1,0,1]
	v_pk_fma_f32 v[72:73], v[108:109], v[146:147], v[72:73] op_sel_hi:[1,0,1]
	v_pk_fma_f32 v[74:75], v[110:111], v[146:147], v[74:75] op_sel_hi:[1,0,1]
	v_cvt_pk_f32_fp8_e32 v[104:105], v11
	v_cvt_pk_f32_fp8_e32 v[108:109], v15
	v_cvt_pk_f32_fp8_sdwa v[106:107], v11 src0_sel:WORD_1
	v_cvt_pk_f32_fp8_sdwa v[110:111], v15 src0_sel:WORD_1
	v_pk_fma_f32 v[76:77], v[104:105], v[144:145], v[76:77] op_sel_hi:[1,0,1]
	v_pk_fma_f32 v[78:79], v[106:107], v[144:145], v[78:79] op_sel_hi:[1,0,1]
	s_waitcnt lgkmcnt(0)
	v_and_or_b32 v142, v142, s90, v240
	v_and_or_b32 v143, v143, s90, v240
	global_load_dwordx4 v[8:11], v142, s[80:81]
	global_load_dwordx4 v[12:15], v143, s[80:81]
	v_pk_fma_f32 v[76:77], v[108:109], v[146:147], v[76:77] op_sel_hi:[1,0,1]
	v_pk_fma_f32 v[78:79], v[110:111], v[146:147], v[78:79] op_sel_hi:[1,0,1]
	ds_bpermute_b32 v142, v253, v134
	ds_bpermute_b32 v143, v254, v134
	ds_bpermute_b32 v144, v255, v136
	ds_bpermute_b32 v146, v153, v136
	s_waitcnt vmcnt(18) lgkmcnt(4)
	v_cvt_pk_f32_fp8_e32 v[104:105], v16
	v_cvt_pk_f32_fp8_e32 v[108:109], v20
	v_cvt_pk_f32_fp8_sdwa v[106:107], v16 src0_sel:WORD_1
	v_cvt_pk_f32_fp8_sdwa v[110:111], v20 src0_sel:WORD_1
	v_pk_fma_f32 v[64:65], v[104:105], v[138:139], v[64:65] op_sel_hi:[1,0,1]
	v_pk_fma_f32 v[66:67], v[106:107], v[138:139], v[66:67] op_sel_hi:[1,0,1]
	v_pk_fma_f32 v[64:65], v[108:109], v[140:141], v[64:65] op_sel_hi:[1,0,1]
	v_pk_fma_f32 v[66:67], v[110:111], v[140:141], v[66:67] op_sel_hi:[1,0,1]
	v_cvt_pk_f32_fp8_e32 v[104:105], v17
	v_cvt_pk_f32_fp8_e32 v[108:109], v21
	v_cvt_pk_f32_fp8_sdwa v[106:107], v17 src0_sel:WORD_1
	v_cvt_pk_f32_fp8_sdwa v[110:111], v21 src0_sel:WORD_1
	v_pk_fma_f32 v[68:69], v[104:105], v[138:139], v[68:69] op_sel_hi:[1,0,1]
	v_pk_fma_f32 v[70:71], v[106:107], v[138:139], v[70:71] op_sel_hi:[1,0,1]
	v_pk_fma_f32 v[68:69], v[108:109], v[140:141], v[68:69] op_sel_hi:[1,0,1]
	v_pk_fma_f32 v[70:71], v[110:111], v[140:141], v[70:71] op_sel_hi:[1,0,1]
	v_cvt_pk_f32_fp8_e32 v[104:105], v18
	v_cvt_pk_f32_fp8_e32 v[108:109], v22
	v_cvt_pk_f32_fp8_sdwa v[106:107], v18 src0_sel:WORD_1
	v_cvt_pk_f32_fp8_sdwa v[110:111], v22 src0_sel:WORD_1
	v_pk_fma_f32 v[72:73], v[104:105], v[138:139], v[72:73] op_sel_hi:[1,0,1]
	v_pk_fma_f32 v[74:75], v[106:107], v[138:139], v[74:75] op_sel_hi:[1,0,1]
	v_pk_fma_f32 v[72:73], v[108:109], v[140:141], v[72:73] op_sel_hi:[1,0,1]
	v_pk_fma_f32 v[74:75], v[110:111], v[140:141], v[74:75] op_sel_hi:[1,0,1]
	v_cvt_pk_f32_fp8_e32 v[104:105], v19
	v_cvt_pk_f32_fp8_e32 v[108:109], v23
	v_cvt_pk_f32_fp8_sdwa v[106:107], v19 src0_sel:WORD_1
	v_cvt_pk_f32_fp8_sdwa v[110:111], v23 src0_sel:WORD_1
	v_pk_fma_f32 v[76:77], v[104:105], v[138:139], v[76:77] op_sel_hi:[1,0,1]
	v_pk_fma_f32 v[78:79], v[106:107], v[138:139], v[78:79] op_sel_hi:[1,0,1]
	s_waitcnt lgkmcnt(0)
	v_and_or_b32 v142, v142, s90, v240
	v_and_or_b32 v143, v143, s90, v240
	global_load_dwordx4 v[16:19], v142, s[80:81]
	global_load_dwordx4 v[20:23], v143, s[80:81]
	v_pk_fma_f32 v[76:77], v[108:109], v[140:141], v[76:77] op_sel_hi:[1,0,1]
	v_pk_fma_f32 v[78:79], v[110:111], v[140:141], v[78:79] op_sel_hi:[1,0,1]
	ds_bpermute_b32 v142, v255, v134
	ds_bpermute_b32 v143, v153, v134
	ds_bpermute_b32 v138, v249, v137
	ds_bpermute_b32 v140, v250, v137
	s_waitcnt vmcnt(18) lgkmcnt(4)
	v_cvt_pk_f32_fp8_e32 v[104:105], v24
	v_cvt_pk_f32_fp8_e32 v[108:109], v28
	v_cvt_pk_f32_fp8_sdwa v[106:107], v24 src0_sel:WORD_1
	v_cvt_pk_f32_fp8_sdwa v[110:111], v28 src0_sel:WORD_1
	v_pk_fma_f32 v[64:65], v[104:105], v[144:145], v[64:65] op_sel_hi:[1,0,1]
	v_pk_fma_f32 v[66:67], v[106:107], v[144:145], v[66:67] op_sel_hi:[1,0,1]
	v_pk_fma_f32 v[64:65], v[108:109], v[146:147], v[64:65] op_sel_hi:[1,0,1]
	v_pk_fma_f32 v[66:67], v[110:111], v[146:147], v[66:67] op_sel_hi:[1,0,1]
	v_cvt_pk_f32_fp8_e32 v[104:105], v25
	v_cvt_pk_f32_fp8_e32 v[108:109], v29
	v_cvt_pk_f32_fp8_sdwa v[106:107], v25 src0_sel:WORD_1
	v_cvt_pk_f32_fp8_sdwa v[110:111], v29 src0_sel:WORD_1
	v_pk_fma_f32 v[68:69], v[104:105], v[144:145], v[68:69] op_sel_hi:[1,0,1]
	v_pk_fma_f32 v[70:71], v[106:107], v[144:145], v[70:71] op_sel_hi:[1,0,1]
	v_pk_fma_f32 v[68:69], v[108:109], v[146:147], v[68:69] op_sel_hi:[1,0,1]
	v_pk_fma_f32 v[70:71], v[110:111], v[146:147], v[70:71] op_sel_hi:[1,0,1]
	v_cvt_pk_f32_fp8_e32 v[104:105], v26
	v_cvt_pk_f32_fp8_e32 v[108:109], v30
	v_cvt_pk_f32_fp8_sdwa v[106:107], v26 src0_sel:WORD_1
	v_cvt_pk_f32_fp8_sdwa v[110:111], v30 src0_sel:WORD_1
	v_pk_fma_f32 v[72:73], v[104:105], v[144:145], v[72:73] op_sel_hi:[1,0,1]
	v_pk_fma_f32 v[74:75], v[106:107], v[144:145], v[74:75] op_sel_hi:[1,0,1]
	v_pk_fma_f32 v[72:73], v[108:109], v[146:147], v[72:73] op_sel_hi:[1,0,1]
	v_pk_fma_f32 v[74:75], v[110:111], v[146:147], v[74:75] op_sel_hi:[1,0,1]
	v_cvt_pk_f32_fp8_e32 v[104:105], v27
	v_cvt_pk_f32_fp8_e32 v[108:109], v31
	v_cvt_pk_f32_fp8_sdwa v[106:107], v27 src0_sel:WORD_1
	v_cvt_pk_f32_fp8_sdwa v[110:111], v31 src0_sel:WORD_1
	v_pk_fma_f32 v[76:77], v[104:105], v[144:145], v[76:77] op_sel_hi:[1,0,1]
	v_pk_fma_f32 v[78:79], v[106:107], v[144:145], v[78:79] op_sel_hi:[1,0,1]
	s_waitcnt lgkmcnt(0)
	v_and_or_b32 v142, v142, s90, v240
	v_and_or_b32 v143, v143, s90, v240
	global_load_dwordx4 v[24:27], v142, s[80:81]
	global_load_dwordx4 v[28:31], v143, s[80:81]
	v_pk_fma_f32 v[76:77], v[108:109], v[146:147], v[76:77] op_sel_hi:[1,0,1]
	v_pk_fma_f32 v[78:79], v[110:111], v[146:147], v[78:79] op_sel_hi:[1,0,1]
	ds_bpermute_b32 v142, v249, v135
	ds_bpermute_b32 v143, v250, v135
	ds_bpermute_b32 v144, v251, v137
	ds_bpermute_b32 v146, v252, v137
	s_waitcnt vmcnt(18) lgkmcnt(4)
	v_cvt_pk_f32_fp8_e32 v[104:105], v32
	v_cvt_pk_f32_fp8_e32 v[108:109], v36
	v_cvt_pk_f32_fp8_sdwa v[106:107], v32 src0_sel:WORD_1
	v_cvt_pk_f32_fp8_sdwa v[110:111], v36 src0_sel:WORD_1
	v_pk_fma_f32 v[64:65], v[104:105], v[138:139], v[64:65] op_sel_hi:[1,0,1]
	v_pk_fma_f32 v[66:67], v[106:107], v[138:139], v[66:67] op_sel_hi:[1,0,1]
	v_pk_fma_f32 v[64:65], v[108:109], v[140:141], v[64:65] op_sel_hi:[1,0,1]
	v_pk_fma_f32 v[66:67], v[110:111], v[140:141], v[66:67] op_sel_hi:[1,0,1]
	v_cvt_pk_f32_fp8_e32 v[104:105], v33
	v_cvt_pk_f32_fp8_e32 v[108:109], v37
	v_cvt_pk_f32_fp8_sdwa v[106:107], v33 src0_sel:WORD_1
	v_cvt_pk_f32_fp8_sdwa v[110:111], v37 src0_sel:WORD_1
	v_pk_fma_f32 v[68:69], v[104:105], v[138:139], v[68:69] op_sel_hi:[1,0,1]
	v_pk_fma_f32 v[70:71], v[106:107], v[138:139], v[70:71] op_sel_hi:[1,0,1]
	v_pk_fma_f32 v[68:69], v[108:109], v[140:141], v[68:69] op_sel_hi:[1,0,1]
	v_pk_fma_f32 v[70:71], v[110:111], v[140:141], v[70:71] op_sel_hi:[1,0,1]
	v_cvt_pk_f32_fp8_e32 v[104:105], v34
	v_cvt_pk_f32_fp8_e32 v[108:109], v38
	v_cvt_pk_f32_fp8_sdwa v[106:107], v34 src0_sel:WORD_1
	v_cvt_pk_f32_fp8_sdwa v[110:111], v38 src0_sel:WORD_1
	v_pk_fma_f32 v[72:73], v[104:105], v[138:139], v[72:73] op_sel_hi:[1,0,1]
	v_pk_fma_f32 v[74:75], v[106:107], v[138:139], v[74:75] op_sel_hi:[1,0,1]
	v_pk_fma_f32 v[72:73], v[108:109], v[140:141], v[72:73] op_sel_hi:[1,0,1]
	v_pk_fma_f32 v[74:75], v[110:111], v[140:141], v[74:75] op_sel_hi:[1,0,1]
	v_cvt_pk_f32_fp8_e32 v[104:105], v35
	v_cvt_pk_f32_fp8_e32 v[108:109], v39
	v_cvt_pk_f32_fp8_sdwa v[106:107], v35 src0_sel:WORD_1
	v_cvt_pk_f32_fp8_sdwa v[110:111], v39 src0_sel:WORD_1
	v_pk_fma_f32 v[76:77], v[104:105], v[138:139], v[76:77] op_sel_hi:[1,0,1]
	v_pk_fma_f32 v[78:79], v[106:107], v[138:139], v[78:79] op_sel_hi:[1,0,1]
	s_waitcnt lgkmcnt(0)
	v_and_or_b32 v142, v142, s90, v240
	v_and_or_b32 v143, v143, s90, v240
	global_load_dwordx4 v[32:35], v142, s[80:81]
	global_load_dwordx4 v[36:39], v143, s[80:81]
	v_pk_fma_f32 v[76:77], v[108:109], v[140:141], v[76:77] op_sel_hi:[1,0,1]
	v_pk_fma_f32 v[78:79], v[110:111], v[140:141], v[78:79] op_sel_hi:[1,0,1]
	ds_bpermute_b32 v142, v251, v135
	ds_bpermute_b32 v143, v252, v135
	ds_bpermute_b32 v138, v253, v137
	ds_bpermute_b32 v140, v254, v137
	s_waitcnt vmcnt(18) lgkmcnt(4)
	v_cvt_pk_f32_fp8_e32 v[104:105], v40
	v_cvt_pk_f32_fp8_e32 v[108:109], v44
	v_cvt_pk_f32_fp8_sdwa v[106:107], v40 src0_sel:WORD_1
	v_cvt_pk_f32_fp8_sdwa v[110:111], v44 src0_sel:WORD_1
	v_pk_fma_f32 v[64:65], v[104:105], v[144:145], v[64:65] op_sel_hi:[1,0,1]
	v_pk_fma_f32 v[66:67], v[106:107], v[144:145], v[66:67] op_sel_hi:[1,0,1]
	v_pk_fma_f32 v[64:65], v[108:109], v[146:147], v[64:65] op_sel_hi:[1,0,1]
	v_pk_fma_f32 v[66:67], v[110:111], v[146:147], v[66:67] op_sel_hi:[1,0,1]
	v_cvt_pk_f32_fp8_e32 v[104:105], v41
	v_cvt_pk_f32_fp8_e32 v[108:109], v45
	v_cvt_pk_f32_fp8_sdwa v[106:107], v41 src0_sel:WORD_1
	v_cvt_pk_f32_fp8_sdwa v[110:111], v45 src0_sel:WORD_1
	v_pk_fma_f32 v[68:69], v[104:105], v[144:145], v[68:69] op_sel_hi:[1,0,1]
	v_pk_fma_f32 v[70:71], v[106:107], v[144:145], v[70:71] op_sel_hi:[1,0,1]
	v_pk_fma_f32 v[68:69], v[108:109], v[146:147], v[68:69] op_sel_hi:[1,0,1]
	v_pk_fma_f32 v[70:71], v[110:111], v[146:147], v[70:71] op_sel_hi:[1,0,1]
	v_cvt_pk_f32_fp8_e32 v[104:105], v42
	v_cvt_pk_f32_fp8_e32 v[108:109], v46
	v_cvt_pk_f32_fp8_sdwa v[106:107], v42 src0_sel:WORD_1
	v_cvt_pk_f32_fp8_sdwa v[110:111], v46 src0_sel:WORD_1
	v_pk_fma_f32 v[72:73], v[104:105], v[144:145], v[72:73] op_sel_hi:[1,0,1]
	v_pk_fma_f32 v[74:75], v[106:107], v[144:145], v[74:75] op_sel_hi:[1,0,1]
	v_pk_fma_f32 v[72:73], v[108:109], v[146:147], v[72:73] op_sel_hi:[1,0,1]
	v_pk_fma_f32 v[74:75], v[110:111], v[146:147], v[74:75] op_sel_hi:[1,0,1]
	v_cvt_pk_f32_fp8_e32 v[104:105], v43
	v_cvt_pk_f32_fp8_e32 v[108:109], v47
	v_cvt_pk_f32_fp8_sdwa v[106:107], v43 src0_sel:WORD_1
	v_cvt_pk_f32_fp8_sdwa v[110:111], v47 src0_sel:WORD_1
	v_pk_fma_f32 v[76:77], v[104:105], v[144:145], v[76:77] op_sel_hi:[1,0,1]
	v_pk_fma_f32 v[78:79], v[106:107], v[144:145], v[78:79] op_sel_hi:[1,0,1]
	s_waitcnt lgkmcnt(0)
; DEV void peer_gather(const Params& P, int l, int m0, const int* idxs, const float* gs) {
;     ...
;     for (int q = 0; q < 4; ++q) {
;       hv[q][0] += acc[2 * q][0] * TAB_INV; hv[q][1] += acc[2 * q][1] * TAB_INV; hv[q][2] += acc[2 * q + 1][0] * TAB_INV; hv[q][3] += acc[2 * q + 1][1] * TAB_INV;
;       ss += hv[q][0] * hv[q][0] + hv[q][1] * hv[q][1] + hv[q][2] * hv[q][2] + hv[q][3] * hv[q][3];
;       *(f32x4*)(hrow + 4 * q) = hv[q];
	v_and_or_b32 v142, v142, s90, v240
	v_and_or_b32 v143, v143, s90, v240
	global_load_dwordx4 v[40:43], v142, s[80:81]
	global_load_dwordx4 v[44:47], v143, s[80:81]
	v_pk_fma_f32 v[76:77], v[108:109], v[146:147], v[76:77] op_sel_hi:[1,0,1]
	v_pk_fma_f32 v[78:79], v[110:111], v[146:147], v[78:79] op_sel_hi:[1,0,1]
	ds_bpermute_b32 v142, v253, v135
	ds_bpermute_b32 v143, v254, v135
	ds_bpermute_b32 v144, v255, v137
	ds_bpermute_b32 v146, v153, v137
	s_waitcnt vmcnt(18) lgkmcnt(4)
	v_cvt_pk_f32_fp8_e32 v[104:105], v48
	v_cvt_pk_f32_fp8_e32 v[108:109], v52
	v_cvt_pk_f32_fp8_sdwa v[106:107], v48 src0_sel:WORD_1
	v_cvt_pk_f32_fp8_sdwa v[110:111], v52 src0_sel:WORD_1
	v_pk_fma_f32 v[64:65], v[104:105], v[138:139], v[64:65] op_sel_hi:[1,0,1]
	v_pk_fma_f32 v[66:67], v[106:107], v[138:139], v[66:67] op_sel_hi:[1,0,1]
	v_pk_fma_f32 v[64:65], v[108:109], v[140:141], v[64:65] op_sel_hi:[1,0,1]
	v_pk_fma_f32 v[66:67], v[110:111], v[140:141], v[66:67] op_sel_hi:[1,0,1]
	v_cvt_pk_f32_fp8_e32 v[104:105], v49
	v_cvt_pk_f32_fp8_e32 v[108:109], v53
	v_cvt_pk_f32_fp8_sdwa v[106:107], v49 src0_sel:WORD_1
	v_cvt_pk_f32_fp8_sdwa v[110:111], v53 src0_sel:WORD_1
	v_pk_fma_f32 v[68:69], v[104:105], v[138:139], v[68:69] op_sel_hi:[1,0,1]
	v_pk_fma_f32 v[70:71], v[106:107], v[138:139], v[70:71] op_sel_hi:[1,0,1]
	v_pk_fma_f32 v[68:69], v[108:109], v[140:141], v[68:69] op_sel_hi:[1,0,1]
	v_pk_fma_f32 v[70:71], v[110:111], v[140:141], v[70:71] op_sel_hi:[1,0,1]
	v_cvt_pk_f32_fp8_e32 v[104:105], v50
	v_cvt_pk_f32_fp8_e32 v[108:109], v54
	v_cvt_pk_f32_fp8_sdwa v[106:107], v50 src0_sel:WORD_1
	v_cvt_pk_f32_fp8_sdwa v[110:111], v54 src0_sel:WORD_1
	v_pk_fma_f32 v[72:73], v[104:105], v[138:139], v[72:73] op_sel_hi:[1,0,1]
	v_pk_fma_f32 v[74:75], v[106:107], v[138:139], v[74:75] op_sel_hi:[1,0,1]
	v_pk_fma_f32 v[72:73], v[108:109], v[140:141], v[72:73] op_sel_hi:[1,0,1]
	v_pk_fma_f32 v[74:75], v[110:111], v[140:141], v[74:75] op_sel_hi:[1,0,1]
	v_cvt_pk_f32_fp8_e32 v[104:105], v51
	v_cvt_pk_f32_fp8_e32 v[108:109], v55
	v_cvt_pk_f32_fp8_sdwa v[106:107], v51 src0_sel:WORD_1
	v_cvt_pk_f32_fp8_sdwa v[110:111], v55 src0_sel:WORD_1
	v_pk_fma_f32 v[76:77], v[104:105], v[138:139], v[76:77] op_sel_hi:[1,0,1]
	v_pk_fma_f32 v[78:79], v[106:107], v[138:139], v[78:79] op_sel_hi:[1,0,1]
	s_waitcnt lgkmcnt(0)
	v_and_or_b32 v142, v142, s90, v240
	v_and_or_b32 v143, v143, s90, v240
	global_load_dwordx4 v[48:51], v142, s[80:81]
	global_load_dwordx4 v[52:55], v143, s[80:81]
	v_pk_fma_f32 v[76:77], v[108:109], v[140:141], v[76:77] op_sel_hi:[1,0,1]
	v_pk_fma_f32 v[78:79], v[110:111], v[140:141], v[78:79] op_sel_hi:[1,0,1]
	ds_bpermute_b32 v142, v255, v135
	ds_bpermute_b32 v143, v153, v135
	s_waitcnt vmcnt(18) lgkmcnt(2)
	v_cvt_pk_f32_fp8_e32 v[104:105], v56
	v_cvt_pk_f32_fp8_e32 v[108:109], v60
	v_cvt_pk_f32_fp8_sdwa v[106:107], v56 src0_sel:WORD_1
	v_cvt_pk_f32_fp8_sdwa v[110:111], v60 src0_sel:WORD_1
	v_pk_fma_f32 v[64:65], v[104:105], v[144:145], v[64:65] op_sel_hi:[1,0,1]
	v_pk_fma_f32 v[66:67], v[106:107], v[144:145], v[66:67] op_sel_hi:[1,0,1]
	v_pk_fma_f32 v[64:65], v[108:109], v[146:147], v[64:65] op_sel_hi:[1,0,1]
	v_pk_fma_f32 v[66:67], v[110:111], v[146:147], v[66:67] op_sel_hi:[1,0,1]
	v_cvt_pk_f32_fp8_e32 v[104:105], v57
	v_cvt_pk_f32_fp8_e32 v[108:109], v61
	v_cvt_pk_f32_fp8_sdwa v[106:107], v57 src0_sel:WORD_1
	v_cvt_pk_f32_fp8_sdwa v[110:111], v61 src0_sel:WORD_1
	v_pk_fma_f32 v[68:69], v[104:105], v[144:145], v[68:69] op_sel_hi:[1,0,1]
	v_pk_fma_f32 v[70:71], v[106:107], v[144:145], v[70:71] op_sel_hi:[1,0,1]
	v_pk_fma_f32 v[68:69], v[108:109], v[146:147], v[68:69] op_sel_hi:[1,0,1]
	v_pk_fma_f32 v[70:71], v[110:111], v[146:147], v[70:71] op_sel_hi:[1,0,1]
	v_cvt_pk_f32_fp8_e32 v[104:105], v58
	v_cvt_pk_f32_fp8_e32 v[108:109], v62
	v_cvt_pk_f32_fp8_sdwa v[106:107], v58 src0_sel:WORD_1
	v_cvt_pk_f32_fp8_sdwa v[110:111], v62 src0_sel:WORD_1
	v_pk_fma_f32 v[72:73], v[104:105], v[144:145], v[72:73] op_sel_hi:[1,0,1]
	v_pk_fma_f32 v[74:75], v[106:107], v[144:145], v[74:75] op_sel_hi:[1,0,1]
	v_pk_fma_f32 v[72:73], v[108:109], v[146:147], v[72:73] op_sel_hi:[1,0,1]
	v_pk_fma_f32 v[74:75], v[110:111], v[146:147], v[74:75] op_sel_hi:[1,0,1]
	v_cvt_pk_f32_fp8_e32 v[104:105], v59
	v_cvt_pk_f32_fp8_e32 v[108:109], v63
	v_cvt_pk_f32_fp8_sdwa v[106:107], v59 src0_sel:WORD_1
	v_cvt_pk_f32_fp8_sdwa v[110:111], v63 src0_sel:WORD_1
	v_pk_fma_f32 v[76:77], v[104:105], v[144:145], v[76:77] op_sel_hi:[1,0,1]
	v_pk_fma_f32 v[78:79], v[106:107], v[144:145], v[78:79] op_sel_hi:[1,0,1]
	s_waitcnt lgkmcnt(0)
	v_and_or_b32 v142, v142, s90, v240
	v_and_or_b32 v143, v143, s90, v240
	global_load_dwordx4 v[56:59], v142, s[80:81]
	global_load_dwordx4 v[60:63], v143, s[80:81]
	v_pk_fma_f32 v[76:77], v[108:109], v[146:147], v[76:77] op_sel_hi:[1,0,1]
	v_pk_fma_f32 v[78:79], v[110:111], v[146:147], v[78:79] op_sel_hi:[1,0,1]
	s_add_u32 s92, s100, 2
	s_min_u32 s92, s92, 127
	s_and_b32 s92, s92, 15
	s_lshl_b32 vcc_lo, s92, 9
	s_add_u32 vcc_lo, vcc_lo, s101
	v_add_u32_e32 v116, vcc_lo, v234
	ds_read_b32 v134, v116
	ds_read_b32 v135, v116 offset:256
	s_add_u32 s92, s100, 1
	s_min_u32 s92, s92, 127
	s_and_b32 s92, s92, 15
	s_lshl_b32 vcc_lo, s92, 9
	s_add_u32 vcc_lo, vcc_lo, s101
	s_add_u32 vcc_lo, vcc_lo, 0x10000
	v_add_u32_e32 v117, vcc_lo, v234
	ds_read_b32 v136, v117
	ds_read_b32 v137, v117 offset:256
	s_nop 1
	v_permlane32_swap_b32_e32 v64, v65
	v_permlane32_swap_b32_e32 v66, v67
	v_permlane32_swap_b32_e32 v68, v69
	v_permlane32_swap_b32_e32 v70, v71
	v_permlane32_swap_b32_e32 v72, v73
	v_permlane32_swap_b32_e32 v74, v75
	v_permlane32_swap_b32_e32 v76, v77
	v_permlane32_swap_b32_e32 v78, v79
	v_add_f32_e32 v64, v64, v65
	v_add_f32_e32 v66, v66, v67
	v_add_f32_e32 v68, v68, v69
	v_add_f32_e32 v70, v70, v71
	v_add_f32_e32 v72, v72, v73
	v_add_f32_e32 v74, v74, v75
	v_add_f32_e32 v76, v76, v77
	v_add_f32_e32 v78, v78, v79
	s_nop 1
	v_permlane16_swap_b32_e32 v64, v66
	v_permlane16_swap_b32_e32 v68, v70
	v_permlane16_swap_b32_e32 v72, v74
	v_permlane16_swap_b32_e32 v76, v78
	v_add_f32_e32 v64, v64, v66
	v_add_f32_e32 v68, v68, v70
	v_add_f32_e32 v72, v72, v74
	v_add_f32_e32 v76, v76, v78
	s_mov_b32 s88, 0xff00ff00
	s_mov_b32 s89, 0xff00ff00
	s_nop 0
	v_cndmask_b32_e64 v65, v64, v68, s[88:89]
	v_cndmask_b32_e64 v66, v68, v64, s[88:89]
	v_cndmask_b32_e64 v73, v72, v76, s[88:89]
	v_cndmask_b32_e64 v74, v76, v72, s[88:89]
	s_nop 1
	v_add_f32_dpp v64, v66, v65 row_ror:8 row_mask:0xf bank_mask:0xf
	v_add_f32_dpp v72, v74, v73 row_ror:8 row_mask:0xf bank_mask:0xf
	s_waitcnt vmcnt(16)
	v_fmac_f32_e32 v80, 0x3c800000, v64
	v_fmac_f32_e32 v81, 0x3c800000, v72
	global_store_dword v119, v80, s[82:83]
	global_store_dword v119, v81, s[82:83] offset:32
	s_add_u32 s100, s100, 1
	s_cmp_lt_u32 s100, 128
	s_cbranch_scc1 .Lpg0_vloop
; DEV unsigned pk2(float lo, float hi) { f32x2_t v = {lo, hi}; bf16x2_t b = __builtin_convertvector(v, bf16x2_t); return __builtin_bit_cast(unsigned, b); }
; DEV void peer_gather(const Params& P, int l, int m0, const int* idxs, const float* gs) {
;     ...
;     float ss = 0.f;
; #pragma unroll
;     for (int q = 0; q < 4; ++q) {
;       hv[q][0] += acc[2 * q][0] * TAB_INV; hv[q][1] += acc[2 * q][1] * TAB_INV; hv[q][2] += acc[2 * q + 1][0] * TAB_INV; hv[q][3] += acc[2 * q + 1][1] * TAB_INV;
;       ss += hv[q][0] * hv[q][0] + hv[q][1] * hv[q][1] + hv[q][2] * hv[q][2] + hv[q][3] * hv[q][3];
;       *(f32x4*)(hrow + 4 * q) = hv[q];
;     }
;     const float rstd = rsqrtf(wave_sum(ss) * (1.f / DM) + EPS);
;     u32x4 oa, ob;
; #pragma unroll
;     for (int q = 0; q < 4; ++q) {
;       const f32x4 g = *(const f32x4*)(gp + lane * 16 + 4 * q);
;       const unsigned p0 = pk2(hv[q][0] * rstd * g[0], hv[q][1] * rstd * g[1]), p1 = pk2(hv[q][2] * rstd * g[2], hv[q][3] * rstd * g[3]);
;       if (q < 2) { oa[2 * q] = p0; oa[2 * q + 1] = p1; } else { ob[2 * (q - 2)] = p0; ob[2 * (q - 2) + 1] = p1; }
;     }
;     *(u32x4*)(hn + tok * DM + lane * 16) = oa; *(u32x4*)(hn + tok * DM + lane * 16 + 8) = ob;
	s_waitcnt vmcnt(0) lgkmcnt(0)
	v_readfirstlane_b32 s88, v130
	v_readfirstlane_b32 s89, v131
	s_nop 4
	v_lshlrev_b32_e32 v117, 6, v233
	global_load_dwordx4 v[16:19], v117, s[88:89] offset:0
	global_load_dwordx4 v[20:23], v117, s[88:89] offset:16
	global_load_dwordx4 v[24:27], v117, s[88:89] offset:32
	global_load_dwordx4 v[28:31], v117, s[88:89] offset:48
	s_mov_b32 s2, 0
.Lpg0_epi:
	v_readfirstlane_b32 s82, v132
	v_readfirstlane_b32 s83, v133
	s_nop 4
	s_add_u32 s98, s3, s2
	s_lshl_b32 s99, s98, 12
	v_lshl_add_u32 v116, v233, 6, s99
	global_load_dwordx4 v[0:3], v116, s[82:83] offset:0
	global_load_dwordx4 v[4:7], v116, s[82:83] offset:16
	global_load_dwordx4 v[8:11], v116, s[82:83] offset:32
	global_load_dwordx4 v[12:15], v116, s[82:83] offset:48
	s_waitcnt vmcnt(0)
	v_pk_mul_f32 v[104:105], v[0:1], v[0:1]
	v_pk_fma_f32 v[104:105], v[2:3], v[2:3], v[104:105]
	v_pk_fma_f32 v[104:105], v[4:5], v[4:5], v[104:105]
	v_pk_fma_f32 v[104:105], v[6:7], v[6:7], v[104:105]
	v_pk_fma_f32 v[104:105], v[8:9], v[8:9], v[104:105]
	v_pk_fma_f32 v[104:105], v[10:11], v[10:11], v[104:105]
	v_pk_fma_f32 v[104:105], v[12:13], v[12:13], v[104:105]
	v_pk_fma_f32 v[104:105], v[14:15], v[14:15], v[104:105]
	s_nop 0
	v_add_f32_e32 v118, v104, v105
	s_nop 1
	v_add_f32_dpp v118, v118, v118 quad_perm:[1,0,3,2] row_mask:0xf bank_mask:0xf
	s_nop 1
	v_add_f32_dpp v118, v118, v118 quad_perm:[2,3,0,1] row_mask:0xf bank_mask:0xf
	s_nop 1
	v_add_f32_dpp v118, v118, v118 row_half_mirror row_mask:0xf bank_mask:0xf
	s_nop 1
	v_add_f32_dpp v118, v118, v118 row_mirror row_mask:0xf bank_mask:0xf
	v_xor_b32_e32 v119, 64, v234
	ds_bpermute_b32 v119, v119, v118
	s_waitcnt lgkmcnt(0)
	v_add_f32_e32 v118, v118, v119
	v_xor_b32_e32 v119, 128, v234
	ds_bpermute_b32 v119, v119, v118
	s_waitcnt lgkmcnt(0)
	v_add_f32_e32 v118, v118, v119
	v_mov_b32_e32 v119, 0x358637bd
	v_fmac_f32_e32 v119, 0x3a800000, v118
	v_rsq_f32_e32 v106, v119
	s_nop 1
	v_pk_mul_f32 v[0:1], v[0:1], v[106:107] op_sel_hi:[1,0]
	v_pk_mul_f32 v[2:3], v[2:3], v[106:107] op_sel_hi:[1,0]
	v_pk_mul_f32 v[4:5], v[4:5], v[106:107] op_sel_hi:[1,0]
	v_pk_mul_f32 v[6:7], v[6:7], v[106:107] op_sel_hi:[1,0]
	v_pk_mul_f32 v[8:9], v[8:9], v[106:107] op_sel_hi:[1,0]
	v_pk_mul_f32 v[10:11], v[10:11], v[106:107] op_sel_hi:[1,0]
	v_pk_mul_f32 v[12:13], v[12:13], v[106:107] op_sel_hi:[1,0]
	v_pk_mul_f32 v[14:15], v[14:15], v[106:107] op_sel_hi:[1,0]
	v_pk_mul_f32 v[0:1], v[16:17], v[0:1]
	v_pk_mul_f32 v[2:3], v[18:19], v[2:3]
	v_pk_mul_f32 v[4:5], v[20:21], v[4:5]
	v_pk_mul_f32 v[6:7], v[22:23], v[6:7]
	v_pk_mul_f32 v[8:9], v[24:25], v[8:9]
	v_pk_mul_f32 v[10:11], v[26:27], v[10:11]
	v_pk_mul_f32 v[12:13], v[28:29], v[12:13]
	v_pk_mul_f32 v[14:15], v[30:31], v[14:15]
	v_cvt_pk_bf16_f32 v32, v0, v1
	v_cvt_pk_bf16_f32 v33, v2, v3
	v_cvt_pk_bf16_f32 v34, v4, v5
	v_cvt_pk_bf16_f32 v35, v6, v7
	v_cvt_pk_bf16_f32 v36, v8, v9
	v_cvt_pk_bf16_f32 v37, v10, v11
	v_cvt_pk_bf16_f32 v38, v12, v13
	v_cvt_pk_bf16_f32 v39, v14, v15
	v_readfirstlane_b32 s82, v128
	v_readfirstlane_b32 s83, v129
	s_nop 4
	s_lshl_b32 s99, s98, 11
	v_lshl_add_u32 v116, v233, 5, s99
	global_store_dwordx4 v116, v[32:35], s[82:83]
	global_store_dwordx4 v116, v[36:39], s[82:83] offset:16
	s_add_u32 s2, s2, 1
	s_cmp_lt_u32 s2, 16
	s_cbranch_scc1 .Lpg0_epi
	s_waitcnt vmcnt(0) lgkmcnt(0)
	v_readlane_b32 s90, v231, 30
	v_readlane_b32 s91, v231, 31

; DEV void sort_lists(int lane, int& myi0, int& myi1, float& myg0, float& myg1) {
; #pragma unroll
;     for (int k = 2; k <= 128; k <<= 1) {
; #pragma unroll
;       for (int j = k >> 1; j >= 1; j >>= 1) {
;         if (j == 64) {
;           const bool sw_ = myi1 < myi0;
;           const int ti = sw_ ? myi1 : myi0, tj = sw_ ? myi0 : myi1; const float tg = sw_ ? myg1 : myg0, th = sw_ ? myg0 : myg1;
;           myi0 = ti; myi1 = tj; myg0 = tg; myg1 = th;
;         } else {
;           const bool lower = (lane & j) == 0;
;           {
;             const bool up = (k == 128) ? true : ((k == 64) ? true : ((lane & k) == 0));
;             const int oi = __shfl_xor(myi0, j); const float og = __shfl_xor(myg0, j);
;             const bool take = (lower == up) ? (oi < myi0) : (oi > myi0);
;             myi0 = take ? oi : myi0; myg0 = take ? og : myg0;
;           }
;           {
;             const bool up = (k == 128) ? true : ((k == 64) ? false : ((lane & k) == 0));
;             const int oi = __shfl_xor(myi1, j); const float og = __shfl_xor(myg1, j);
;             const bool take = (lower == up) ? (oi < myi1) : (oi > myi1);
;             myi1 = take ? oi : myi1; myg1 = take ? og : myg1;
;           }
;         }
;       }
;     }
; }
; DEV void peer_gather(const Params& P, int l, int m0, const int* idxs, const float* gs) {
;     ...
;   const int row = lane >> 4, rmap = ((row & 1) << 1) | (row >> 1);
;   u32x4 nxa = *(const u32x4*)(hn + (size_t)(m0 + wid * 16) * DM + lane * 16), nxb = *(const u32x4*)(hn + (size_t)(m0 + wid * 16) * DM + lane * 16 + 8);
;   int ni0 = idxs[(wid * 16) * 128 + lane], ni1 = idxs[(wid * 16) * 128 + 64 + lane];
;   float ng0 = gs[(wid * 16) * 128 + lane], ng1 = gs[(wid * 16) * 128 + 64 + lane];
;   sort_lists(lane, ni0, ni1, ng0, ng1);
.LBB0_752:
	s_waitcnt vmcnt(0) lgkmcnt(0)
	v_and_b32_e32 v233, 63, v176
	v_lshlrev_b32_e32 v234, 2, v233
	v_and_b32_e32 v116, 7, v233
	v_lshlrev_b32_e32 v235, 4, v116
	v_lshlrev_b32_e32 v236, 5, v116
	v_lshrrev_b32_e32 v117, 3, v233
	v_lshlrev_b32_e32 v237, 2, v117
	v_lshl_add_u32 v239, v116, 3, v117
	v_lshlrev_b32_e32 v239, 2, v239
	v_lshlrev_b32_e32 v238, 4, v116
	v_and_b32_e32 v117, 1, v117
	v_lshl_add_u32 v238, v117, 2, v238
	v_bfe_u32 v117, v233, 4, 1
	v_lshl_add_u32 v238, v117, 1, v238
	v_lshrrev_b32_e32 v117, 5, v233
	v_add_u32_e32 v238, v117, v238
	v_lshlrev_b32_e32 v238, 2, v238
	v_add_u32_e32 v249, 0, v237
	v_add_u32_e32 v250, 32, v237
	v_add_u32_e32 v251, 64, v237
	v_add_u32_e32 v252, 96, v237
	v_add_u32_e32 v253, 128, v237
	v_add_u32_e32 v254, 160, v237
	v_add_u32_e32 v255, 192, v237
	v_add_u32_e32 v153, 224, v237
	v_readfirstlane_b32 s33, v176
	s_lshr_b32 s33, s33, 6
	s_lshl_b32 s101, s33, 13
	s_lshl_b32 s33, s33, 4
	v_readlane_b32 s3, v231, 15
	s_add_u32 s3, s3, s33
	s_mov_b32 s2, 0
.Lpg1_p0:
	v_readlane_b32 s82, v231, 13
	v_readlane_b32 s83, v231, 14
	s_nop 4
	s_lshl_b32 s98, s2, 2
	s_add_u32 s98, s98, s33
	s_add_u32 s98, s98, 0
	s_lshl_b32 s98, s98, 9
	v_add_u32_e32 v116, s98, v234
	global_load_dword v241, v116, s[82:83]
	global_load_dword v242, v116, s[82:83] offset:256
	s_lshl_b32 s98, s2, 2
	s_add_u32 s98, s98, s33
	s_add_u32 s98, s98, 1
	s_lshl_b32 s98, s98, 9
	v_add_u32_e32 v117, s98, v234
	global_load_dword v243, v117, s[82:83]
	global_load_dword v244, v117, s[82:83] offset:256
	s_lshl_b32 s98, s2, 2
	s_add_u32 s98, s98, s33
	s_add_u32 s98, s98, 2
	s_lshl_b32 s98, s98, 9
	v_add_u32_e32 v118, s98, v234
	global_load_dword v245, v118, s[82:83]
	global_load_dword v246, v118, s[82:83] offset:256
	s_lshl_b32 s98, s2, 2
	s_add_u32 s98, s98, s33
	s_add_u32 s98, s98, 3
	s_lshl_b32 s98, s98, 9
	v_add_u32_e32 v119, s98, v234
	global_load_dword v247, v119, s[82:83]
	global_load_dword v248, v119, s[82:83] offset:256
	s_waitcnt vmcnt(0)
	v_or_b32_e32 v116, 64, v233
	v_lshl_or_b32 v241, v241, 7, v233
	v_lshl_or_b32 v242, v242, 7, v116
	v_lshl_or_b32 v243, v243, 7, v233
	v_lshl_or_b32 v244, v244, 7, v116
	v_lshl_or_b32 v245, v245, 7, v233
	v_lshl_or_b32 v246, v246, 7, v116
	v_lshl_or_b32 v247, v247, 7, v233
	v_lshl_or_b32 v248, v248, 7, v116
	v_xor_b32_e32 v116, 4, v234
	ds_bpermute_b32 v0, v116, v241
	ds_bpermute_b32 v1, v116, v243
	ds_bpermute_b32 v2, v116, v245
	ds_bpermute_b32 v3, v116, v247
	ds_bpermute_b32 v4, v116, v242
	ds_bpermute_b32 v5, v116, v244
	ds_bpermute_b32 v6, v116, v246
	ds_bpermute_b32 v7, v116, v248
	s_waitcnt lgkmcnt(0)
	s_mov_b32 s88, 0x99999999
	s_mov_b32 s89, 0x99999999
	v_min_u32_e32 v104, v241, v0
	v_max_u32_e32 v105, v241, v0
	v_cndmask_b32_e64 v241, v105, v104, s[88:89]
	v_min_u32_e32 v106, v243, v1
	v_max_u32_e32 v107, v243, v1
	v_cndmask_b32_e64 v243, v107, v106, s[88:89]
	v_min_u32_e32 v104, v245, v2
	v_max_u32_e32 v105, v245, v2
	v_cndmask_b32_e64 v245, v105, v104, s[88:89]
	v_min_u32_e32 v106, v247, v3
	v_max_u32_e32 v107, v247, v3
	v_cndmask_b32_e64 v247, v107, v106, s[88:89]
	v_min_u32_e32 v104, v242, v4
	v_max_u32_e32 v105, v242, v4
	v_cndmask_b32_e64 v242, v105, v104, s[88:89]
	v_min_u32_e32 v106, v244, v5
	v_max_u32_e32 v107, v244, v5
	v_cndmask_b32_e64 v244, v107, v106, s[88:89]
	v_min_u32_e32 v104, v246, v6
	v_max_u32_e32 v105, v246, v6
	v_cndmask_b32_e64 v246, v105, v104, s[88:89]
	v_min_u32_e32 v106, v248, v7
	v_max_u32_e32 v107, v248, v7
	v_cndmask_b32_e64 v248, v107, v106, s[88:89]
	v_xor_b32_e32 v116, 8, v234
	ds_bpermute_b32 v0, v116, v241
	ds_bpermute_b32 v1, v116, v243
	ds_bpermute_b32 v2, v116, v245
	ds_bpermute_b32 v3, v116, v247
	ds_bpermute_b32 v4, v116, v242
	ds_bpermute_b32 v5, v116, v244
	ds_bpermute_b32 v6, v116, v246
	ds_bpermute_b32 v7, v116, v248
	s_waitcnt lgkmcnt(0)
	s_mov_b32 s88, 0xc3c3c3c3
	s_mov_b32 s89, 0xc3c3c3c3
	v_min_u32_e32 v104, v241, v0
	v_max_u32_e32 v105, v241, v0
	v_cndmask_b32_e64 v241, v105, v104, s[88:89]
	v_min_u32_e32 v106, v243, v1
	v_max_u32_e32 v107, v243, v1
	v_cndmask_b32_e64 v243, v107, v106, s[88:89]
	v_min_u32_e32 v104, v245, v2
	v_max_u32_e32 v105, v245, v2
	v_cndmask_b32_e64 v245, v105, v104, s[88:89]
	v_min_u32_e32 v106, v247, v3
	v_max_u32_e32 v107, v247, v3
	v_cndmask_b32_e64 v247, v107, v106, s[88:89]
	v_min_u32_e32 v104, v242, v4
	v_max_u32_e32 v105, v242, v4
	v_cndmask_b32_e64 v242, v105, v104, s[88:89]
	v_min_u32_e32 v106, v244, v5
	v_max_u32_e32 v107, v244, v5
	v_cndmask_b32_e64 v244, v107, v106, s[88:89]
	v_min_u32_e32 v104, v246, v6
	v_max_u32_e32 v105, v246, v6
	v_cndmask_b32_e64 v246, v105, v104, s[88:89]
	v_min_u32_e32 v106, v248, v7
	v_max_u32_e32 v107, v248, v7
	v_cndmask_b32_e64 v248, v107, v106, s[88:89]
	v_xor_b32_e32 v116, 4, v234
	ds_bpermute_b32 v0, v116, v241
	ds_bpermute_b32 v1, v116, v243
	ds_bpermute_b32 v2, v116, v245
	ds_bpermute_b32 v3, v116, v247
	ds_bpermute_b32 v4, v116, v242
	ds_bpermute_b32 v5, v116, v244
	ds_bpermute_b32 v6, v116, v246
	ds_bpermute_b32 v7, v116, v248
	s_waitcnt lgkmcnt(0)
	s_mov_b32 s88, 0xa5a5a5a5
	s_mov_b32 s89, 0xa5a5a5a5
	v_min_u32_e32 v104, v241, v0
	v_max_u32_e32 v105, v241, v0
	v_cndmask_b32_e64 v241, v105, v104, s[88:89]
	v_min_u32_e32 v106, v243, v1
	v_max_u32_e32 v107, v243, v1
	v_cndmask_b32_e64 v243, v107, v106, s[88:89]
	v_min_u32_e32 v104, v245, v2
	v_max_u32_e32 v105, v245, v2
	v_cndmask_b32_e64 v245, v105, v104, s[88:89]
	v_min_u32_e32 v106, v247, v3
	v_max_u32_e32 v107, v247, v3
	v_cndmask_b32_e64 v247, v107, v106, s[88:89]
	v_min_u32_e32 v104, v242, v4
	v_max_u32_e32 v105, v242, v4
	v_cndmask_b32_e64 v242, v105, v104, s[88:89]
	v_min_u32_e32 v106, v244, v5
	v_max_u32_e32 v107, v244, v5
	v_cndmask_b32_e64 v244, v107, v106, s[88:89]
	v_min_u32_e32 v104, v246, v6
	v_max_u32_e32 v105, v246, v6
	v_cndmask_b32_e64 v246, v105, v104, s[88:89]
	v_min_u32_e32 v106, v248, v7
	v_max_u32_e32 v107, v248, v7
	v_cndmask_b32_e64 v248, v107, v106, s[88:89]
	v_xor_b32_e32 v116, 16, v234
	ds_bpermute_b32 v0, v116, v241
	ds_bpermute_b32 v1, v116, v243
	ds_bpermute_b32 v2, v116, v245
	ds_bpermute_b32 v3, v116, v247
	ds_bpermute_b32 v4, v116, v242
	ds_bpermute_b32 v5, v116, v244
	ds_bpermute_b32 v6, v116, v246
	ds_bpermute_b32 v7, v116, v248
	s_waitcnt lgkmcnt(0)
; DEV void sort_lists(int lane, int& myi0, int& myi1, float& myg0, float& myg1) {
; #pragma unroll
;     for (int k = 2; k <= 128; k <<= 1) {
; #pragma unroll
;       for (int j = k >> 1; j >= 1; j >>= 1) {
;         if (j == 64) {
;           const bool sw_ = myi1 < myi0;
;           const int ti = sw_ ? myi1 : myi0, tj = sw_ ? myi0 : myi1; const float tg = sw_ ? myg1 : myg0, th = sw_ ? myg0 : myg1;
;           myi0 = ti; myi1 = tj; myg0 = tg; myg1 = th;
;         } else {
;           const bool lower = (lane & j) == 0;
;           {
;             const bool up = (k == 128) ? true : ((k == 64) ? true : ((lane & k) == 0));
;             const int oi = __shfl_xor(myi0, j); const float og = __shfl_xor(myg0, j);
;             const bool take = (lower == up) ? (oi < myi0) : (oi > myi0);
;             myi0 = take ? oi : myi0; myg0 = take ? og : myg0;
;           }
;           {
;             const bool up = (k == 128) ? true : ((k == 64) ? false : ((lane & k) == 0));
;             const int oi = __shfl_xor(myi1, j); const float og = __shfl_xor(myg1, j);
;             const bool take = (lower == up) ? (oi < myi1) : (oi > myi1);
;             myi1 = take ? oi : myi1; myg1 = take ? og : myg1;
;           }
;         }
;       }
;     }
; }
	s_mov_b32 s88, 0xf00ff00f
	s_mov_b32 s89, 0xf00ff00f
	v_min_u32_e32 v104, v241, v0
	v_max_u32_e32 v105, v241, v0
	v_cndmask_b32_e64 v241, v105, v104, s[88:89]
	v_min_u32_e32 v106, v243, v1
	v_max_u32_e32 v107, v243, v1
	v_cndmask_b32_e64 v243, v107, v106, s[88:89]
	v_min_u32_e32 v104, v245, v2
	v_max_u32_e32 v105, v245, v2
	v_cndmask_b32_e64 v245, v105, v104, s[88:89]
	v_min_u32_e32 v106, v247, v3
	v_max_u32_e32 v107, v247, v3
	v_cndmask_b32_e64 v247, v107, v106, s[88:89]
	v_min_u32_e32 v104, v242, v4
	v_max_u32_e32 v105, v242, v4
	v_cndmask_b32_e64 v242, v105, v104, s[88:89]
	v_min_u32_e32 v106, v244, v5
	v_max_u32_e32 v107, v244, v5
	v_cndmask_b32_e64 v244, v107, v106, s[88:89]
	v_min_u32_e32 v104, v246, v6
	v_max_u32_e32 v105, v246, v6
	v_cndmask_b32_e64 v246, v105, v104, s[88:89]
	v_min_u32_e32 v106, v248, v7
	v_max_u32_e32 v107, v248, v7
	v_cndmask_b32_e64 v248, v107, v106, s[88:89]
	v_xor_b32_e32 v116, 8, v234
	ds_bpermute_b32 v0, v116, v241
	ds_bpermute_b32 v1, v116, v243
	ds_bpermute_b32 v2, v116, v245
	ds_bpermute_b32 v3, v116, v247
	ds_bpermute_b32 v4, v116, v242
	ds_bpermute_b32 v5, v116, v244
	ds_bpermute_b32 v6, v116, v246
	ds_bpermute_b32 v7, v116, v248
	s_waitcnt lgkmcnt(0)
	s_mov_b32 s88, 0xcc33cc33
	s_mov_b32 s89, 0xcc33cc33
	v_min_u32_e32 v104, v241, v0
	v_max_u32_e32 v105, v241, v0
	v_cndmask_b32_e64 v241, v105, v104, s[88:89]
	v_min_u32_e32 v106, v243, v1
	v_max_u32_e32 v107, v243, v1
	v_cndmask_b32_e64 v243, v107, v106, s[88:89]
	v_min_u32_e32 v104, v245, v2
	v_max_u32_e32 v105, v245, v2
	v_cndmask_b32_e64 v245, v105, v104, s[88:89]
	v_min_u32_e32 v106, v247, v3
	v_max_u32_e32 v107, v247, v3
	v_cndmask_b32_e64 v247, v107, v106, s[88:89]
	v_min_u32_e32 v104, v242, v4
	v_max_u32_e32 v105, v242, v4
	v_cndmask_b32_e64 v242, v105, v104, s[88:89]
	v_min_u32_e32 v106, v244, v5
	v_max_u32_e32 v107, v244, v5
	v_cndmask_b32_e64 v244, v107, v106, s[88:89]
	v_min_u32_e32 v104, v246, v6
	v_max_u32_e32 v105, v246, v6
	v_cndmask_b32_e64 v246, v105, v104, s[88:89]
	v_min_u32_e32 v106, v248, v7
	v_max_u32_e32 v107, v248, v7
	v_cndmask_b32_e64 v248, v107, v106, s[88:89]
	v_xor_b32_e32 v116, 4, v234
	ds_bpermute_b32 v0, v116, v241
	ds_bpermute_b32 v1, v116, v243
	ds_bpermute_b32 v2, v116, v245
	ds_bpermute_b32 v3, v116, v247
	ds_bpermute_b32 v4, v116, v242
	ds_bpermute_b32 v5, v116, v244
	ds_bpermute_b32 v6, v116, v246
	ds_bpermute_b32 v7, v116, v248
	s_waitcnt lgkmcnt(0)
	s_mov_b32 s88, 0xaa55aa55
	s_mov_b32 s89, 0xaa55aa55
	v_min_u32_e32 v104, v241, v0
	v_max_u32_e32 v105, v241, v0
	v_cndmask_b32_e64 v241, v105, v104, s[88:89]
	v_min_u32_e32 v106, v243, v1
	v_max_u32_e32 v107, v243, v1
	v_cndmask_b32_e64 v243, v107, v106, s[88:89]
	v_min_u32_e32 v104, v245, v2
	v_max_u32_e32 v105, v245, v2
	v_cndmask_b32_e64 v245, v105, v104, s[88:89]
	v_min_u32_e32 v106, v247, v3
	v_max_u32_e32 v107, v247, v3
	v_cndmask_b32_e64 v247, v107, v106, s[88:89]
	v_min_u32_e32 v104, v242, v4
	v_max_u32_e32 v105, v242, v4
	v_cndmask_b32_e64 v242, v105, v104, s[88:89]
	v_min_u32_e32 v106, v244, v5
	v_max_u32_e32 v107, v244, v5
	v_cndmask_b32_e64 v244, v107, v106, s[88:89]
	v_min_u32_e32 v104, v246, v6
	v_max_u32_e32 v105, v246, v6
	v_cndmask_b32_e64 v246, v105, v104, s[88:89]
	v_min_u32_e32 v106, v248, v7
	v_max_u32_e32 v107, v248, v7
	v_cndmask_b32_e64 v248, v107, v106, s[88:89]
	v_xor_b32_e32 v116, 32, v234
	ds_bpermute_b32 v0, v116, v241
	ds_bpermute_b32 v1, v116, v243
	ds_bpermute_b32 v2, v116, v245
	ds_bpermute_b32 v3, v116, v247
	ds_bpermute_b32 v4, v116, v242
	ds_bpermute_b32 v5, v116, v244
	ds_bpermute_b32 v6, v116, v246
	ds_bpermute_b32 v7, v116, v248
	s_waitcnt lgkmcnt(0)
	s_mov_b32 s88, 0xff0000ff
	s_mov_b32 s89, 0xff0000ff
	v_min_u32_e32 v104, v241, v0
	v_max_u32_e32 v105, v241, v0
	v_cndmask_b32_e64 v241, v105, v104, s[88:89]
	v_min_u32_e32 v106, v243, v1
	v_max_u32_e32 v107, v243, v1
	v_cndmask_b32_e64 v243, v107, v106, s[88:89]
	v_min_u32_e32 v104, v245, v2
	v_max_u32_e32 v105, v245, v2
	v_cndmask_b32_e64 v245, v105, v104, s[88:89]
	v_min_u32_e32 v106, v247, v3
	v_max_u32_e32 v107, v247, v3
	v_cndmask_b32_e64 v247, v107, v106, s[88:89]
	v_min_u32_e32 v104, v242, v4
	v_max_u32_e32 v105, v242, v4
	v_cndmask_b32_e64 v242, v105, v104, s[88:89]
	v_min_u32_e32 v106, v244, v5
	v_max_u32_e32 v107, v244, v5
	v_cndmask_b32_e64 v244, v107, v106, s[88:89]
	v_min_u32_e32 v104, v246, v6
	v_max_u32_e32 v105, v246, v6
	v_cndmask_b32_e64 v246, v105, v104, s[88:89]
	v_min_u32_e32 v106, v248, v7
	v_max_u32_e32 v107, v248, v7
	v_cndmask_b32_e64 v248, v107, v106, s[88:89]
	v_xor_b32_e32 v116, 16, v234
	ds_bpermute_b32 v0, v116, v241
	ds_bpermute_b32 v1, v116, v243
	ds_bpermute_b32 v2, v116, v245
	ds_bpermute_b32 v3, v116, v247
	ds_bpermute_b32 v4, v116, v242
	ds_bpermute_b32 v5, v116, v244
	ds_bpermute_b32 v6, v116, v246
	ds_bpermute_b32 v7, v116, v248
	s_waitcnt lgkmcnt(0)
	s_mov_b32 s88, 0xf0f00f0f
	s_mov_b32 s89, 0xf0f00f0f
	v_min_u32_e32 v104, v241, v0
	v_max_u32_e32 v105, v241, v0
	v_cndmask_b32_e64 v241, v105, v104, s[88:89]
	v_min_u32_e32 v106, v243, v1
	v_max_u32_e32 v107, v243, v1
	v_cndmask_b32_e64 v243, v107, v106, s[88:89]
	v_min_u32_e32 v104, v245, v2
	v_max_u32_e32 v105, v245, v2
	v_cndmask_b32_e64 v245, v105, v104, s[88:89]
	v_min_u32_e32 v106, v247, v3
	v_max_u32_e32 v107, v247, v3
	v_cndmask_b32_e64 v247, v107, v106, s[88:89]
	v_min_u32_e32 v104, v242, v4
	v_max_u32_e32 v105, v242, v4
	v_cndmask_b32_e64 v242, v105, v104, s[88:89]
	v_min_u32_e32 v106, v244, v5
	v_max_u32_e32 v107, v244, v5
	v_cndmask_b32_e64 v244, v107, v106, s[88:89]
	v_min_u32_e32 v104, v246, v6
	v_max_u32_e32 v105, v246, v6
	v_cndmask_b32_e64 v246, v105, v104, s[88:89]
	v_min_u32_e32 v106, v248, v7
	v_max_u32_e32 v107, v248, v7
	v_cndmask_b32_e64 v248, v107, v106, s[88:89]
	v_xor_b32_e32 v116, 8, v234
	ds_bpermute_b32 v0, v116, v241
	ds_bpermute_b32 v1, v116, v243
	ds_bpermute_b32 v2, v116, v245
	ds_bpermute_b32 v3, v116, v247
	ds_bpermute_b32 v4, v116, v242
	ds_bpermute_b32 v5, v116, v244
	ds_bpermute_b32 v6, v116, v246
	ds_bpermute_b32 v7, v116, v248
	s_waitcnt lgkmcnt(0)
; DEV void sort_lists(int lane, int& myi0, int& myi1, float& myg0, float& myg1) {
; #pragma unroll
;     for (int k = 2; k <= 128; k <<= 1) {
; #pragma unroll
;       for (int j = k >> 1; j >= 1; j >>= 1) {
;         if (j == 64) {
;           const bool sw_ = myi1 < myi0;
;           const int ti = sw_ ? myi1 : myi0, tj = sw_ ? myi0 : myi1; const float tg = sw_ ? myg1 : myg0, th = sw_ ? myg0 : myg1;
;           myi0 = ti; myi1 = tj; myg0 = tg; myg1 = th;
;         } else {
;           const bool lower = (lane & j) == 0;
;           {
;             const bool up = (k == 128) ? true : ((k == 64) ? true : ((lane & k) == 0));
;             const int oi = __shfl_xor(myi0, j); const float og = __shfl_xor(myg0, j);
;             const bool take = (lower == up) ? (oi < myi0) : (oi > myi0);
;             myi0 = take ? oi : myi0; myg0 = take ? og : myg0;
;           }
;           {
;             const bool up = (k == 128) ? true : ((k == 64) ? false : ((lane & k) == 0));
;             const int oi = __shfl_xor(myi1, j); const float og = __shfl_xor(myg1, j);
;             const bool take = (lower == up) ? (oi < myi1) : (oi > myi1);
;             myi1 = take ? oi : myi1; myg1 = take ? og : myg1;
;           }
;         }
;       }
;     }
; }
	s_mov_b32 s88, 0xcccc3333
	s_mov_b32 s89, 0xcccc3333
	v_min_u32_e32 v104, v241, v0
	v_max_u32_e32 v105, v241, v0
	v_cndmask_b32_e64 v241, v105, v104, s[88:89]
	v_min_u32_e32 v106, v243, v1
	v_max_u32_e32 v107, v243, v1
	v_cndmask_b32_e64 v243, v107, v106, s[88:89]
	v_min_u32_e32 v104, v245, v2
	v_max_u32_e32 v105, v245, v2
	v_cndmask_b32_e64 v245, v105, v104, s[88:89]
	v_min_u32_e32 v106, v247, v3
	v_max_u32_e32 v107, v247, v3
	v_cndmask_b32_e64 v247, v107, v106, s[88:89]
	v_min_u32_e32 v104, v242, v4
	v_max_u32_e32 v105, v242, v4
	v_cndmask_b32_e64 v242, v105, v104, s[88:89]
	v_min_u32_e32 v106, v244, v5
	v_max_u32_e32 v107, v244, v5
	v_cndmask_b32_e64 v244, v107, v106, s[88:89]
	v_min_u32_e32 v104, v246, v6
	v_max_u32_e32 v105, v246, v6
	v_cndmask_b32_e64 v246, v105, v104, s[88:89]
	v_min_u32_e32 v106, v248, v7
	v_max_u32_e32 v107, v248, v7
	v_cndmask_b32_e64 v248, v107, v106, s[88:89]
	v_xor_b32_e32 v116, 4, v234
	ds_bpermute_b32 v0, v116, v241
	ds_bpermute_b32 v1, v116, v243
	ds_bpermute_b32 v2, v116, v245
	ds_bpermute_b32 v3, v116, v247
	ds_bpermute_b32 v4, v116, v242
	ds_bpermute_b32 v5, v116, v244
	ds_bpermute_b32 v6, v116, v246
	ds_bpermute_b32 v7, v116, v248
	s_waitcnt lgkmcnt(0)
	s_mov_b32 s88, 0xaaaa5555
	s_mov_b32 s89, 0xaaaa5555
	v_min_u32_e32 v104, v241, v0
	v_max_u32_e32 v105, v241, v0
	v_cndmask_b32_e64 v241, v105, v104, s[88:89]
	v_min_u32_e32 v106, v243, v1
	v_max_u32_e32 v107, v243, v1
	v_cndmask_b32_e64 v243, v107, v106, s[88:89]
	v_min_u32_e32 v104, v245, v2
	v_max_u32_e32 v105, v245, v2
	v_cndmask_b32_e64 v245, v105, v104, s[88:89]
	v_min_u32_e32 v106, v247, v3
	v_max_u32_e32 v107, v247, v3
	v_cndmask_b32_e64 v247, v107, v106, s[88:89]
	v_min_u32_e32 v104, v242, v4
	v_max_u32_e32 v105, v242, v4
	v_cndmask_b32_e64 v242, v105, v104, s[88:89]
	v_min_u32_e32 v106, v244, v5
	v_max_u32_e32 v107, v244, v5
	v_cndmask_b32_e64 v244, v107, v106, s[88:89]
	v_min_u32_e32 v104, v246, v6
	v_max_u32_e32 v105, v246, v6
	v_cndmask_b32_e64 v246, v105, v104, s[88:89]
	v_min_u32_e32 v106, v248, v7
	v_max_u32_e32 v107, v248, v7
	v_cndmask_b32_e64 v248, v107, v106, s[88:89]
	v_xor_b32_e32 v116, 64, v234
	ds_bpermute_b32 v0, v116, v241
	ds_bpermute_b32 v1, v116, v243
	ds_bpermute_b32 v2, v116, v245
	ds_bpermute_b32 v3, v116, v247
	ds_bpermute_b32 v4, v116, v242
	ds_bpermute_b32 v5, v116, v244
	ds_bpermute_b32 v6, v116, v246
	ds_bpermute_b32 v7, v116, v248
	s_waitcnt lgkmcnt(0)
	s_mov_b32 s88, 0xffff
	s_mov_b32 s89, 0xffff0000
	v_min_u32_e32 v104, v241, v0
	v_max_u32_e32 v105, v241, v0
	v_cndmask_b32_e64 v241, v105, v104, s[88:89]
	v_min_u32_e32 v106, v243, v1
	v_max_u32_e32 v107, v243, v1
	v_cndmask_b32_e64 v243, v107, v106, s[88:89]
	v_min_u32_e32 v104, v245, v2
	v_max_u32_e32 v105, v245, v2
	v_cndmask_b32_e64 v245, v105, v104, s[88:89]
	v_min_u32_e32 v106, v247, v3
	v_max_u32_e32 v107, v247, v3
	v_cndmask_b32_e64 v247, v107, v106, s[88:89]
	v_min_u32_e32 v104, v242, v4
	v_max_u32_e32 v105, v242, v4
	v_cndmask_b32_e64 v242, v105, v104, s[88:89]
	v_min_u32_e32 v106, v244, v5
	v_max_u32_e32 v107, v244, v5
	v_cndmask_b32_e64 v244, v107, v106, s[88:89]
	v_min_u32_e32 v104, v246, v6
	v_max_u32_e32 v105, v246, v6
	v_cndmask_b32_e64 v246, v105, v104, s[88:89]
	v_min_u32_e32 v106, v248, v7
	v_max_u32_e32 v107, v248, v7
	v_cndmask_b32_e64 v248, v107, v106, s[88:89]
	v_xor_b32_e32 v116, 32, v234
	ds_bpermute_b32 v0, v116, v241
	ds_bpermute_b32 v1, v116, v243
	ds_bpermute_b32 v2, v116, v245
	ds_bpermute_b32 v3, v116, v247
	ds_bpermute_b32 v4, v116, v242
	ds_bpermute_b32 v5, v116, v244
	ds_bpermute_b32 v6, v116, v246
	ds_bpermute_b32 v7, v116, v248
	s_waitcnt lgkmcnt(0)
	s_mov_b32 s88, 0xff00ff
	s_mov_b32 s89, 0xff00ff00
	v_min_u32_e32 v104, v241, v0
	v_max_u32_e32 v105, v241, v0
	v_cndmask_b32_e64 v241, v105, v104, s[88:89]
	v_min_u32_e32 v106, v243, v1
	v_max_u32_e32 v107, v243, v1
	v_cndmask_b32_e64 v243, v107, v106, s[88:89]
	v_min_u32_e32 v104, v245, v2
	v_max_u32_e32 v105, v245, v2
	v_cndmask_b32_e64 v245, v105, v104, s[88:89]
	v_min_u32_e32 v106, v247, v3
	v_max_u32_e32 v107, v247, v3
	v_cndmask_b32_e64 v247, v107, v106, s[88:89]
	v_min_u32_e32 v104, v242, v4
	v_max_u32_e32 v105, v242, v4
	v_cndmask_b32_e64 v242, v105, v104, s[88:89]
	v_min_u32_e32 v106, v244, v5
	v_max_u32_e32 v107, v244, v5
	v_cndmask_b32_e64 v244, v107, v106, s[88:89]
	v_min_u32_e32 v104, v246, v6
	v_max_u32_e32 v105, v246, v6
	v_cndmask_b32_e64 v246, v105, v104, s[88:89]
	v_min_u32_e32 v106, v248, v7
	v_max_u32_e32 v107, v248, v7
	v_cndmask_b32_e64 v248, v107, v106, s[88:89]
	v_xor_b32_e32 v116, 16, v234
	ds_bpermute_b32 v0, v116, v241
	ds_bpermute_b32 v1, v116, v243
	ds_bpermute_b32 v2, v116, v245
	ds_bpermute_b32 v3, v116, v247
	ds_bpermute_b32 v4, v116, v242
	ds_bpermute_b32 v5, v116, v244
	ds_bpermute_b32 v6, v116, v246
	ds_bpermute_b32 v7, v116, v248
	s_waitcnt lgkmcnt(0)
	s_mov_b32 s88, 0xf0f0f0f
	s_mov_b32 s89, 0xf0f0f0f0
	v_min_u32_e32 v104, v241, v0
	v_max_u32_e32 v105, v241, v0
	v_cndmask_b32_e64 v241, v105, v104, s[88:89]
	v_min_u32_e32 v106, v243, v1
	v_max_u32_e32 v107, v243, v1
	v_cndmask_b32_e64 v243, v107, v106, s[88:89]
	v_min_u32_e32 v104, v245, v2
	v_max_u32_e32 v105, v245, v2
	v_cndmask_b32_e64 v245, v105, v104, s[88:89]
	v_min_u32_e32 v106, v247, v3
	v_max_u32_e32 v107, v247, v3
	v_cndmask_b32_e64 v247, v107, v106, s[88:89]
	v_min_u32_e32 v104, v242, v4
	v_max_u32_e32 v105, v242, v4
	v_cndmask_b32_e64 v242, v105, v104, s[88:89]
	v_min_u32_e32 v106, v244, v5
	v_max_u32_e32 v107, v244, v5
	v_cndmask_b32_e64 v244, v107, v106, s[88:89]
	v_min_u32_e32 v104, v246, v6
	v_max_u32_e32 v105, v246, v6
	v_cndmask_b32_e64 v246, v105, v104, s[88:89]
	v_min_u32_e32 v106, v248, v7
	v_max_u32_e32 v107, v248, v7
	v_cndmask_b32_e64 v248, v107, v106, s[88:89]
	v_xor_b32_e32 v116, 8, v234
	ds_bpermute_b32 v0, v116, v241
	ds_bpermute_b32 v1, v116, v243
	ds_bpermute_b32 v2, v116, v245
	ds_bpermute_b32 v3, v116, v247
	ds_bpermute_b32 v4, v116, v242
	ds_bpermute_b32 v5, v116, v244
	ds_bpermute_b32 v6, v116, v246
	ds_bpermute_b32 v7, v116, v248
	s_waitcnt lgkmcnt(0)
; DEV void sort_lists(int lane, int& myi0, int& myi1, float& myg0, float& myg1) {
; #pragma unroll
;     for (int k = 2; k <= 128; k <<= 1) {
; #pragma unroll
;       for (int j = k >> 1; j >= 1; j >>= 1) {
;         if (j == 64) {
;           const bool sw_ = myi1 < myi0;
;           const int ti = sw_ ? myi1 : myi0, tj = sw_ ? myi0 : myi1; const float tg = sw_ ? myg1 : myg0, th = sw_ ? myg0 : myg1;
;           myi0 = ti; myi1 = tj; myg0 = tg; myg1 = th;
;         } else {
;           const bool lower = (lane & j) == 0;
;           {
;             const bool up = (k == 128) ? true : ((k == 64) ? true : ((lane & k) == 0));
;             const int oi = __shfl_xor(myi0, j); const float og = __shfl_xor(myg0, j);
;             const bool take = (lower == up) ? (oi < myi0) : (oi > myi0);
;             myi0 = take ? oi : myi0; myg0 = take ? og : myg0;
;           }
;           {
;             const bool up = (k == 128) ? true : ((k == 64) ? false : ((lane & k) == 0));
;             const int oi = __shfl_xor(myi1, j); const float og = __shfl_xor(myg1, j);
;             const bool take = (lower == up) ? (oi < myi1) : (oi > myi1);
;             myi1 = take ? oi : myi1; myg1 = take ? og : myg1;
;           }
;         }
;       }
;     }
; }
	s_mov_b32 s88, 0x33333333
	s_mov_b32 s89, 0xcccccccc
	v_min_u32_e32 v104, v241, v0
	v_max_u32_e32 v105, v241, v0
	v_cndmask_b32_e64 v241, v105, v104, s[88:89]
	v_min_u32_e32 v106, v243, v1
	v_max_u32_e32 v107, v243, v1
	v_cndmask_b32_e64 v243, v107, v106, s[88:89]
	v_min_u32_e32 v104, v245, v2
	v_max_u32_e32 v105, v245, v2
	v_cndmask_b32_e64 v245, v105, v104, s[88:89]
	v_min_u32_e32 v106, v247, v3
	v_max_u32_e32 v107, v247, v3
	v_cndmask_b32_e64 v247, v107, v106, s[88:89]
	v_min_u32_e32 v104, v242, v4
	v_max_u32_e32 v105, v242, v4
	v_cndmask_b32_e64 v242, v105, v104, s[88:89]
	v_min_u32_e32 v106, v244, v5
	v_max_u32_e32 v107, v244, v5
	v_cndmask_b32_e64 v244, v107, v106, s[88:89]
	v_min_u32_e32 v104, v246, v6
	v_max_u32_e32 v105, v246, v6
	v_cndmask_b32_e64 v246, v105, v104, s[88:89]
	v_min_u32_e32 v106, v248, v7
	v_max_u32_e32 v107, v248, v7
	v_cndmask_b32_e64 v248, v107, v106, s[88:89]
	v_xor_b32_e32 v116, 4, v234
	ds_bpermute_b32 v0, v116, v241
	ds_bpermute_b32 v1, v116, v243
	ds_bpermute_b32 v2, v116, v245
	ds_bpermute_b32 v3, v116, v247
	ds_bpermute_b32 v4, v116, v242
	ds_bpermute_b32 v5, v116, v244
	ds_bpermute_b32 v6, v116, v246
	ds_bpermute_b32 v7, v116, v248
	s_waitcnt lgkmcnt(0)
	s_mov_b32 s88, 0x55555555
	s_mov_b32 s89, 0xaaaaaaaa
	v_min_u32_e32 v104, v241, v0
	v_max_u32_e32 v105, v241, v0
	v_cndmask_b32_e64 v241, v105, v104, s[88:89]
	v_min_u32_e32 v106, v243, v1
	v_max_u32_e32 v107, v243, v1
	v_cndmask_b32_e64 v243, v107, v106, s[88:89]
	v_min_u32_e32 v104, v245, v2
	v_max_u32_e32 v105, v245, v2
	v_cndmask_b32_e64 v245, v105, v104, s[88:89]
	v_min_u32_e32 v106, v247, v3
	v_max_u32_e32 v107, v247, v3
	v_cndmask_b32_e64 v247, v107, v106, s[88:89]
	v_min_u32_e32 v104, v242, v4
	v_max_u32_e32 v105, v242, v4
	v_cndmask_b32_e64 v242, v105, v104, s[88:89]
	v_min_u32_e32 v106, v244, v5
	v_max_u32_e32 v107, v244, v5
	v_cndmask_b32_e64 v244, v107, v106, s[88:89]
	v_min_u32_e32 v104, v246, v6
	v_max_u32_e32 v105, v246, v6
	v_cndmask_b32_e64 v246, v105, v104, s[88:89]
	v_min_u32_e32 v106, v248, v7
	v_max_u32_e32 v107, v248, v7
	v_cndmask_b32_e64 v248, v107, v106, s[88:89]
	v_xor_b32_e32 v116, 128, v234
	ds_bpermute_b32 v0, v116, v241
	ds_bpermute_b32 v1, v116, v243
	ds_bpermute_b32 v2, v116, v245
	ds_bpermute_b32 v3, v116, v247
	ds_bpermute_b32 v4, v116, v242
	ds_bpermute_b32 v5, v116, v244
	ds_bpermute_b32 v6, v116, v246
	ds_bpermute_b32 v7, v116, v248
	s_waitcnt lgkmcnt(0)
	s_mov_b32 s88, 0xffffffff
	s_mov_b32 s89, 0x0
	v_min_u32_e32 v104, v241, v0
	v_max_u32_e32 v105, v241, v0
	v_cndmask_b32_e64 v241, v105, v104, s[88:89]
	v_min_u32_e32 v106, v243, v1
	v_max_u32_e32 v107, v243, v1
	v_cndmask_b32_e64 v243, v107, v106, s[88:89]
	v_min_u32_e32 v104, v245, v2
	v_max_u32_e32 v105, v245, v2
	v_cndmask_b32_e64 v245, v105, v104, s[88:89]
	v_min_u32_e32 v106, v247, v3
	v_max_u32_e32 v107, v247, v3
	v_cndmask_b32_e64 v247, v107, v106, s[88:89]
	s_mov_b32 s88, 0x0
	s_mov_b32 s89, 0xffffffff
	v_min_u32_e32 v104, v242, v4
	v_max_u32_e32 v105, v242, v4
	v_cndmask_b32_e64 v242, v105, v104, s[88:89]
	v_min_u32_e32 v106, v244, v5
	v_max_u32_e32 v107, v244, v5
	v_cndmask_b32_e64 v244, v107, v106, s[88:89]
	v_min_u32_e32 v104, v246, v6
	v_max_u32_e32 v105, v246, v6
	v_cndmask_b32_e64 v246, v105, v104, s[88:89]
	v_min_u32_e32 v106, v248, v7
	v_max_u32_e32 v107, v248, v7
	v_cndmask_b32_e64 v248, v107, v106, s[88:89]
	v_xor_b32_e32 v116, 64, v234
	ds_bpermute_b32 v0, v116, v241
	ds_bpermute_b32 v1, v116, v243
	ds_bpermute_b32 v2, v116, v245
	ds_bpermute_b32 v3, v116, v247
	ds_bpermute_b32 v4, v116, v242
	ds_bpermute_b32 v5, v116, v244
	ds_bpermute_b32 v6, v116, v246
	ds_bpermute_b32 v7, v116, v248
	s_waitcnt lgkmcnt(0)
	s_mov_b32 s88, 0xffff
	s_mov_b32 s89, 0xffff
	v_min_u32_e32 v104, v241, v0
	v_max_u32_e32 v105, v241, v0
	v_cndmask_b32_e64 v241, v105, v104, s[88:89]
	v_min_u32_e32 v106, v243, v1
	v_max_u32_e32 v107, v243, v1
	v_cndmask_b32_e64 v243, v107, v106, s[88:89]
	v_min_u32_e32 v104, v245, v2
	v_max_u32_e32 v105, v245, v2
	v_cndmask_b32_e64 v245, v105, v104, s[88:89]
	v_min_u32_e32 v106, v247, v3
	v_max_u32_e32 v107, v247, v3
	v_cndmask_b32_e64 v247, v107, v106, s[88:89]
	s_mov_b32 s88, 0xffff0000
	s_mov_b32 s89, 0xffff0000
	v_min_u32_e32 v104, v242, v4
	v_max_u32_e32 v105, v242, v4
	v_cndmask_b32_e64 v242, v105, v104, s[88:89]
	v_min_u32_e32 v106, v244, v5
	v_max_u32_e32 v107, v244, v5
	v_cndmask_b32_e64 v244, v107, v106, s[88:89]
	v_min_u32_e32 v104, v246, v6
	v_max_u32_e32 v105, v246, v6
	v_cndmask_b32_e64 v246, v105, v104, s[88:89]
	v_min_u32_e32 v106, v248, v7
	v_max_u32_e32 v107, v248, v7
	v_cndmask_b32_e64 v248, v107, v106, s[88:89]
	v_xor_b32_e32 v116, 32, v234
	ds_bpermute_b32 v0, v116, v241
	ds_bpermute_b32 v1, v116, v243
	ds_bpermute_b32 v2, v116, v245
	ds_bpermute_b32 v3, v116, v247
	ds_bpermute_b32 v4, v116, v242
	ds_bpermute_b32 v5, v116, v244
	ds_bpermute_b32 v6, v116, v246
	ds_bpermute_b32 v7, v116, v248
	s_waitcnt lgkmcnt(0)
	s_mov_b32 s88, 0xff00ff
	s_mov_b32 s89, 0xff00ff
	v_min_u32_e32 v104, v241, v0
	v_max_u32_e32 v105, v241, v0
	v_cndmask_b32_e64 v241, v105, v104, s[88:89]
	v_min_u32_e32 v106, v243, v1
	v_max_u32_e32 v107, v243, v1
	v_cndmask_b32_e64 v243, v107, v106, s[88:89]
	v_min_u32_e32 v104, v245, v2
	v_max_u32_e32 v105, v245, v2
	v_cndmask_b32_e64 v245, v105, v104, s[88:89]
	v_min_u32_e32 v106, v247, v3
	v_max_u32_e32 v107, v247, v3
	v_cndmask_b32_e64 v247, v107, v106, s[88:89]
	s_mov_b32 s88, 0xff00ff00
	s_mov_b32 s89, 0xff00ff00
	v_min_u32_e32 v104, v242, v4
	v_max_u32_e32 v105, v242, v4
	v_cndmask_b32_e64 v242, v105, v104, s[88:89]
	v_min_u32_e32 v106, v244, v5
	v_max_u32_e32 v107, v244, v5
	v_cndmask_b32_e64 v244, v107, v106, s[88:89]
	v_min_u32_e32 v104, v246, v6
	v_max_u32_e32 v105, v246, v6
	v_cndmask_b32_e64 v246, v105, v104, s[88:89]
	v_min_u32_e32 v106, v248, v7
	v_max_u32_e32 v107, v248, v7
	v_cndmask_b32_e64 v248, v107, v106, s[88:89]
	v_xor_b32_e32 v116, 16, v234
	ds_bpermute_b32 v0, v116, v241
	ds_bpermute_b32 v1, v116, v243
	ds_bpermute_b32 v2, v116, v245
	ds_bpermute_b32 v3, v116, v247
	ds_bpermute_b32 v4, v116, v242
	ds_bpermute_b32 v5, v116, v244
	ds_bpermute_b32 v6, v116, v246
	ds_bpermute_b32 v7, v116, v248
	s_waitcnt lgkmcnt(0)
; DEV void sort_lists(int lane, int& myi0, int& myi1, float& myg0, float& myg1) {
; #pragma unroll
;     for (int k = 2; k <= 128; k <<= 1) {
; #pragma unroll
;       for (int j = k >> 1; j >= 1; j >>= 1) {
;         if (j == 64) {
;           const bool sw_ = myi1 < myi0;
;           const int ti = sw_ ? myi1 : myi0, tj = sw_ ? myi0 : myi1; const float tg = sw_ ? myg1 : myg0, th = sw_ ? myg0 : myg1;
;           myi0 = ti; myi1 = tj; myg0 = tg; myg1 = th;
;         } else {
;           const bool lower = (lane & j) == 0;
;           {
;             const bool up = (k == 128) ? true : ((k == 64) ? true : ((lane & k) == 0));
;             const int oi = __shfl_xor(myi0, j); const float og = __shfl_xor(myg0, j);
;             const bool take = (lower == up) ? (oi < myi0) : (oi > myi0);
;             myi0 = take ? oi : myi0; myg0 = take ? og : myg0;
;           }
;           {
;             const bool up = (k == 128) ? true : ((k == 64) ? false : ((lane & k) == 0));
;             const int oi = __shfl_xor(myi1, j); const float og = __shfl_xor(myg1, j);
;             const bool take = (lower == up) ? (oi < myi1) : (oi > myi1);
;             myi1 = take ? oi : myi1; myg1 = take ? og : myg1;
;           }
;         }
;       }
;     }
; }
	s_mov_b32 s88, 0xf0f0f0f
	s_mov_b32 s89, 0xf0f0f0f
	v_min_u32_e32 v104, v241, v0
	v_max_u32_e32 v105, v241, v0
	v_cndmask_b32_e64 v241, v105, v104, s[88:89]
	v_min_u32_e32 v106, v243, v1
	v_max_u32_e32 v107, v243, v1
	v_cndmask_b32_e64 v243, v107, v106, s[88:89]
	v_min_u32_e32 v104, v245, v2
	v_max_u32_e32 v105, v245, v2
	v_cndmask_b32_e64 v245, v105, v104, s[88:89]
	v_min_u32_e32 v106, v247, v3
	v_max_u32_e32 v107, v247, v3
	v_cndmask_b32_e64 v247, v107, v106, s[88:89]
	s_mov_b32 s88, 0xf0f0f0f0
	s_mov_b32 s89, 0xf0f0f0f0
	v_min_u32_e32 v104, v242, v4
	v_max_u32_e32 v105, v242, v4
	v_cndmask_b32_e64 v242, v105, v104, s[88:89]
	v_min_u32_e32 v106, v244, v5
	v_max_u32_e32 v107, v244, v5
	v_cndmask_b32_e64 v244, v107, v106, s[88:89]
	v_min_u32_e32 v104, v246, v6
	v_max_u32_e32 v105, v246, v6
	v_cndmask_b32_e64 v246, v105, v104, s[88:89]
	v_min_u32_e32 v106, v248, v7
	v_max_u32_e32 v107, v248, v7
	v_cndmask_b32_e64 v248, v107, v106, s[88:89]
	v_xor_b32_e32 v116, 8, v234
	ds_bpermute_b32 v0, v116, v241
	ds_bpermute_b32 v1, v116, v243
	ds_bpermute_b32 v2, v116, v245
	ds_bpermute_b32 v3, v116, v247
	ds_bpermute_b32 v4, v116, v242
	ds_bpermute_b32 v5, v116, v244
	ds_bpermute_b32 v6, v116, v246
	ds_bpermute_b32 v7, v116, v248
	s_waitcnt lgkmcnt(0)
	s_mov_b32 s88, 0x33333333
	s_mov_b32 s89, 0x33333333
	v_min_u32_e32 v104, v241, v0
	v_max_u32_e32 v105, v241, v0
	v_cndmask_b32_e64 v241, v105, v104, s[88:89]
	v_min_u32_e32 v106, v243, v1
	v_max_u32_e32 v107, v243, v1
	v_cndmask_b32_e64 v243, v107, v106, s[88:89]
	v_min_u32_e32 v104, v245, v2
	v_max_u32_e32 v105, v245, v2
	v_cndmask_b32_e64 v245, v105, v104, s[88:89]
	v_min_u32_e32 v106, v247, v3
	v_max_u32_e32 v107, v247, v3
	v_cndmask_b32_e64 v247, v107, v106, s[88:89]
	s_mov_b32 s88, 0xcccccccc
	s_mov_b32 s89, 0xcccccccc
	v_min_u32_e32 v104, v242, v4
	v_max_u32_e32 v105, v242, v4
	v_cndmask_b32_e64 v242, v105, v104, s[88:89]
	v_min_u32_e32 v106, v244, v5
	v_max_u32_e32 v107, v244, v5
	v_cndmask_b32_e64 v244, v107, v106, s[88:89]
	v_min_u32_e32 v104, v246, v6
	v_max_u32_e32 v105, v246, v6
	v_cndmask_b32_e64 v246, v105, v104, s[88:89]
	v_min_u32_e32 v106, v248, v7
	v_max_u32_e32 v107, v248, v7
	v_cndmask_b32_e64 v248, v107, v106, s[88:89]
	v_xor_b32_e32 v116, 4, v234
	ds_bpermute_b32 v0, v116, v241
	ds_bpermute_b32 v1, v116, v243
	ds_bpermute_b32 v2, v116, v245
	ds_bpermute_b32 v3, v116, v247
	ds_bpermute_b32 v4, v116, v242
	ds_bpermute_b32 v5, v116, v244
	ds_bpermute_b32 v6, v116, v246
	ds_bpermute_b32 v7, v116, v248
	s_waitcnt lgkmcnt(0)
	s_mov_b32 s88, 0x55555555
	s_mov_b32 s89, 0x55555555
	v_min_u32_e32 v104, v241, v0
	v_max_u32_e32 v105, v241, v0
	v_cndmask_b32_e64 v241, v105, v104, s[88:89]
	v_min_u32_e32 v106, v243, v1
	v_max_u32_e32 v107, v243, v1
	v_cndmask_b32_e64 v243, v107, v106, s[88:89]
	v_min_u32_e32 v104, v245, v2
	v_max_u32_e32 v105, v245, v2
	v_cndmask_b32_e64 v245, v105, v104, s[88:89]
	v_min_u32_e32 v106, v247, v3
	v_max_u32_e32 v107, v247, v3
	v_cndmask_b32_e64 v247, v107, v106, s[88:89]
	s_mov_b32 s88, 0xaaaaaaaa
	s_mov_b32 s89, 0xaaaaaaaa
	v_min_u32_e32 v104, v242, v4
	v_max_u32_e32 v105, v242, v4
	v_cndmask_b32_e64 v242, v105, v104, s[88:89]
	v_min_u32_e32 v106, v244, v5
	v_max_u32_e32 v107, v244, v5
	v_cndmask_b32_e64 v244, v107, v106, s[88:89]
	v_min_u32_e32 v104, v246, v6
	v_max_u32_e32 v105, v246, v6
	v_cndmask_b32_e64 v246, v105, v104, s[88:89]
	v_min_u32_e32 v106, v248, v7
	v_max_u32_e32 v107, v248, v7
	v_cndmask_b32_e64 v248, v107, v106, s[88:89]
	v_min_u32_e32 v104, v241, v242
	v_max_u32_e32 v242, v241, v242
	v_mov_b32_e32 v241, v104
	v_min_u32_e32 v106, v243, v244
	v_max_u32_e32 v244, v243, v244
	v_mov_b32_e32 v243, v106
	v_min_u32_e32 v104, v245, v246
	v_max_u32_e32 v246, v245, v246
	v_mov_b32_e32 v245, v104
	v_min_u32_e32 v106, v247, v248
	v_max_u32_e32 v248, v247, v248
	v_mov_b32_e32 v247, v106
	v_xor_b32_e32 v116, 128, v234
	ds_bpermute_b32 v0, v116, v241
	ds_bpermute_b32 v1, v116, v243
	ds_bpermute_b32 v2, v116, v245
	ds_bpermute_b32 v3, v116, v247
	ds_bpermute_b32 v4, v116, v242
	ds_bpermute_b32 v5, v116, v244
	ds_bpermute_b32 v6, v116, v246
	ds_bpermute_b32 v7, v116, v248
	s_waitcnt lgkmcnt(0)
	s_mov_b32 s88, 0xffffffff
	s_mov_b32 s89, 0x0
	v_min_u32_e32 v104, v241, v0
	v_max_u32_e32 v105, v241, v0
	v_cndmask_b32_e64 v241, v105, v104, s[88:89]
	v_min_u32_e32 v106, v243, v1
	v_max_u32_e32 v107, v243, v1
	v_cndmask_b32_e64 v243, v107, v106, s[88:89]
	v_min_u32_e32 v104, v245, v2
	v_max_u32_e32 v105, v245, v2
	v_cndmask_b32_e64 v245, v105, v104, s[88:89]
	v_min_u32_e32 v106, v247, v3
	v_max_u32_e32 v107, v247, v3
	v_cndmask_b32_e64 v247, v107, v106, s[88:89]
	v_min_u32_e32 v104, v242, v4
	v_max_u32_e32 v105, v242, v4
	v_cndmask_b32_e64 v242, v105, v104, s[88:89]
	v_min_u32_e32 v106, v244, v5
	v_max_u32_e32 v107, v244, v5
	v_cndmask_b32_e64 v244, v107, v106, s[88:89]
	v_min_u32_e32 v104, v246, v6
	v_max_u32_e32 v105, v246, v6
	v_cndmask_b32_e64 v246, v105, v104, s[88:89]
	v_min_u32_e32 v106, v248, v7
	v_max_u32_e32 v107, v248, v7
	v_cndmask_b32_e64 v248, v107, v106, s[88:89]
	v_xor_b32_e32 v116, 64, v234
	ds_bpermute_b32 v0, v116, v241
	ds_bpermute_b32 v1, v116, v243
	ds_bpermute_b32 v2, v116, v245
	ds_bpermute_b32 v3, v116, v247
	ds_bpermute_b32 v4, v116, v242
	ds_bpermute_b32 v5, v116, v244
	ds_bpermute_b32 v6, v116, v246
	ds_bpermute_b32 v7, v116, v248
	s_waitcnt lgkmcnt(0)
; DEV void sort_lists(int lane, int& myi0, int& myi1, float& myg0, float& myg1) {
; #pragma unroll
;     for (int k = 2; k <= 128; k <<= 1) {
; #pragma unroll
;       for (int j = k >> 1; j >= 1; j >>= 1) {
;         if (j == 64) {
;           const bool sw_ = myi1 < myi0;
;           const int ti = sw_ ? myi1 : myi0, tj = sw_ ? myi0 : myi1; const float tg = sw_ ? myg1 : myg0, th = sw_ ? myg0 : myg1;
;           myi0 = ti; myi1 = tj; myg0 = tg; myg1 = th;
;         } else {
;           const bool lower = (lane & j) == 0;
;           {
;             const bool up = (k == 128) ? true : ((k == 64) ? true : ((lane & k) == 0));
;             const int oi = __shfl_xor(myi0, j); const float og = __shfl_xor(myg0, j);
;             const bool take = (lower == up) ? (oi < myi0) : (oi > myi0);
;             myi0 = take ? oi : myi0; myg0 = take ? og : myg0;
;           }
;           {
;             const bool up = (k == 128) ? true : ((k == 64) ? false : ((lane & k) == 0));
;             const int oi = __shfl_xor(myi1, j); const float og = __shfl_xor(myg1, j);
;             const bool take = (lower == up) ? (oi < myi1) : (oi > myi1);
;             myi1 = take ? oi : myi1; myg1 = take ? og : myg1;
;           }
;         }
;       }
;     }
; }
	s_mov_b32 s88, 0xffff
	s_mov_b32 s89, 0xffff
	v_min_u32_e32 v104, v241, v0
	v_max_u32_e32 v105, v241, v0
	v_cndmask_b32_e64 v241, v105, v104, s[88:89]
	v_min_u32_e32 v106, v243, v1
	v_max_u32_e32 v107, v243, v1
	v_cndmask_b32_e64 v243, v107, v106, s[88:89]
	v_min_u32_e32 v104, v245, v2
	v_max_u32_e32 v105, v245, v2
	v_cndmask_b32_e64 v245, v105, v104, s[88:89]
	v_min_u32_e32 v106, v247, v3
	v_max_u32_e32 v107, v247, v3
	v_cndmask_b32_e64 v247, v107, v106, s[88:89]
	v_min_u32_e32 v104, v242, v4
	v_max_u32_e32 v105, v242, v4
	v_cndmask_b32_e64 v242, v105, v104, s[88:89]
	v_min_u32_e32 v106, v244, v5
	v_max_u32_e32 v107, v244, v5
	v_cndmask_b32_e64 v244, v107, v106, s[88:89]
	v_min_u32_e32 v104, v246, v6
	v_max_u32_e32 v105, v246, v6
	v_cndmask_b32_e64 v246, v105, v104, s[88:89]
	v_min_u32_e32 v106, v248, v7
	v_max_u32_e32 v107, v248, v7
	v_cndmask_b32_e64 v248, v107, v106, s[88:89]
	v_xor_b32_e32 v116, 32, v234
	ds_bpermute_b32 v0, v116, v241
	ds_bpermute_b32 v1, v116, v243
	ds_bpermute_b32 v2, v116, v245
	ds_bpermute_b32 v3, v116, v247
	ds_bpermute_b32 v4, v116, v242
	ds_bpermute_b32 v5, v116, v244
	ds_bpermute_b32 v6, v116, v246
	ds_bpermute_b32 v7, v116, v248
	s_waitcnt lgkmcnt(0)
	s_mov_b32 s88, 0xff00ff
	s_mov_b32 s89, 0xff00ff
	v_min_u32_e32 v104, v241, v0
	v_max_u32_e32 v105, v241, v0
	v_cndmask_b32_e64 v241, v105, v104, s[88:89]
	v_min_u32_e32 v106, v243, v1
	v_max_u32_e32 v107, v243, v1
	v_cndmask_b32_e64 v243, v107, v106, s[88:89]
	v_min_u32_e32 v104, v245, v2
	v_max_u32_e32 v105, v245, v2
	v_cndmask_b32_e64 v245, v105, v104, s[88:89]
	v_min_u32_e32 v106, v247, v3
	v_max_u32_e32 v107, v247, v3
	v_cndmask_b32_e64 v247, v107, v106, s[88:89]
	v_min_u32_e32 v104, v242, v4
	v_max_u32_e32 v105, v242, v4
	v_cndmask_b32_e64 v242, v105, v104, s[88:89]
	v_min_u32_e32 v106, v244, v5
	v_max_u32_e32 v107, v244, v5
	v_cndmask_b32_e64 v244, v107, v106, s[88:89]
	v_min_u32_e32 v104, v246, v6
	v_max_u32_e32 v105, v246, v6
	v_cndmask_b32_e64 v246, v105, v104, s[88:89]
	v_min_u32_e32 v106, v248, v7
	v_max_u32_e32 v107, v248, v7
	v_cndmask_b32_e64 v248, v107, v106, s[88:89]
	v_xor_b32_e32 v116, 16, v234
	ds_bpermute_b32 v0, v116, v241
	ds_bpermute_b32 v1, v116, v243
	ds_bpermute_b32 v2, v116, v245
	ds_bpermute_b32 v3, v116, v247
	ds_bpermute_b32 v4, v116, v242
	ds_bpermute_b32 v5, v116, v244
	ds_bpermute_b32 v6, v116, v246
	ds_bpermute_b32 v7, v116, v248
	s_waitcnt lgkmcnt(0)
	s_mov_b32 s88, 0xf0f0f0f
	s_mov_b32 s89, 0xf0f0f0f
	v_min_u32_e32 v104, v241, v0
	v_max_u32_e32 v105, v241, v0
	v_cndmask_b32_e64 v241, v105, v104, s[88:89]
	v_min_u32_e32 v106, v243, v1
	v_max_u32_e32 v107, v243, v1
	v_cndmask_b32_e64 v243, v107, v106, s[88:89]
	v_min_u32_e32 v104, v245, v2
	v_max_u32_e32 v105, v245, v2
	v_cndmask_b32_e64 v245, v105, v104, s[88:89]
	v_min_u32_e32 v106, v247, v3
	v_max_u32_e32 v107, v247, v3
	v_cndmask_b32_e64 v247, v107, v106, s[88:89]
	v_min_u32_e32 v104, v242, v4
	v_max_u32_e32 v105, v242, v4
	v_cndmask_b32_e64 v242, v105, v104, s[88:89]
	v_min_u32_e32 v106, v244, v5
	v_max_u32_e32 v107, v244, v5
	v_cndmask_b32_e64 v244, v107, v106, s[88:89]
	v_min_u32_e32 v104, v246, v6
	v_max_u32_e32 v105, v246, v6
	v_cndmask_b32_e64 v246, v105, v104, s[88:89]
	v_min_u32_e32 v106, v248, v7
	v_max_u32_e32 v107, v248, v7
	v_cndmask_b32_e64 v248, v107, v106, s[88:89]
	v_xor_b32_e32 v116, 8, v234
	ds_bpermute_b32 v0, v116, v241
	ds_bpermute_b32 v1, v116, v243
	ds_bpermute_b32 v2, v116, v245
	ds_bpermute_b32 v3, v116, v247
	ds_bpermute_b32 v4, v116, v242
	ds_bpermute_b32 v5, v116, v244
	ds_bpermute_b32 v6, v116, v246
	ds_bpermute_b32 v7, v116, v248
	s_waitcnt lgkmcnt(0)
; DEV void sort_lists(int lane, int& myi0, int& myi1, float& myg0, float& myg1) {
; #pragma unroll
;     for (int k = 2; k <= 128; k <<= 1) {
; #pragma unroll
;       for (int j = k >> 1; j >= 1; j >>= 1) {
;         if (j == 64) {
;           const bool sw_ = myi1 < myi0;
;           const int ti = sw_ ? myi1 : myi0, tj = sw_ ? myi0 : myi1; const float tg = sw_ ? myg1 : myg0, th = sw_ ? myg0 : myg1;
;           myi0 = ti; myi1 = tj; myg0 = tg; myg1 = th;
;         } else {
;           const bool lower = (lane & j) == 0;
;           {
;             const bool up = (k == 128) ? true : ((k == 64) ? true : ((lane & k) == 0));
;             const int oi = __shfl_xor(myi0, j); const float og = __shfl_xor(myg0, j);
;             const bool take = (lower == up) ? (oi < myi0) : (oi > myi0);
;             myi0 = take ? oi : myi0; myg0 = take ? og : myg0;
;           }
;           {
;             const bool up = (k == 128) ? true : ((k == 64) ? false : ((lane & k) == 0));
;             const int oi = __shfl_xor(myi1, j); const float og = __shfl_xor(myg1, j);
;             const bool take = (lower == up) ? (oi < myi1) : (oi > myi1);
;             myi1 = take ? oi : myi1; myg1 = take ? og : myg1;
;           }
;         }
;       }
;     }
; }
; DEV void peer_gather(const Params& P, int l, int m0, const int* idxs, const float* gs) {
;     ...
;   int ni0 = idxs[(wid * 16) * 128 + lane], ni1 = idxs[(wid * 16) * 128 + 64 + lane];
;   float ng0 = gs[(wid * 16) * 128 + lane], ng1 = gs[(wid * 16) * 128 + 64 + lane];
;   sort_lists(lane, ni0, ni1, ng0, ng1);
	s_mov_b32 s88, 0x33333333
	s_mov_b32 s89, 0x33333333
	v_min_u32_e32 v104, v241, v0
	v_max_u32_e32 v105, v241, v0
	v_cndmask_b32_e64 v241, v105, v104, s[88:89]
	v_min_u32_e32 v106, v243, v1
	v_max_u32_e32 v107, v243, v1
	v_cndmask_b32_e64 v243, v107, v106, s[88:89]
	v_min_u32_e32 v104, v245, v2
	v_max_u32_e32 v105, v245, v2
	v_cndmask_b32_e64 v245, v105, v104, s[88:89]
	v_min_u32_e32 v106, v247, v3
	v_max_u32_e32 v107, v247, v3
	v_cndmask_b32_e64 v247, v107, v106, s[88:89]
	v_min_u32_e32 v104, v242, v4
	v_max_u32_e32 v105, v242, v4
	v_cndmask_b32_e64 v242, v105, v104, s[88:89]
	v_min_u32_e32 v106, v244, v5
	v_max_u32_e32 v107, v244, v5
	v_cndmask_b32_e64 v244, v107, v106, s[88:89]
	v_min_u32_e32 v104, v246, v6
	v_max_u32_e32 v105, v246, v6
	v_cndmask_b32_e64 v246, v105, v104, s[88:89]
	v_min_u32_e32 v106, v248, v7
	v_max_u32_e32 v107, v248, v7
	v_cndmask_b32_e64 v248, v107, v106, s[88:89]
	v_xor_b32_e32 v116, 4, v234
	ds_bpermute_b32 v0, v116, v241
	ds_bpermute_b32 v1, v116, v243
	ds_bpermute_b32 v2, v116, v245
	ds_bpermute_b32 v3, v116, v247
	ds_bpermute_b32 v4, v116, v242
	ds_bpermute_b32 v5, v116, v244
	ds_bpermute_b32 v6, v116, v246
	ds_bpermute_b32 v7, v116, v248
	s_waitcnt lgkmcnt(0)
	s_mov_b32 s88, 0x55555555
	s_mov_b32 s89, 0x55555555
	v_min_u32_e32 v104, v241, v0
	v_max_u32_e32 v105, v241, v0
	v_cndmask_b32_e64 v241, v105, v104, s[88:89]
	v_min_u32_e32 v106, v243, v1
	v_max_u32_e32 v107, v243, v1
	v_cndmask_b32_e64 v243, v107, v106, s[88:89]
	v_min_u32_e32 v104, v245, v2
	v_max_u32_e32 v105, v245, v2
	v_cndmask_b32_e64 v245, v105, v104, s[88:89]
	v_min_u32_e32 v106, v247, v3
	v_max_u32_e32 v107, v247, v3
	v_cndmask_b32_e64 v247, v107, v106, s[88:89]
	v_min_u32_e32 v104, v242, v4
	v_max_u32_e32 v105, v242, v4
	v_cndmask_b32_e64 v242, v105, v104, s[88:89]
	v_min_u32_e32 v106, v244, v5
	v_max_u32_e32 v107, v244, v5
	v_cndmask_b32_e64 v244, v107, v106, s[88:89]
	v_min_u32_e32 v104, v246, v6
	v_max_u32_e32 v105, v246, v6
	v_cndmask_b32_e64 v246, v105, v104, s[88:89]
	v_min_u32_e32 v106, v248, v7
	v_max_u32_e32 v107, v248, v7
	v_cndmask_b32_e64 v248, v107, v106, s[88:89]
	v_mov_b32_e32 v117, 0
	s_lshl_b32 s98, s2, 11
	s_add_u32 s98, s98, s101
	v_add_u32_e32 v116, s98, v234
	v_and_b32_e32 v144, 0x7f, v241
	v_and_b32_e32 v241, 0xffffff80, v241
	v_lshl_or_b32 v241, v241, 3, v144
	ds_write_b32 v116, v241 offset:0
	v_and_b32_e32 v145, 0x7f, v242
	v_and_b32_e32 v242, 0xffffff80, v242
	v_lshl_or_b32 v242, v242, 3, v145
	ds_write_b32 v116, v242 offset:256
	v_and_b32_e32 v146, 0x7f, v243
	v_and_b32_e32 v243, 0xffffff80, v243
	v_lshl_or_b32 v243, v243, 3, v146
	ds_write_b32 v116, v243 offset:512
	v_and_b32_e32 v147, 0x7f, v244
	v_and_b32_e32 v244, 0xffffff80, v244
	v_lshl_or_b32 v244, v244, 3, v147
	ds_write_b32 v116, v244 offset:768
	v_and_b32_e32 v148, 0x7f, v245
	v_and_b32_e32 v245, 0xffffff80, v245
	v_lshl_or_b32 v245, v245, 3, v148
	ds_write_b32 v116, v245 offset:1024
	v_and_b32_e32 v149, 0x7f, v246
	v_and_b32_e32 v246, 0xffffff80, v246
	v_lshl_or_b32 v246, v246, 3, v149
	ds_write_b32 v116, v246 offset:1280
	v_and_b32_e32 v150, 0x7f, v247
	v_and_b32_e32 v247, 0xffffff80, v247
	v_lshl_or_b32 v247, v247, 3, v150
	ds_write_b32 v116, v247 offset:1536
	v_and_b32_e32 v151, 0x7f, v248
	v_and_b32_e32 v248, 0xffffff80, v248
	v_lshl_or_b32 v248, v248, 3, v151
	ds_write_b32 v116, v248 offset:1792
	v_add_u32_e32 v118, 0x10000, v116
	ds_write_b32 v118, v117 offset:0
	ds_write_b32 v118, v117 offset:256
	ds_write_b32 v118, v117 offset:512
	ds_write_b32 v118, v117 offset:768
	ds_write_b32 v118, v117 offset:1024
	ds_write_b32 v118, v117 offset:1280
	ds_write_b32 v118, v117 offset:1536
	ds_write_b32 v118, v117 offset:1792
	s_add_u32 s2, s2, 1
	s_cmp_lt_u32 s2, 4
	s_cbranch_scc1 .Lpg1_p0
	s_waitcnt lgkmcnt(0)
	v_readfirstlane_b32 s80, v126
	v_readfirstlane_b32 s81, v127
	s_nop 4
	s_waitcnt vmcnt(0) lgkmcnt(0)
	s_barrier
	v_readfirstlane_b32 s98, v176
	s_cmp_lt_u32 s98, 64
	s_cbranch_scc0 .Lpg1_sk1
	v_readfirstlane_b32 s82, v124
	v_readfirstlane_b32 s83, v125
	s_nop 4
	s_add_u32 s82, s82, 0x123800
	s_addc_u32 s83, s83, 0
	s_getreg_b32 s99, hwreg(HW_REG_XCC_ID, 0, 4)
	s_lshl_b32 s99, s99, 6
	v_mov_b32_e32 v144, s99
	v_mov_b32_e32 v145, 1
	v_mov_b32_e32 v146, 0x27fc0
	s_mov_b64 exec, 1
	ds_read_b32 v147, v146
	global_atomic_add v144, v145, s[82:83]
	s_waitcnt lgkmcnt(0)
	v_readfirstlane_b32 s92, v147
	s_mul_i32 s92, s92, 3
	s_mov_b32 s93, 0

; DEV float bflo(unsigned u) { return __uint_as_float(u << 16); }
; DEV float bfhi(unsigned u) { return __uint_as_float(u & 0xffff0000u); }
; DEV void peer_gather(const Params& P, int l, int m0, const int* idxs, const float* gs) {
;     ...
;     const u32x4 xa = nxa, xb = nxb;
;     f32x2_t xp[8];
; #pragma unroll
;     for (int q = 0; q < 4; ++q) { xp[q] = (f32x2_t){bflo(xa[q]), bfhi(xa[q])}; xp[4 + q] = (f32x2_t){bflo(xb[q]), bfhi(xb[q])}; }
.Lpg1_sk1:
	s_barrier
	s_mov_b32 s90, 0xfffffc00
	s_mov_b32 s100, 0
	s_mov_b32 s98, 0
	s_mov_b32 s99, 0
	v_readfirstlane_b32 s82, v122
	v_readfirstlane_b32 s83, v123
	s_nop 4
	s_add_u32 vcc_lo, s3, s98
	s_lshl_b32 vcc_lo, vcc_lo, 11
	s_lshl_b32 vcc_hi, s99, 8
	s_add_u32 vcc_lo, vcc_lo, vcc_hi
	v_add_u32_e32 v119, vcc_lo, v236
	global_load_dwordx4 v[80:83], v119, s[82:83]
	global_load_dwordx4 v[84:87], v119, s[82:83] offset:16
	s_lshl_b32 vcc_lo, s98, 9
	s_add_u32 vcc_lo, vcc_lo, s101
	v_add_u32_e32 v116, vcc_lo, v234
	ds_read_b32 v134, v116
	ds_read_b32 v135, v116 offset:256
	s_lshl_b32 vcc_lo, s99, 7
	v_add_u32_e32 v240, vcc_lo, v235
	s_waitcnt lgkmcnt(0)
	ds_bpermute_b32 v142, v249, v134
	ds_bpermute_b32 v143, v250, v134
	s_waitcnt lgkmcnt(0)
	v_and_or_b32 v142, v142, s90, v240
	v_and_or_b32 v143, v143, s90, v240
	global_load_dwordx4 v[0:3], v142, s[80:81]
	global_load_dwordx4 v[4:7], v143, s[80:81]
	ds_bpermute_b32 v142, v251, v134
	ds_bpermute_b32 v143, v252, v134
	s_waitcnt lgkmcnt(0)
	v_and_or_b32 v142, v142, s90, v240
	v_and_or_b32 v143, v143, s90, v240
	global_load_dwordx4 v[8:11], v142, s[80:81]
	global_load_dwordx4 v[12:15], v143, s[80:81]
	ds_bpermute_b32 v142, v253, v134
	ds_bpermute_b32 v143, v254, v134
	s_waitcnt lgkmcnt(0)
	v_and_or_b32 v142, v142, s90, v240
	v_and_or_b32 v143, v143, s90, v240
	global_load_dwordx4 v[16:19], v142, s[80:81]
	global_load_dwordx4 v[20:23], v143, s[80:81]
	ds_bpermute_b32 v142, v255, v134
	ds_bpermute_b32 v143, v153, v134
	s_waitcnt lgkmcnt(0)
	v_and_or_b32 v142, v142, s90, v240
	v_and_or_b32 v143, v143, s90, v240
	global_load_dwordx4 v[24:27], v142, s[80:81]
	global_load_dwordx4 v[28:31], v143, s[80:81]
	ds_bpermute_b32 v142, v249, v135
	ds_bpermute_b32 v143, v250, v135
	s_waitcnt lgkmcnt(0)
	v_and_or_b32 v142, v142, s90, v240
	v_and_or_b32 v143, v143, s90, v240
	global_load_dwordx4 v[32:35], v142, s[80:81]
	global_load_dwordx4 v[36:39], v143, s[80:81]
	ds_bpermute_b32 v142, v251, v135
	ds_bpermute_b32 v143, v252, v135
	s_waitcnt lgkmcnt(0)
	v_and_or_b32 v142, v142, s90, v240
	v_and_or_b32 v143, v143, s90, v240
	global_load_dwordx4 v[40:43], v142, s[80:81]
	global_load_dwordx4 v[44:47], v143, s[80:81]
	ds_bpermute_b32 v142, v253, v135
	ds_bpermute_b32 v143, v254, v135
	s_waitcnt lgkmcnt(0)
	v_and_or_b32 v142, v142, s90, v240
	v_and_or_b32 v143, v143, s90, v240
	global_load_dwordx4 v[48:51], v142, s[80:81]
	global_load_dwordx4 v[52:55], v143, s[80:81]
	ds_bpermute_b32 v142, v255, v135
	ds_bpermute_b32 v143, v153, v135
	s_waitcnt lgkmcnt(0)
	v_and_or_b32 v142, v142, s90, v240
	v_and_or_b32 v143, v143, s90, v240
	global_load_dwordx4 v[56:59], v142, s[80:81]
	global_load_dwordx4 v[60:63], v143, s[80:81]
	s_mov_b32 s92, 1
	s_lshl_b32 vcc_lo, s92, 9
	s_add_u32 vcc_lo, vcc_lo, s101
	v_add_u32_e32 v116, vcc_lo, v234
	ds_read_b32 v134, v116
	ds_read_b32 v135, v116 offset:256
.Lpg1_uloop:
	s_and_b32 s98, s100, 15
	s_lshr_b32 s99, s100, 4
	s_add_u32 s92, s100, 1
	s_min_u32 s92, s92, 127
	s_lshr_b32 s93, s92, 4
	s_and_b32 s92, s92, 15
	s_waitcnt vmcnt(16)
	v_lshlrev_b32_e32 v64, 16, v80
	v_and_b32_e32 v65, 0xffff0000, v80
	v_lshlrev_b32_e32 v66, 16, v81
	v_and_b32_e32 v67, 0xffff0000, v81
	v_lshlrev_b32_e32 v68, 16, v82
	v_and_b32_e32 v69, 0xffff0000, v82
	v_lshlrev_b32_e32 v70, 16, v83
	v_and_b32_e32 v71, 0xffff0000, v83
	v_lshlrev_b32_e32 v72, 16, v84
	v_and_b32_e32 v73, 0xffff0000, v84
	v_lshlrev_b32_e32 v74, 16, v85
	v_and_b32_e32 v75, 0xffff0000, v85
	v_lshlrev_b32_e32 v76, 16, v86
	v_and_b32_e32 v77, 0xffff0000, v86
	v_lshlrev_b32_e32 v78, 16, v87
	v_and_b32_e32 v79, 0xffff0000, v87
	v_readfirstlane_b32 s82, v122
	v_readfirstlane_b32 s83, v123
	s_nop 4
	s_add_u32 vcc_lo, s3, s92
	s_lshl_b32 vcc_lo, vcc_lo, 11
	s_lshl_b32 vcc_hi, s93, 8
	s_add_u32 vcc_lo, vcc_lo, vcc_hi
	v_add_u32_e32 v119, vcc_lo, v236
	global_load_dwordx4 v[80:83], v119, s[82:83]
	global_load_dwordx4 v[84:87], v119, s[82:83] offset:16
	s_lshl_b32 vcc_lo, s93, 7
	v_add_u32_e32 v240, vcc_lo, v235
	s_waitcnt lgkmcnt(0)
	ds_bpermute_b32 v142, v249, v134
	ds_bpermute_b32 v143, v250, v134
	s_waitcnt vmcnt(16)
	v_cvt_pk_f32_fp8_e32 v[104:105], v0
	v_cvt_pk_f32_fp8_e32 v[108:109], v4
	v_cvt_pk_f32_fp8_sdwa v[106:107], v0 src0_sel:WORD_1
	v_cvt_pk_f32_fp8_sdwa v[110:111], v4 src0_sel:WORD_1
	v_pk_mul_f32 v[112:113], v[64:65], v[104:105]
	v_pk_mul_f32 v[114:115], v[64:65], v[108:109]
	v_pk_fma_f32 v[112:113], v[66:67], v[106:107], v[112:113]
	v_pk_fma_f32 v[114:115], v[66:67], v[110:111], v[114:115]
	v_cvt_pk_f32_fp8_e32 v[104:105], v1
	v_cvt_pk_f32_fp8_e32 v[108:109], v5
	v_cvt_pk_f32_fp8_sdwa v[106:107], v1 src0_sel:WORD_1
	v_cvt_pk_f32_fp8_sdwa v[110:111], v5 src0_sel:WORD_1
	v_pk_fma_f32 v[112:113], v[68:69], v[104:105], v[112:113]
	v_pk_fma_f32 v[114:115], v[68:69], v[108:109], v[114:115]
	v_pk_fma_f32 v[112:113], v[70:71], v[106:107], v[112:113]
	v_pk_fma_f32 v[114:115], v[70:71], v[110:111], v[114:115]
	v_cvt_pk_f32_fp8_e32 v[104:105], v2
	v_cvt_pk_f32_fp8_e32 v[108:109], v6
	v_cvt_pk_f32_fp8_sdwa v[106:107], v2 src0_sel:WORD_1
	v_cvt_pk_f32_fp8_sdwa v[110:111], v6 src0_sel:WORD_1
	v_pk_fma_f32 v[112:113], v[72:73], v[104:105], v[112:113]
	v_pk_fma_f32 v[114:115], v[72:73], v[108:109], v[114:115]
	v_pk_fma_f32 v[112:113], v[74:75], v[106:107], v[112:113]
	v_pk_fma_f32 v[114:115], v[74:75], v[110:111], v[114:115]
	v_cvt_pk_f32_fp8_e32 v[104:105], v3
	v_cvt_pk_f32_fp8_e32 v[108:109], v7
	v_cvt_pk_f32_fp8_sdwa v[106:107], v3 src0_sel:WORD_1
	v_cvt_pk_f32_fp8_sdwa v[110:111], v7 src0_sel:WORD_1
	v_pk_fma_f32 v[112:113], v[76:77], v[104:105], v[112:113]
	v_pk_fma_f32 v[114:115], v[76:77], v[108:109], v[114:115]
	s_waitcnt lgkmcnt(0)
	v_and_or_b32 v142, v142, s90, v240
	v_and_or_b32 v143, v143, s90, v240
	global_load_dwordx4 v[0:3], v142, s[80:81]
	global_load_dwordx4 v[4:7], v143, s[80:81]
	v_pk_fma_f32 v[112:113], v[78:79], v[106:107], v[112:113]
	v_pk_fma_f32 v[114:115], v[78:79], v[110:111], v[114:115]
	v_add_f32_e32 v88, v112, v113
	v_add_f32_e32 v89, v114, v115
	ds_bpermute_b32 v142, v251, v134
	ds_bpermute_b32 v143, v252, v134
	s_waitcnt vmcnt(16)
	v_cvt_pk_f32_fp8_e32 v[104:105], v8
	v_cvt_pk_f32_fp8_e32 v[108:109], v12
	v_cvt_pk_f32_fp8_sdwa v[106:107], v8 src0_sel:WORD_1
	v_cvt_pk_f32_fp8_sdwa v[110:111], v12 src0_sel:WORD_1
	v_pk_mul_f32 v[112:113], v[64:65], v[104:105]
	v_pk_mul_f32 v[114:115], v[64:65], v[108:109]
	v_pk_fma_f32 v[112:113], v[66:67], v[106:107], v[112:113]
	v_pk_fma_f32 v[114:115], v[66:67], v[110:111], v[114:115]
	v_cvt_pk_f32_fp8_e32 v[104:105], v9
	v_cvt_pk_f32_fp8_e32 v[108:109], v13
	v_cvt_pk_f32_fp8_sdwa v[106:107], v9 src0_sel:WORD_1
	v_cvt_pk_f32_fp8_sdwa v[110:111], v13 src0_sel:WORD_1
	v_pk_fma_f32 v[112:113], v[68:69], v[104:105], v[112:113]
	v_pk_fma_f32 v[114:115], v[68:69], v[108:109], v[114:115]
	v_pk_fma_f32 v[112:113], v[70:71], v[106:107], v[112:113]
	v_pk_fma_f32 v[114:115], v[70:71], v[110:111], v[114:115]
	v_cvt_pk_f32_fp8_e32 v[104:105], v10
	v_cvt_pk_f32_fp8_e32 v[108:109], v14
	v_cvt_pk_f32_fp8_sdwa v[106:107], v10 src0_sel:WORD_1
	v_cvt_pk_f32_fp8_sdwa v[110:111], v14 src0_sel:WORD_1
	v_pk_fma_f32 v[112:113], v[72:73], v[104:105], v[112:113]
	v_pk_fma_f32 v[114:115], v[72:73], v[108:109], v[114:115]
	v_pk_fma_f32 v[112:113], v[74:75], v[106:107], v[112:113]
	v_pk_fma_f32 v[114:115], v[74:75], v[110:111], v[114:115]
	v_cvt_pk_f32_fp8_e32 v[104:105], v11
	v_cvt_pk_f32_fp8_e32 v[108:109], v15
	v_cvt_pk_f32_fp8_sdwa v[106:107], v11 src0_sel:WORD_1
	v_cvt_pk_f32_fp8_sdwa v[110:111], v15 src0_sel:WORD_1
	v_pk_fma_f32 v[112:113], v[76:77], v[104:105], v[112:113]
	v_pk_fma_f32 v[114:115], v[76:77], v[108:109], v[114:115]
	s_waitcnt lgkmcnt(0)
	v_and_or_b32 v142, v142, s90, v240
	v_and_or_b32 v143, v143, s90, v240
	global_load_dwordx4 v[8:11], v142, s[80:81]
	global_load_dwordx4 v[12:15], v143, s[80:81]
	v_pk_fma_f32 v[112:113], v[78:79], v[106:107], v[112:113]
	v_pk_fma_f32 v[114:115], v[78:79], v[110:111], v[114:115]
	v_add_f32_e32 v90, v112, v113
	v_add_f32_e32 v91, v114, v115
	ds_bpermute_b32 v142, v253, v134
	ds_bpermute_b32 v143, v254, v134
	s_waitcnt vmcnt(16)
	v_cvt_pk_f32_fp8_e32 v[104:105], v16
	v_cvt_pk_f32_fp8_e32 v[108:109], v20
	v_cvt_pk_f32_fp8_sdwa v[106:107], v16 src0_sel:WORD_1
	v_cvt_pk_f32_fp8_sdwa v[110:111], v20 src0_sel:WORD_1
	v_pk_mul_f32 v[112:113], v[64:65], v[104:105]
	v_pk_mul_f32 v[114:115], v[64:65], v[108:109]
	v_pk_fma_f32 v[112:113], v[66:67], v[106:107], v[112:113]
	v_pk_fma_f32 v[114:115], v[66:67], v[110:111], v[114:115]
	v_cvt_pk_f32_fp8_e32 v[104:105], v17
	v_cvt_pk_f32_fp8_e32 v[108:109], v21
	v_cvt_pk_f32_fp8_sdwa v[106:107], v17 src0_sel:WORD_1
	v_cvt_pk_f32_fp8_sdwa v[110:111], v21 src0_sel:WORD_1
	v_pk_fma_f32 v[112:113], v[68:69], v[104:105], v[112:113]
	v_pk_fma_f32 v[114:115], v[68:69], v[108:109], v[114:115]
	v_pk_fma_f32 v[112:113], v[70:71], v[106:107], v[112:113]
	v_pk_fma_f32 v[114:115], v[70:71], v[110:111], v[114:115]
	v_cvt_pk_f32_fp8_e32 v[104:105], v18
	v_cvt_pk_f32_fp8_e32 v[108:109], v22
	v_cvt_pk_f32_fp8_sdwa v[106:107], v18 src0_sel:WORD_1
	v_cvt_pk_f32_fp8_sdwa v[110:111], v22 src0_sel:WORD_1
	v_pk_fma_f32 v[112:113], v[72:73], v[104:105], v[112:113]
	v_pk_fma_f32 v[114:115], v[72:73], v[108:109], v[114:115]
	v_pk_fma_f32 v[112:113], v[74:75], v[106:107], v[112:113]
	v_pk_fma_f32 v[114:115], v[74:75], v[110:111], v[114:115]
	v_cvt_pk_f32_fp8_e32 v[104:105], v19
	v_cvt_pk_f32_fp8_e32 v[108:109], v23
	v_cvt_pk_f32_fp8_sdwa v[106:107], v19 src0_sel:WORD_1
	v_cvt_pk_f32_fp8_sdwa v[110:111], v23 src0_sel:WORD_1
	v_pk_fma_f32 v[112:113], v[76:77], v[104:105], v[112:113]
	v_pk_fma_f32 v[114:115], v[76:77], v[108:109], v[114:115]
	s_waitcnt lgkmcnt(0)
	v_and_or_b32 v142, v142, s90, v240
	v_and_or_b32 v143, v143, s90, v240
	global_load_dwordx4 v[16:19], v142, s[80:81]
	global_load_dwordx4 v[20:23], v143, s[80:81]
	v_pk_fma_f32 v[112:113], v[78:79], v[106:107], v[112:113]
	v_pk_fma_f32 v[114:115], v[78:79], v[110:111], v[114:115]
	v_add_f32_e32 v92, v112, v113
	v_add_f32_e32 v93, v114, v115
	ds_bpermute_b32 v142, v255, v134
	ds_bpermute_b32 v143, v153, v134
	s_waitcnt vmcnt(16)
	v_cvt_pk_f32_fp8_e32 v[104:105], v24
	v_cvt_pk_f32_fp8_e32 v[108:109], v28
	v_cvt_pk_f32_fp8_sdwa v[106:107], v24 src0_sel:WORD_1
	v_cvt_pk_f32_fp8_sdwa v[110:111], v28 src0_sel:WORD_1
	v_pk_mul_f32 v[112:113], v[64:65], v[104:105]
	v_pk_mul_f32 v[114:115], v[64:65], v[108:109]
	v_pk_fma_f32 v[112:113], v[66:67], v[106:107], v[112:113]
	v_pk_fma_f32 v[114:115], v[66:67], v[110:111], v[114:115]
	v_cvt_pk_f32_fp8_e32 v[104:105], v25
	v_cvt_pk_f32_fp8_e32 v[108:109], v29
	v_cvt_pk_f32_fp8_sdwa v[106:107], v25 src0_sel:WORD_1
	v_cvt_pk_f32_fp8_sdwa v[110:111], v29 src0_sel:WORD_1
	v_pk_fma_f32 v[112:113], v[68:69], v[104:105], v[112:113]
	v_pk_fma_f32 v[114:115], v[68:69], v[108:109], v[114:115]
	v_pk_fma_f32 v[112:113], v[70:71], v[106:107], v[112:113]
	v_pk_fma_f32 v[114:115], v[70:71], v[110:111], v[114:115]
	v_cvt_pk_f32_fp8_e32 v[104:105], v26
	v_cvt_pk_f32_fp8_e32 v[108:109], v30
	v_cvt_pk_f32_fp8_sdwa v[106:107], v26 src0_sel:WORD_1
	v_cvt_pk_f32_fp8_sdwa v[110:111], v30 src0_sel:WORD_1
	v_pk_fma_f32 v[112:113], v[72:73], v[104:105], v[112:113]
	v_pk_fma_f32 v[114:115], v[72:73], v[108:109], v[114:115]
	v_pk_fma_f32 v[112:113], v[74:75], v[106:107], v[112:113]
	v_pk_fma_f32 v[114:115], v[74:75], v[110:111], v[114:115]
	v_cvt_pk_f32_fp8_e32 v[104:105], v27
	v_cvt_pk_f32_fp8_e32 v[108:109], v31
	v_cvt_pk_f32_fp8_sdwa v[106:107], v27 src0_sel:WORD_1
	v_cvt_pk_f32_fp8_sdwa v[110:111], v31 src0_sel:WORD_1
	v_pk_fma_f32 v[112:113], v[76:77], v[104:105], v[112:113]
	v_pk_fma_f32 v[114:115], v[76:77], v[108:109], v[114:115]
	s_waitcnt lgkmcnt(0)
	v_and_or_b32 v142, v142, s90, v240
	v_and_or_b32 v143, v143, s90, v240
	global_load_dwordx4 v[24:27], v142, s[80:81]
	global_load_dwordx4 v[28:31], v143, s[80:81]
	v_pk_fma_f32 v[112:113], v[78:79], v[106:107], v[112:113]
	v_pk_fma_f32 v[114:115], v[78:79], v[110:111], v[114:115]
	v_add_f32_e32 v94, v112, v113
	v_add_f32_e32 v95, v114, v115
	ds_bpermute_b32 v142, v249, v135
	ds_bpermute_b32 v143, v250, v135
	s_waitcnt vmcnt(16)
	v_cvt_pk_f32_fp8_e32 v[104:105], v32
	v_cvt_pk_f32_fp8_e32 v[108:109], v36
	v_cvt_pk_f32_fp8_sdwa v[106:107], v32 src0_sel:WORD_1
	v_cvt_pk_f32_fp8_sdwa v[110:111], v36 src0_sel:WORD_1
	v_pk_mul_f32 v[112:113], v[64:65], v[104:105]
	v_pk_mul_f32 v[114:115], v[64:65], v[108:109]
	v_pk_fma_f32 v[112:113], v[66:67], v[106:107], v[112:113]
	v_pk_fma_f32 v[114:115], v[66:67], v[110:111], v[114:115]
	v_cvt_pk_f32_fp8_e32 v[104:105], v33
	v_cvt_pk_f32_fp8_e32 v[108:109], v37
	v_cvt_pk_f32_fp8_sdwa v[106:107], v33 src0_sel:WORD_1
	v_cvt_pk_f32_fp8_sdwa v[110:111], v37 src0_sel:WORD_1
	v_pk_fma_f32 v[112:113], v[68:69], v[104:105], v[112:113]
	v_pk_fma_f32 v[114:115], v[68:69], v[108:109], v[114:115]
	v_pk_fma_f32 v[112:113], v[70:71], v[106:107], v[112:113]
	v_pk_fma_f32 v[114:115], v[70:71], v[110:111], v[114:115]
	v_cvt_pk_f32_fp8_e32 v[104:105], v34
	v_cvt_pk_f32_fp8_e32 v[108:109], v38
	v_cvt_pk_f32_fp8_sdwa v[106:107], v34 src0_sel:WORD_1
	v_cvt_pk_f32_fp8_sdwa v[110:111], v38 src0_sel:WORD_1
	v_pk_fma_f32 v[112:113], v[72:73], v[104:105], v[112:113]
	v_pk_fma_f32 v[114:115], v[72:73], v[108:109], v[114:115]
	v_pk_fma_f32 v[112:113], v[74:75], v[106:107], v[112:113]
	v_pk_fma_f32 v[114:115], v[74:75], v[110:111], v[114:115]
	v_cvt_pk_f32_fp8_e32 v[104:105], v35
	v_cvt_pk_f32_fp8_e32 v[108:109], v39
	v_cvt_pk_f32_fp8_sdwa v[106:107], v35 src0_sel:WORD_1
	v_cvt_pk_f32_fp8_sdwa v[110:111], v39 src0_sel:WORD_1
	v_pk_fma_f32 v[112:113], v[76:77], v[104:105], v[112:113]
	v_pk_fma_f32 v[114:115], v[76:77], v[108:109], v[114:115]
	s_waitcnt lgkmcnt(0)
	v_and_or_b32 v142, v142, s90, v240
	v_and_or_b32 v143, v143, s90, v240
	global_load_dwordx4 v[32:35], v142, s[80:81]
	global_load_dwordx4 v[36:39], v143, s[80:81]
	v_pk_fma_f32 v[112:113], v[78:79], v[106:107], v[112:113]
	v_pk_fma_f32 v[114:115], v[78:79], v[110:111], v[114:115]
	v_add_f32_e32 v96, v112, v113
	v_add_f32_e32 v97, v114, v115
	ds_bpermute_b32 v142, v251, v135
	ds_bpermute_b32 v143, v252, v135
	s_waitcnt vmcnt(16)
	v_cvt_pk_f32_fp8_e32 v[104:105], v40
	v_cvt_pk_f32_fp8_e32 v[108:109], v44
	v_cvt_pk_f32_fp8_sdwa v[106:107], v40 src0_sel:WORD_1
	v_cvt_pk_f32_fp8_sdwa v[110:111], v44 src0_sel:WORD_1
	v_pk_mul_f32 v[112:113], v[64:65], v[104:105]
	v_pk_mul_f32 v[114:115], v[64:65], v[108:109]
	v_pk_fma_f32 v[112:113], v[66:67], v[106:107], v[112:113]
	v_pk_fma_f32 v[114:115], v[66:67], v[110:111], v[114:115]
	v_cvt_pk_f32_fp8_e32 v[104:105], v41
	v_cvt_pk_f32_fp8_e32 v[108:109], v45
	v_cvt_pk_f32_fp8_sdwa v[106:107], v41 src0_sel:WORD_1
	v_cvt_pk_f32_fp8_sdwa v[110:111], v45 src0_sel:WORD_1
	v_pk_fma_f32 v[112:113], v[68:69], v[104:105], v[112:113]
	v_pk_fma_f32 v[114:115], v[68:69], v[108:109], v[114:115]
	v_pk_fma_f32 v[112:113], v[70:71], v[106:107], v[112:113]
	v_pk_fma_f32 v[114:115], v[70:71], v[110:111], v[114:115]
	v_cvt_pk_f32_fp8_e32 v[104:105], v42
	v_cvt_pk_f32_fp8_e32 v[108:109], v46
	v_cvt_pk_f32_fp8_sdwa v[106:107], v42 src0_sel:WORD_1
	v_cvt_pk_f32_fp8_sdwa v[110:111], v46 src0_sel:WORD_1
	v_pk_fma_f32 v[112:113], v[72:73], v[104:105], v[112:113]
	v_pk_fma_f32 v[114:115], v[72:73], v[108:109], v[114:115]
	v_pk_fma_f32 v[112:113], v[74:75], v[106:107], v[112:113]
	v_pk_fma_f32 v[114:115], v[74:75], v[110:111], v[114:115]
	v_cvt_pk_f32_fp8_e32 v[104:105], v43
	v_cvt_pk_f32_fp8_e32 v[108:109], v47
	v_cvt_pk_f32_fp8_sdwa v[106:107], v43 src0_sel:WORD_1
	v_cvt_pk_f32_fp8_sdwa v[110:111], v47 src0_sel:WORD_1
	v_pk_fma_f32 v[112:113], v[76:77], v[104:105], v[112:113]
	v_pk_fma_f32 v[114:115], v[76:77], v[108:109], v[114:115]
	s_waitcnt lgkmcnt(0)
	v_and_or_b32 v142, v142, s90, v240
	v_and_or_b32 v143, v143, s90, v240
	global_load_dwordx4 v[40:43], v142, s[80:81]
	global_load_dwordx4 v[44:47], v143, s[80:81]
	v_pk_fma_f32 v[112:113], v[78:79], v[106:107], v[112:113]
	v_pk_fma_f32 v[114:115], v[78:79], v[110:111], v[114:115]
	v_add_f32_e32 v98, v112, v113
	v_add_f32_e32 v99, v114, v115
	ds_bpermute_b32 v142, v253, v135
	ds_bpermute_b32 v143, v254, v135
	s_waitcnt vmcnt(16)
	v_cvt_pk_f32_fp8_e32 v[104:105], v48
	v_cvt_pk_f32_fp8_e32 v[108:109], v52
	v_cvt_pk_f32_fp8_sdwa v[106:107], v48 src0_sel:WORD_1
	v_cvt_pk_f32_fp8_sdwa v[110:111], v52 src0_sel:WORD_1
	v_pk_mul_f32 v[112:113], v[64:65], v[104:105]
	v_pk_mul_f32 v[114:115], v[64:65], v[108:109]
	v_pk_fma_f32 v[112:113], v[66:67], v[106:107], v[112:113]
	v_pk_fma_f32 v[114:115], v[66:67], v[110:111], v[114:115]
	v_cvt_pk_f32_fp8_e32 v[104:105], v49
	v_cvt_pk_f32_fp8_e32 v[108:109], v53
	v_cvt_pk_f32_fp8_sdwa v[106:107], v49 src0_sel:WORD_1
	v_cvt_pk_f32_fp8_sdwa v[110:111], v53 src0_sel:WORD_1
	v_pk_fma_f32 v[112:113], v[68:69], v[104:105], v[112:113]
	v_pk_fma_f32 v[114:115], v[68:69], v[108:109], v[114:115]
	v_pk_fma_f32 v[112:113], v[70:71], v[106:107], v[112:113]
	v_pk_fma_f32 v[114:115], v[70:71], v[110:111], v[114:115]
	v_cvt_pk_f32_fp8_e32 v[104:105], v50
	v_cvt_pk_f32_fp8_e32 v[108:109], v54
	v_cvt_pk_f32_fp8_sdwa v[106:107], v50 src0_sel:WORD_1
	v_cvt_pk_f32_fp8_sdwa v[110:111], v54 src0_sel:WORD_1
	v_pk_fma_f32 v[112:113], v[72:73], v[104:105], v[112:113]
	v_pk_fma_f32 v[114:115], v[72:73], v[108:109], v[114:115]
	v_pk_fma_f32 v[112:113], v[74:75], v[106:107], v[112:113]
	v_pk_fma_f32 v[114:115], v[74:75], v[110:111], v[114:115]
	v_cvt_pk_f32_fp8_e32 v[104:105], v51
	v_cvt_pk_f32_fp8_e32 v[108:109], v55
	v_cvt_pk_f32_fp8_sdwa v[106:107], v51 src0_sel:WORD_1
	v_cvt_pk_f32_fp8_sdwa v[110:111], v55 src0_sel:WORD_1
	v_pk_fma_f32 v[112:113], v[76:77], v[104:105], v[112:113]
	v_pk_fma_f32 v[114:115], v[76:77], v[108:109], v[114:115]
	s_waitcnt lgkmcnt(0)
	v_and_or_b32 v142, v142, s90, v240
	v_and_or_b32 v143, v143, s90, v240
	global_load_dwordx4 v[48:51], v142, s[80:81]
	global_load_dwordx4 v[52:55], v143, s[80:81]
	v_pk_fma_f32 v[112:113], v[78:79], v[106:107], v[112:113]
	v_pk_fma_f32 v[114:115], v[78:79], v[110:111], v[114:115]
	v_add_f32_e32 v100, v112, v113
	v_add_f32_e32 v101, v114, v115
	ds_bpermute_b32 v142, v255, v135
	ds_bpermute_b32 v143, v153, v135
	s_waitcnt vmcnt(16)
	v_cvt_pk_f32_fp8_e32 v[104:105], v56
	v_cvt_pk_f32_fp8_e32 v[108:109], v60
	v_cvt_pk_f32_fp8_sdwa v[106:107], v56 src0_sel:WORD_1
	v_cvt_pk_f32_fp8_sdwa v[110:111], v60 src0_sel:WORD_1
	v_pk_mul_f32 v[112:113], v[64:65], v[104:105]
	v_pk_mul_f32 v[114:115], v[64:65], v[108:109]
	v_pk_fma_f32 v[112:113], v[66:67], v[106:107], v[112:113]
	v_pk_fma_f32 v[114:115], v[66:67], v[110:111], v[114:115]
	v_cvt_pk_f32_fp8_e32 v[104:105], v57
	v_cvt_pk_f32_fp8_e32 v[108:109], v61
	v_cvt_pk_f32_fp8_sdwa v[106:107], v57 src0_sel:WORD_1
	v_cvt_pk_f32_fp8_sdwa v[110:111], v61 src0_sel:WORD_1
	v_pk_fma_f32 v[112:113], v[68:69], v[104:105], v[112:113]
	v_pk_fma_f32 v[114:115], v[68:69], v[108:109], v[114:115]
	v_pk_fma_f32 v[112:113], v[70:71], v[106:107], v[112:113]
	v_pk_fma_f32 v[114:115], v[70:71], v[110:111], v[114:115]
	v_cvt_pk_f32_fp8_e32 v[104:105], v58
	v_cvt_pk_f32_fp8_e32 v[108:109], v62
	v_cvt_pk_f32_fp8_sdwa v[106:107], v58 src0_sel:WORD_1
	v_cvt_pk_f32_fp8_sdwa v[110:111], v62 src0_sel:WORD_1
	v_pk_fma_f32 v[112:113], v[72:73], v[104:105], v[112:113]
	v_pk_fma_f32 v[114:115], v[72:73], v[108:109], v[114:115]
	v_pk_fma_f32 v[112:113], v[74:75], v[106:107], v[112:113]
	v_pk_fma_f32 v[114:115], v[74:75], v[110:111], v[114:115]
	v_cvt_pk_f32_fp8_e32 v[104:105], v59
	v_cvt_pk_f32_fp8_e32 v[108:109], v63
	v_cvt_pk_f32_fp8_sdwa v[106:107], v59 src0_sel:WORD_1
	v_cvt_pk_f32_fp8_sdwa v[110:111], v63 src0_sel:WORD_1
	v_pk_fma_f32 v[112:113], v[76:77], v[104:105], v[112:113]
	v_pk_fma_f32 v[114:115], v[76:77], v[108:109], v[114:115]
	s_waitcnt lgkmcnt(0)
	v_and_or_b32 v142, v142, s90, v240
	v_and_or_b32 v143, v143, s90, v240
	global_load_dwordx4 v[56:59], v142, s[80:81]
	global_load_dwordx4 v[60:63], v143, s[80:81]
	v_pk_fma_f32 v[112:113], v[78:79], v[106:107], v[112:113]
	v_pk_fma_f32 v[114:115], v[78:79], v[110:111], v[114:115]
	v_add_f32_e32 v102, v112, v113
	v_add_f32_e32 v103, v114, v115
	s_add_u32 s92, s100, 2
	s_min_u32 s92, s92, 127
	s_and_b32 s92, s92, 15
	s_lshl_b32 vcc_lo, s92, 9
	s_add_u32 vcc_lo, vcc_lo, s101
	v_add_u32_e32 v116, vcc_lo, v234
	ds_read_b32 v134, v116
	ds_read_b32 v135, v116 offset:256
	s_lshl_b32 vcc_lo, s98, 9
	s_add_u32 vcc_lo, vcc_lo, s101
	s_add_u32 vcc_lo, vcc_lo, 0x10000
	v_add_u32_e32 v117, vcc_lo, v234
	ds_read_b32 v136, v117
	ds_read_b32 v137, v117 offset:256
	s_mov_b32 s88, 0xf0f0f0f0
	s_mov_b32 s89, 0xf0f0f0f0
	v_cndmask_b32_e64 v144, v88, v92, s[88:89]
	v_cndmask_b32_e64 v92, v92, v88, s[88:89]
	v_cndmask_b32_e64 v145, v89, v93, s[88:89]
	v_cndmask_b32_e64 v93, v93, v89, s[88:89]
	v_cndmask_b32_e64 v146, v90, v94, s[88:89]
	v_cndmask_b32_e64 v94, v94, v90, s[88:89]
	v_cndmask_b32_e64 v147, v91, v95, s[88:89]
	v_cndmask_b32_e64 v95, v95, v91, s[88:89]
	v_add_f32_dpp v88, v92, v144 row_shl:4 row_mask:0xf bank_mask:0x5
	v_add_f32_dpp v89, v93, v145 row_shl:4 row_mask:0xf bank_mask:0x5
	v_add_f32_dpp v90, v94, v146 row_shl:4 row_mask:0xf bank_mask:0x5
	v_add_f32_dpp v91, v95, v147 row_shl:4 row_mask:0xf bank_mask:0x5
	v_add_f32_dpp v88, v92, v144 row_shr:4 row_mask:0xf bank_mask:0xa
	v_add_f32_dpp v89, v93, v145 row_shr:4 row_mask:0xf bank_mask:0xa
	v_add_f32_dpp v90, v94, v146 row_shr:4 row_mask:0xf bank_mask:0xa
	v_add_f32_dpp v91, v95, v147 row_shr:4 row_mask:0xf bank_mask:0xa
	v_cndmask_b32_e64 v144, v96, v100, s[88:89]
	v_cndmask_b32_e64 v100, v100, v96, s[88:89]
	v_cndmask_b32_e64 v145, v97, v101, s[88:89]
	v_cndmask_b32_e64 v101, v101, v97, s[88:89]
	v_cndmask_b32_e64 v146, v98, v102, s[88:89]
	v_cndmask_b32_e64 v102, v102, v98, s[88:89]
	v_cndmask_b32_e64 v147, v99, v103, s[88:89]
	v_cndmask_b32_e64 v103, v103, v99, s[88:89]
	v_add_f32_dpp v96, v100, v144 row_shl:4 row_mask:0xf bank_mask:0x5
	v_add_f32_dpp v97, v101, v145 row_shl:4 row_mask:0xf bank_mask:0x5
	v_add_f32_dpp v98, v102, v146 row_shl:4 row_mask:0xf bank_mask:0x5
	v_add_f32_dpp v99, v103, v147 row_shl:4 row_mask:0xf bank_mask:0x5
	v_add_f32_dpp v96, v100, v144 row_shr:4 row_mask:0xf bank_mask:0xa
	v_add_f32_dpp v97, v101, v145 row_shr:4 row_mask:0xf bank_mask:0xa
	v_add_f32_dpp v98, v102, v146 row_shr:4 row_mask:0xf bank_mask:0xa
	v_add_f32_dpp v99, v103, v147 row_shr:4 row_mask:0xf bank_mask:0xa
	s_mov_b32 s88, 0xcccccccc
	s_mov_b32 s89, 0xcccccccc
	v_cndmask_b32_e64 v144, v88, v90, s[88:89]
	v_cndmask_b32_e64 v90, v90, v88, s[88:89]
	v_cndmask_b32_e64 v145, v89, v91, s[88:89]
	v_cndmask_b32_e64 v91, v91, v89, s[88:89]
	v_cndmask_b32_e64 v146, v96, v98, s[88:89]
	v_cndmask_b32_e64 v98, v98, v96, s[88:89]
	v_cndmask_b32_e64 v147, v97, v99, s[88:89]
	v_cndmask_b32_e64 v99, v99, v97, s[88:89]
	v_add_f32_dpp v88, v90, v144 quad_perm:[2,3,0,1] row_mask:0xf bank_mask:0xf
	v_add_f32_dpp v89, v91, v145 quad_perm:[2,3,0,1] row_mask:0xf bank_mask:0xf
	v_add_f32_dpp v96, v98, v146 quad_perm:[2,3,0,1] row_mask:0xf bank_mask:0xf
	v_add_f32_dpp v97, v99, v147 quad_perm:[2,3,0,1] row_mask:0xf bank_mask:0xf
	s_mov_b32 s88, 0xaaaaaaaa
	s_mov_b32 s89, 0xaaaaaaaa
	v_cndmask_b32_e64 v144, v88, v89, s[88:89]
	v_cndmask_b32_e64 v89, v89, v88, s[88:89]
	v_cndmask_b32_e64 v145, v96, v97, s[88:89]
	v_cndmask_b32_e64 v97, v97, v96, s[88:89]
	s_nop 1
	v_add_f32_dpp v88, v89, v144 quad_perm:[1,0,3,2] row_mask:0xf bank_mask:0xf
	v_add_f32_dpp v96, v97, v145 quad_perm:[1,0,3,2] row_mask:0xf bank_mask:0xf
	s_nop 0
	ds_bpermute_b32 v144, v239, v88
	ds_bpermute_b32 v145, v239, v96
	s_waitcnt lgkmcnt(0)
	v_add_f32_e32 v136, v136, v144
	v_add_f32_e32 v137, v137, v145
	ds_write_b32 v117, v136
	ds_write_b32 v117, v137 offset:256
	s_add_u32 s100, s100, 1
	s_cmp_lt_u32 s100, 128
	s_cbranch_scc1 .Lpg1_uloop
	s_waitcnt vmcnt(0) lgkmcnt(0)
	s_mov_b32 s2, 0
.Lpg1_act:
	v_readlane_b32 s82, v232, 1
	v_readlane_b32 s83, v232, 2
	s_nop 4
	s_lshl_b32 s98, s2, 11
	s_add_u32 s98, s98, s101
	v_add_u32_e32 v116, s98, v234
	v_add_u32_e32 v117, 0x10000, v116
	ds_read_b32 v0, v116 offset:0
	ds_read_b32 v8, v117 offset:0
	ds_read_b32 v1, v116 offset:256
	ds_read_b32 v9, v117 offset:256
	ds_read_b32 v2, v116 offset:512
	ds_read_b32 v10, v117 offset:512
	ds_read_b32 v3, v116 offset:768
	ds_read_b32 v11, v117 offset:768
	ds_read_b32 v4, v116 offset:1024
	ds_read_b32 v12, v117 offset:1024
	ds_read_b32 v5, v116 offset:1280
	ds_read_b32 v13, v117 offset:1280
	ds_read_b32 v6, v116 offset:1536
	ds_read_b32 v14, v117 offset:1536
	ds_read_b32 v7, v116 offset:1792
	ds_read_b32 v15, v117 offset:1792
	s_waitcnt lgkmcnt(0)
	s_lshl_b32 s99, s2, 2
	s_add_u32 s99, s99, s33
	s_add_u32 s99, s99, 0
	s_lshl_b32 s99, s99, 9
	v_and_b32_e32 v0, 0x7f, v0
	v_lshl_add_u32 v0, v0, 2, s99
	global_load_dword v16, v0, s[82:83]
	v_and_b32_e32 v1, 0x7f, v1
	v_lshl_add_u32 v1, v1, 2, s99
	global_load_dword v17, v1, s[82:83]
	s_lshl_b32 s99, s2, 2
	s_add_u32 s99, s99, s33
	s_add_u32 s99, s99, 1
	s_lshl_b32 s99, s99, 9
	v_and_b32_e32 v2, 0x7f, v2
	v_lshl_add_u32 v2, v2, 2, s99
	global_load_dword v18, v2, s[82:83]
	v_and_b32_e32 v3, 0x7f, v3
	v_lshl_add_u32 v3, v3, 2, s99
	global_load_dword v19, v3, s[82:83]
	s_lshl_b32 s99, s2, 2
	s_add_u32 s99, s99, s33
	s_add_u32 s99, s99, 2
	s_lshl_b32 s99, s99, 9
	v_and_b32_e32 v4, 0x7f, v4
	v_lshl_add_u32 v4, v4, 2, s99
	global_load_dword v20, v4, s[82:83]
	v_and_b32_e32 v5, 0x7f, v5
	v_lshl_add_u32 v5, v5, 2, s99
	global_load_dword v21, v5, s[82:83]
	s_lshl_b32 s99, s2, 2
	s_add_u32 s99, s99, s33
	s_add_u32 s99, s99, 3
	s_lshl_b32 s99, s99, 9
	v_and_b32_e32 v6, 0x7f, v6
	v_lshl_add_u32 v6, v6, 2, s99
	global_load_dword v22, v6, s[82:83]
	v_and_b32_e32 v7, 0x7f, v7
	v_lshl_add_u32 v7, v7, 2, s99
	global_load_dword v23, v7, s[82:83]
	v_mul_f32_e32 v8, 0x3c800000, v8
	v_mul_f32_e32 v9, 0x3c800000, v9
	v_mul_f32_e32 v10, 0x3c800000, v10
	v_mul_f32_e32 v11, 0x3c800000, v11
	v_mul_f32_e32 v12, 0x3c800000, v12
	v_mul_f32_e32 v13, 0x3c800000, v13
	v_mul_f32_e32 v14, 0x3c800000, v14
	v_mul_f32_e32 v15, 0x3c800000, v15
	v_mul_f32_e32 v24, 0x3d372713, v8
	v_mul_f32_e32 v25, 0x3d372713, v9
	v_mul_f32_e32 v26, 0x3d372713, v10
	v_mul_f32_e32 v27, 0x3d372713, v11
	v_mul_f32_e32 v28, 0x3d372713, v12
	v_mul_f32_e32 v29, 0x3d372713, v13
	v_mul_f32_e32 v30, 0x3d372713, v14
	v_mul_f32_e32 v31, 0x3d372713, v15
	v_mul_f32_e32 v24, v8, v24
	v_mul_f32_e32 v25, v9, v25
	v_mul_f32_e32 v26, v10, v26
	v_mul_f32_e32 v27, v11, v27
	v_mul_f32_e32 v28, v12, v28
	v_mul_f32_e32 v29, v13, v29
	v_mul_f32_e32 v30, v14, v30
	v_mul_f32_e32 v31, v15, v31
	v_fma_f32 v24, v8, v24, v8
	v_fma_f32 v25, v9, v25, v9
	v_fma_f32 v26, v10, v26, v10
	v_fma_f32 v27, v11, v27, v11
	v_fma_f32 v28, v12, v28, v12
	v_fma_f32 v29, v13, v29, v13
	v_fma_f32 v30, v14, v30, v14
	v_fma_f32 v31, v15, v31, v15
	v_mul_f32_e32 v24, 0xbfcc422a, v24
	v_mul_f32_e32 v25, 0xbfcc422a, v25
	v_mul_f32_e32 v26, 0xbfcc422a, v26
	v_mul_f32_e32 v27, 0xbfcc422a, v27
	v_mul_f32_e32 v28, 0xbfcc422a, v28
	v_mul_f32_e32 v29, 0xbfcc422a, v29
	v_mul_f32_e32 v30, 0xbfcc422a, v30
	v_mul_f32_e32 v31, 0xbfcc422a, v31
	v_mul_f32_e32 v24, 0x3fb8aa3b, v24
	v_mul_f32_e32 v25, 0x3fb8aa3b, v25
	v_mul_f32_e32 v26, 0x3fb8aa3b, v26
	v_mul_f32_e32 v27, 0x3fb8aa3b, v27
	v_mul_f32_e32 v28, 0x3fb8aa3b, v28
	v_mul_f32_e32 v29, 0x3fb8aa3b, v29
	v_mul_f32_e32 v30, 0x3fb8aa3b, v30
	v_mul_f32_e32 v31, 0x3fb8aa3b, v31
	v_exp_f32_e32 v24, v24
	v_exp_f32_e32 v25, v25
	v_exp_f32_e32 v26, v26
	v_exp_f32_e32 v27, v27
	v_exp_f32_e32 v28, v28
	v_exp_f32_e32 v29, v29
	v_exp_f32_e32 v30, v30
	v_exp_f32_e32 v31, v31
	s_nop 0
	v_add_f32_e32 v24, 1.0, v24
	v_add_f32_e32 v25, 1.0, v25
	v_add_f32_e32 v26, 1.0, v26
	v_add_f32_e32 v27, 1.0, v27
	v_add_f32_e32 v28, 1.0, v28
	v_add_f32_e32 v29, 1.0, v29
	v_add_f32_e32 v30, 1.0, v30
	v_add_f32_e32 v31, 1.0, v31
	v_rcp_f32_e32 v24, v24
	v_rcp_f32_e32 v25, v25
	v_rcp_f32_e32 v26, v26
	v_rcp_f32_e32 v27, v27
	v_rcp_f32_e32 v28, v28
	v_rcp_f32_e32 v29, v29
	v_rcp_f32_e32 v30, v30
	v_rcp_f32_e32 v31, v31
	s_nop 0
	v_mul_f32_e32 v24, v8, v24
	v_mul_f32_e32 v25, v9, v25
	v_mul_f32_e32 v26, v10, v26
	v_mul_f32_e32 v27, v11, v27
	v_mul_f32_e32 v28, v12, v28
	v_mul_f32_e32 v29, v13, v29
	v_mul_f32_e32 v30, v14, v30
	v_mul_f32_e32 v31, v15, v31
	s_waitcnt vmcnt(0)
	v_mul_f32_e32 v24, v24, v16
	ds_write_b32 v117, v24 offset:0
	v_mul_f32_e32 v25, v25, v17
	ds_write_b32 v117, v25 offset:256
	v_mul_f32_e32 v26, v26, v18
	ds_write_b32 v117, v26 offset:512
	v_mul_f32_e32 v27, v27, v19
	ds_write_b32 v117, v27 offset:768
	v_mul_f32_e32 v28, v28, v20
	ds_write_b32 v117, v28 offset:1024
	v_mul_f32_e32 v29, v29, v21
	ds_write_b32 v117, v29 offset:1280
	v_mul_f32_e32 v30, v30, v22
	ds_write_b32 v117, v30 offset:1536
	v_mul_f32_e32 v31, v31, v23
	ds_write_b32 v117, v31 offset:1792
	s_add_u32 s2, s2, 1
	s_cmp_lt_u32 s2, 4
	s_cbranch_scc1 .Lpg1_act
	s_waitcnt lgkmcnt(0)
	v_readfirstlane_b32 s80, v128
	v_readfirstlane_b32 s81, v129
	s_nop 4
	s_waitcnt vmcnt(0) lgkmcnt(0)
	s_barrier
	v_readfirstlane_b32 s98, v176
	s_cmp_lt_u32 s98, 64
	s_cbranch_scc0 .Lpg1_sk2
	v_readfirstlane_b32 s82, v124
	v_readfirstlane_b32 s83, v125
	s_nop 4
	s_add_u32 s82, s82, 0x123800
	s_addc_u32 s83, s83, 0
	s_getreg_b32 s99, hwreg(HW_REG_XCC_ID, 0, 4)
	s_lshl_b32 s99, s99, 6
	v_mov_b32_e32 v144, s99
	v_mov_b32_e32 v145, 1
	v_mov_b32_e32 v146, 0x27fc0
	s_mov_b64 exec, 1
	ds_read_b32 v147, v146
	global_atomic_add v144, v145, s[82:83]
	s_waitcnt lgkmcnt(0)
	v_readfirstlane_b32 s92, v147
	s_mul_i32 s92, s92, 4
	s_mov_b32 s93, 0

; DEV unsigned pk2(float lo, float hi) { f32x2_t v = {lo, hi}; bf16x2_t b = __builtin_convertvector(v, bf16x2_t); return __builtin_bit_cast(unsigned, b); }
; DEV void peer_gather(const Params& P, int l, int m0, const int* idxs, const float* gs) {
;     ...
;     float ss = 0.f;
; #pragma unroll
;     for (int q = 0; q < 4; ++q) {
;       hv[q][0] += acc[2 * q][0] * TAB_INV; hv[q][1] += acc[2 * q][1] * TAB_INV; hv[q][2] += acc[2 * q + 1][0] * TAB_INV; hv[q][3] += acc[2 * q + 1][1] * TAB_INV;
;       ss += hv[q][0] * hv[q][0] + hv[q][1] * hv[q][1] + hv[q][2] * hv[q][2] + hv[q][3] * hv[q][3];
;       *(f32x4*)(hrow + 4 * q) = hv[q];
;     }
;     const float rstd = rsqrtf(wave_sum(ss) * (1.f / DM) + EPS);
;     u32x4 oa, ob;
; #pragma unroll
;     for (int q = 0; q < 4; ++q) {
;       const f32x4 g = *(const f32x4*)(gp + lane * 16 + 4 * q);
;       const unsigned p0 = pk2(hv[q][0] * rstd * g[0], hv[q][1] * rstd * g[1]), p1 = pk2(hv[q][2] * rstd * g[2], hv[q][3] * rstd * g[3]);
;       if (q < 2) { oa[2 * q] = p0; oa[2 * q + 1] = p1; } else { ob[2 * (q - 2)] = p0; ob[2 * (q - 2) + 1] = p1; }
;     }
;     *(u32x4*)(hn + tok * DM + lane * 16) = oa; *(u32x4*)(hn + tok * DM + lane * 16 + 8) = ob;
.Lpg1_epi:
	v_readfirstlane_b32 s82, v132
	v_readfirstlane_b32 s83, v133
	s_nop 4
	s_add_u32 s98, s3, s2
	s_lshl_b32 s99, s98, 12
	v_lshl_add_u32 v116, v233, 6, s99
	global_load_dwordx4 v[0:3], v116, s[82:83] offset:0
	global_load_dwordx4 v[4:7], v116, s[82:83] offset:16
	global_load_dwordx4 v[8:11], v116, s[82:83] offset:32
	global_load_dwordx4 v[12:15], v116, s[82:83] offset:48
	s_waitcnt vmcnt(0)
	v_pk_mul_f32 v[104:105], v[0:1], v[0:1]
	v_pk_fma_f32 v[104:105], v[2:3], v[2:3], v[104:105]
	v_pk_fma_f32 v[104:105], v[4:5], v[4:5], v[104:105]
	v_pk_fma_f32 v[104:105], v[6:7], v[6:7], v[104:105]
	v_pk_fma_f32 v[104:105], v[8:9], v[8:9], v[104:105]
	v_pk_fma_f32 v[104:105], v[10:11], v[10:11], v[104:105]
	v_pk_fma_f32 v[104:105], v[12:13], v[12:13], v[104:105]
	v_pk_fma_f32 v[104:105], v[14:15], v[14:15], v[104:105]
	s_nop 0
	v_add_f32_e32 v118, v104, v105
	s_nop 1
	v_add_f32_dpp v118, v118, v118 quad_perm:[1,0,3,2] row_mask:0xf bank_mask:0xf
	s_nop 1
	v_add_f32_dpp v118, v118, v118 quad_perm:[2,3,0,1] row_mask:0xf bank_mask:0xf
	s_nop 1
	v_add_f32_dpp v118, v118, v118 row_half_mirror row_mask:0xf bank_mask:0xf
	s_nop 1
	v_add_f32_dpp v118, v118, v118 row_mirror row_mask:0xf bank_mask:0xf
	v_xor_b32_e32 v119, 64, v234
	ds_bpermute_b32 v119, v119, v118
	s_waitcnt lgkmcnt(0)
	v_add_f32_e32 v118, v118, v119
	v_xor_b32_e32 v119, 128, v234
	ds_bpermute_b32 v119, v119, v118
	s_waitcnt lgkmcnt(0)
	v_add_f32_e32 v118, v118, v119
	v_mov_b32_e32 v119, 0x358637bd
	v_fmac_f32_e32 v119, 0x3a800000, v118
	v_rsq_f32_e32 v106, v119
	s_nop 1
	v_pk_mul_f32 v[0:1], v[0:1], v[106:107] op_sel_hi:[1,0]
	v_pk_mul_f32 v[2:3], v[2:3], v[106:107] op_sel_hi:[1,0]
	v_pk_mul_f32 v[4:5], v[4:5], v[106:107] op_sel_hi:[1,0]
	v_pk_mul_f32 v[6:7], v[6:7], v[106:107] op_sel_hi:[1,0]
	v_pk_mul_f32 v[8:9], v[8:9], v[106:107] op_sel_hi:[1,0]
	v_pk_mul_f32 v[10:11], v[10:11], v[106:107] op_sel_hi:[1,0]
	v_pk_mul_f32 v[12:13], v[12:13], v[106:107] op_sel_hi:[1,0]
	v_pk_mul_f32 v[14:15], v[14:15], v[106:107] op_sel_hi:[1,0]
	v_pk_mul_f32 v[0:1], v[16:17], v[0:1]
	v_pk_mul_f32 v[2:3], v[18:19], v[2:3]
	v_pk_mul_f32 v[4:5], v[20:21], v[4:5]
	v_pk_mul_f32 v[6:7], v[22:23], v[6:7]
	v_pk_mul_f32 v[8:9], v[24:25], v[8:9]
	v_pk_mul_f32 v[10:11], v[26:27], v[10:11]
	v_pk_mul_f32 v[12:13], v[28:29], v[12:13]
	v_pk_mul_f32 v[14:15], v[30:31], v[14:15]
	v_cvt_pk_bf16_f32 v32, v0, v1
	v_cvt_pk_bf16_f32 v33, v2, v3
	v_cvt_pk_bf16_f32 v34, v4, v5
	v_cvt_pk_bf16_f32 v35, v6, v7
	v_cvt_pk_bf16_f32 v36, v8, v9
	v_cvt_pk_bf16_f32 v37, v10, v11
	v_cvt_pk_bf16_f32 v38, v12, v13
	v_cvt_pk_bf16_f32 v39, v14, v15
	v_readfirstlane_b32 s82, v122
	v_readfirstlane_b32 s83, v123
	s_nop 4
	s_lshl_b32 s99, s98, 11
	v_lshl_add_u32 v116, v233, 5, s99
	global_store_dwordx4 v116, v[32:35], s[82:83]
	global_store_dwordx4 v116, v[36:39], s[82:83] offset:16
	s_add_u32 s2, s2, 1
	s_cmp_lt_u32 s2, 16
	s_cbranch_scc1 .Lpg1_epi
	s_waitcnt vmcnt(0) lgkmcnt(0)
	v_readlane_b32 s92, v231, 15
	v_readlane_b32 s93, v231, 16
